# plus chunk-prep transposed kbT/vbT LDS images XOR-swizzled by (row>>3)&3 per 16-byte granule: step-1 scatter bank conflict 16-way to 4-way, step-4 fragment reads use the same XOR
# speedup vs baseline: 1.0531x; 1.0028x over previous
; #define LAS __attribute__((address_space(3)))
; __device__ __forceinline__ void gdn_prep_item(LAS unsigned char* lds, int item, int b0, PrepRaw& R, int next_item, const bf16_t* qkv, const float* bg, const float* gconv_w, unsigned char* rec, float* gtarr) {
;     ...
;     {
;         const f32x4 z4 = (f32x4){0.f, 0.f, 0.f, 0.f};
; #pragma unroll
;         for (int rt = 0; rt < 4; ++rt) { f32x4 acc = z4;
; #pragma unroll
;             for (int s = 0; s < 2; ++s) { const bf16x8 tf = *(const LAS bf16x8*)(lds + P2_TB + ((16 * rt + l15) * 72 + 32 * s + 8 * g) * 2), vf = *(const LAS bf16x8*)(lds + P2_VBT + ((16 * wave + l15) * 72 + 32 * s + 8 * g) * 2);
;                 acc = MFMA16(tf, vf, acc); }
;             u32x2 w; w.x = cvt_pk_bf16(acc[0], acc[1]); w.y = cvt_pk_bf16(acc[2], acc[3]);
;             *(u32x2*)(rec + REC_U + ((rt * 8 + wave) * 64 + lane) * 8) = w; }
;         const int rt = wave >> 1;
; #pragma unroll
;         for (int q = 0; q < 2; ++q) { const int s2 = 2 * (wave & 1) + q; f32x4 a0 = z4, a1 = z4;
; #pragma unroll
;             for (int s = 0; s < 2; ++s) { const bf16x8 tf = *(const LAS bf16x8*)(lds + P2_TB + ((16 * rt + l15) * 72 + 32 * s + 8 * g) * 2);
;                 const bf16x8 k0 = *(const LAS bf16x8*)(lds + P2_KBT + ((32 * s2 + l15) * 72 + 32 * s + 8 * g) * 2), k1 = *(const LAS bf16x8*)(lds + P2_KBT + ((32 * s2 + 16 + l15) * 72 + 32 * s + 8 * g) * 2);
;                 a0 = MFMA16(k0, tf, a0); a1 = MFMA16(k1, tf, a1); }
;             *(bf16x8*)(rec + REC_WN + ((rt * 4 + s2) * 64 + lane) * 16) = pack8(-a0, -a1); }
;     }
; #pragma unroll
;     for (int q = 0; q < 2; ++q) { const int task = tid + q * NTHREADS, fragi = task >> 6, ln = task & 63, lg = ln >> 4, l = ln & 15;
;         const int rt = fragi >> 2, s2 = fragi & 3, i = 16 * rt + l; const float e = EG[i];
;         const u32x2 lo = *(const LAS u32x2*)(lds + P2_QN + (i * 136 + 32 * s2 + 4 * lg) * 2), hi = *(const LAS u32x2*)(lds + P2_QN + (i * 136 + 32 * s2 + 16 + 4 * lg) * 2);
;         const unsigned vv[4] = {lo.x, lo.y, hi.x, hi.y}; u32x4 w; unsigned ww[4];
; #pragma unroll
;         for (int k2 = 0; k2 < 4; ++k2) ww[k2] = cvt_pk_bf16(__uint_as_float(vv[k2] << 16) * e, __uint_as_float(vv[k2] & 0xffff0000u) * e);
;         w.x = ww[0]; w.y = ww[1]; w.z = ww[2]; w.w = ww[3];
;         *(u32x4*)(rec + REC_QD + (fragi * 64 + ln) * 16) = w; }
.LBB0_464:
	s_or_b64 exec, exec, s[0:1]
	s_add_u32 s0, s4, 0xe000
	s_addc_u32 s1, s5, 0
	v_mad_u32_u24 v46, v114, s28, v36
	s_add_i32 s8, 0, 0x1a000
	v_lshl_add_u32 v55, v46, 1, s8
	s_waitcnt lgkmcnt(0)
	s_barrier
	ds_read_b128 v[46:49], v55
	v_lshl_or_b32 v52, s30, 4, v114
	s_and_b32 s98, s30, 1
	s_lshl_b32 s98, s98, 4
	v_and_or_b32 v248, v114, 8, s98
	v_xor_b32_e32 v248, v248, v36
	v_mad_u32_u24 v52, v52, s28, v248
	v_lshl_add_u32 v52, v52, 1, 0
	ds_read_b128 v[56:59], v55 offset:64
	ds_read_b128 v[60:63], v52 offset:34816
	ds_read_b128 v[64:67], v52 offset:34880
	s_waitcnt lgkmcnt(1)
	v_mfma_f32_16x16x32_bf16 v[46:49], v[46:49], v[60:63], 0
	ds_read_b128 v[68:71], v55 offset:2304
	ds_read_b128 v[72:75], v55 offset:2368
	v_lshl_or_b32 v50, s14, 12, v50
	v_and_b32_e32 v51, 12, v51
	s_waitcnt lgkmcnt(2)
	v_mfma_f32_16x16x32_bf16 v[46:49], v[56:59], v[64:67], v[46:49]
	s_nop 7
	v_cvt_pk_bf16_f32 v52, v46, v47
	v_lshlrev_b32_e32 v46, 3, v118
	v_lshl_or_b32 v80, s30, 9, v46
	v_ashrrev_i32_e32 v81, 31, v80
	v_cvt_pk_bf16_f32 v53, v48, v49
	v_lshl_add_u64 v[56:57], s[0:1], 0, v[80:81]
	global_store_dwordx2 v[56:57], v[52:53], off
	ds_read_b128 v[56:59], v55 offset:4608
	s_waitcnt lgkmcnt(2)
	v_mfma_f32_16x16x32_bf16 v[46:49], v[68:71], v[60:63], 0
	ds_read_b128 v[68:71], v55 offset:4672
	v_add_u32_e32 v76, 0x2000, v80
	v_ashrrev_i32_e32 v77, 31, v76
	s_waitcnt lgkmcnt(2)
	v_mfma_f32_16x16x32_bf16 v[46:49], v[72:75], v[64:67], v[46:49]
	v_add_u32_e32 v72, 0x1000, v80
	v_ashrrev_i32_e32 v73, 31, v72
	v_lshl_add_u64 v[76:77], s[0:1], 0, v[76:77]
	v_add_u32_e32 v80, 0x3000, v80
	v_ashrrev_i32_e32 v81, 31, v80
	s_nop 2
	v_cvt_pk_bf16_f32 v52, v46, v47
	v_cvt_pk_bf16_f32 v53, v48, v49
	s_waitcnt lgkmcnt(1)
	v_mfma_f32_16x16x32_bf16 v[46:49], v[56:59], v[60:63], 0
	v_lshl_add_u64 v[56:57], s[0:1], 0, v[72:73]
	global_store_dwordx2 v[56:57], v[52:53], off
	ds_read_b128 v[56:59], v55 offset:6912
	s_waitcnt lgkmcnt(1)
	v_mfma_f32_16x16x32_bf16 v[46:49], v[68:71], v[64:67], v[46:49]
	v_lshl_or_b32 v68, s20, 6, v114
	s_nop 6
	v_cvt_pk_bf16_f32 v52, v46, v47
	v_cvt_pk_bf16_f32 v53, v48, v49
	ds_read_b128 v[46:49], v55 offset:6976
	s_waitcnt lgkmcnt(1)
	v_mfma_f32_16x16x32_bf16 v[56:59], v[56:59], v[60:63], 0
	v_mad_u64_u32 v[60:61], s[6:7], v37, s28, v[36:37]
	v_or_b32_e32 v37, 0x480, v36
	v_and_b32_e32 v249, 8, v114
	v_xor_b32_e32 v249, v249, v36
	v_xor_b32_e32 v250, 16, v249
	v_or_b32_e32 v250, 0x480, v250
	v_lshl_add_u32 v55, v60, 1, s8
	v_mad_u32_u24 v60, v68, s28, v249
	v_lshl_add_u32 v78, v60, 1, 0
	v_mad_u32_u24 v72, v68, s28, v250
	ds_read_b128 v[60:63], v78 offset:53248
	ds_read_b128 v[68:71], v55
	v_lshl_add_u32 v79, v72, 1, 0
	ds_read_b128 v[72:75], v79 offset:53248
	s_waitcnt lgkmcnt(3)
	v_mfma_f32_16x16x32_bf16 v[46:49], v[46:49], v[64:67], v[56:59]
	s_nop 2
	ds_read_b128 v[56:59], v55 offset:64
	ds_read_b128 v[64:67], v78 offset:53312
	global_store_dwordx2 v[76:77], v[52:53], off
	ds_read_b128 v[76:79], v79 offset:53312
	s_waitcnt lgkmcnt(4)
	v_mfma_f32_16x16x32_bf16 v[60:63], v[60:63], v[68:71], 0
	v_cvt_pk_bf16_f32 v52, v46, v47
	v_cvt_pk_bf16_f32 v53, v48, v49
	s_waitcnt lgkmcnt(3)
	v_mfma_f32_16x16x32_bf16 v[72:75], v[72:75], v[68:71], 0
	s_waitcnt lgkmcnt(1)
	v_mfma_f32_16x16x32_bf16 v[46:49], v[64:67], v[56:59], v[60:63]
	s_nop 2
	v_lshl_add_u64 v[60:61], s[0:1], 0, v[80:81]
	global_store_dwordx2 v[60:61], v[52:53], off
	s_waitcnt lgkmcnt(0)
	v_mfma_f32_16x16x32_bf16 v[60:63], v[76:79], v[56:59], v[72:75]
	s_lshl_b32 s0, s20, 1
	s_or_b32 s0, s0, 1
	v_xor_b32_e32 v52, 0x80000000, v49
	v_xor_b32_e32 v53, 0x80000000, v48
	v_xor_b32_e32 v55, 0x80000000, v47
	s_nop 2
	v_xor_b32_e32 v67, 0x80000000, v63
	v_lshl_or_b32 v63, s0, 5, v114
	v_mad_u32_u24 v36, v63, s28, v249
	v_lshl_add_u32 v36, v36, 1, 0
	v_xor_b32_e32 v66, 0x80000000, v46
	ds_read_b128 v[46:49], v36 offset:53248
	ds_read_b128 v[76:79], v36 offset:53312
	v_mad_u32_u24 v37, v63, s28, v250
	v_lshl_add_u32 v37, v37, 1, 0
	v_xor_b32_e32 v75, 0x80000000, v62
	ds_read_b128 v[62:65], v37 offset:53248
	ds_read_b128 v[80:83], v37 offset:53312
	s_waitcnt lgkmcnt(3)
	v_mfma_f32_16x16x32_bf16 v[46:49], v[46:49], v[68:71], 0
	v_xor_b32_e32 v61, 0x80000000, v61
	v_xor_b32_e32 v60, 0x80000000, v60
	v_cvt_pk_bf16_f32 v74, v60, v61
	s_waitcnt lgkmcnt(1)
	v_mfma_f32_16x16x32_bf16 v[60:63], v[62:65], v[68:71], 0
	v_lshl_or_b32 v36, s20, 11, v50
	v_ashrrev_i32_e32 v37, 31, v36
	v_cvt_pk_bf16_f32 v72, v66, v55
	v_mfma_f32_16x16x32_bf16 v[46:49], v[76:79], v[56:59], v[46:49]
	v_cvt_pk_bf16_f32 v73, v53, v52
	v_cvt_pk_bf16_f32 v75, v75, v67
	v_lshl_add_u64 v[36:37], s[4:5], 0, v[36:37]
	s_waitcnt lgkmcnt(0)
	v_mfma_f32_16x16x32_bf16 v[56:59], v[80:83], v[56:59], v[60:63]
	global_store_dwordx4 v[36:37], v[72:75], off
	s_nop 1
	v_xor_b32_e32 v36, 0x80000000, v49
	v_xor_b32_e32 v37, 0x80000000, v48
	v_xor_b32_e32 v47, 0x80000000, v47
	v_xor_b32_e32 v46, 0x80000000, v46
	v_cvt_pk_bf16_f32 v46, v46, v47
	v_cvt_pk_bf16_f32 v47, v37, v36
	v_lshl_or_b32 v36, s0, 10, v50
	v_xor_b32_e32 v49, 0x80000000, v59
	v_xor_b32_e32 v52, 0x80000000, v58
	v_xor_b32_e32 v48, 0x80000000, v57
	v_xor_b32_e32 v53, 0x80000000, v56
	v_ashrrev_i32_e32 v37, 31, v36
	v_cvt_pk_bf16_f32 v48, v53, v48
	v_cvt_pk_bf16_f32 v49, v52, v49
	v_lshl_add_u64 v[36:37], s[4:5], 0, v[36:37]
	global_store_dwordx4 v[36:37], v[46:49], off
	v_lshrrev_b32_e32 v58, 1, v116
	v_ashrrev_i32_e32 v37, 4, v116
	v_and_b32_e32 v36, 0x60, v58
	v_and_or_b32 v37, v37, -16, v114
	v_or_b32_e32 v59, 16, v51
	v_mad_u64_u32 v[46:47], s[0:1], v37, s23, v[36:37]
	v_lshl_add_u32 v52, v37, 2, s31
	v_add_u32_e32 v37, v46, v51
	v_add_u32_e32 v46, v46, v59
	v_add_u32_e32 v60, 0x200, v116
	v_lshl_add_u32 v48, v46, 1, 0
	v_ashrrev_i32_e32 v46, 4, v60
	v_and_or_b32 v61, v46, -16, v114
	v_lshl_add_u32 v37, v37, 1, 0
	v_lshl_add_u32 v50, v61, 2, s31
	ds_read_b64 v[46:47], v37
	ds_read_b64 v[48:49], v48
	ds_read_b32 v50, v50
	ds_read_b32 v52, v52
	s_add_u32 s0, s4, 0x4000
	s_waitcnt lgkmcnt(3)
; #define LAS __attribute__((address_space(3)))
; __device__ __forceinline__ float bf2f(bf16_t b) { return __uint_as_float(((unsigned)b) << 16); }
; __device__ __forceinline__ unsigned cvt_pk_bf16(float lo, float hi) { const bf16x2_t r = __builtin_convertvector((f32x2){lo, hi}, bf16x2_t); return __builtin_bit_cast(unsigned, r); }
; __device__ __forceinline__ void gdn_prep_item(LAS unsigned char* lds, int item, int b0, PrepRaw& R, int next_item, const bf16_t* qkv, const float* bg, const float* gconv_w, unsigned char* rec, float* gtarr) {
;     ...
;     for (int q = 0; q < 2; ++q) { const int task = tid + q * NTHREADS, fragi = task >> 6, ln = task & 63, lg = ln >> 4, l = ln & 15;
;         const int rt = fragi >> 2, s2 = fragi & 3, i = 16 * rt + l; const float e = EG[i];
;         const u32x2 lo = *(const LAS u32x2*)(lds + P2_QN + (i * 136 + 32 * s2 + 4 * lg) * 2), hi = *(const LAS u32x2*)(lds + P2_QN + (i * 136 + 32 * s2 + 16 + 4 * lg) * 2);
;         const unsigned vv[4] = {lo.x, lo.y, hi.x, hi.y}; u32x4 w; unsigned ww[4];
; #pragma unroll
;         for (int k2 = 0; k2 < 4; ++k2) ww[k2] = cvt_pk_bf16(__uint_as_float(vv[k2] << 16) * e, __uint_as_float(vv[k2] & 0xffff0000u) * e);
;         w.x = ww[0]; w.y = ww[1]; w.z = ww[2]; w.w = ww[3];
;         *(u32x4*)(rec + REC_QD + (fragi * 64 + ln) * 16) = w; }
; #pragma unroll
;     for (int q = 0; q < 2; ++q) { const int task = tid + q * NTHREADS, fragi = task >> 6, ln = task & 63, lg = ln >> 4, l = ln & 15;
;         const int dt = fragi >> 1, s = fragi & 1, dk = 16 * dt + l; float v[8];
; #pragma unroll
;         for (int j = 0; j < 8; ++j) { const int i = 32 * s + 4 * lg + (j & 3) + 16 * (j >> 2); v[j] = bf2f(*(const LAS bf16_t*)(lds + P2_KN + (i * 136 + dk) * 2)) * DKs[i]; }
;         u32x4 w; w.x = cvt_pk_bf16(v[0], v[1]); w.y = cvt_pk_bf16(v[2], v[3]); w.z = cvt_pk_bf16(v[4], v[5]); w.w = cvt_pk_bf16(v[6], v[7]);
;         *(u32x4*)(rec + REC_KDT + (fragi * 64 + ln) * 16) = w; }
;     __syncthreads();
	v_lshlrev_b32_e32 v56, 16, v46
	v_and_b32_e32 v57, 0xffff0000, v46
	v_mad_u64_u32 v[36:37], s[6:7], v61, s23, v[36:37]
	s_waitcnt lgkmcnt(0)
	v_pk_mul_f32 v[56:57], v[52:53], v[56:57] op_sel_hi:[0,1]
	v_cvt_pk_bf16_f32 v46, v56, v57
	v_lshlrev_b32_e32 v56, 16, v47
	v_and_b32_e32 v57, 0xffff0000, v47
	v_pk_mul_f32 v[56:57], v[52:53], v[56:57] op_sel_hi:[0,1]
	v_cvt_pk_bf16_f32 v47, v56, v57
	v_lshlrev_b32_e32 v56, 16, v48
	v_and_b32_e32 v57, 0xffff0000, v48
	v_pk_mul_f32 v[56:57], v[52:53], v[56:57] op_sel_hi:[0,1]
	v_cvt_pk_bf16_f32 v48, v56, v57
	v_lshlrev_b32_e32 v56, 16, v49
	v_and_b32_e32 v57, 0xffff0000, v49
	s_addc_u32 s1, s5, 0
	v_pk_mul_f32 v[52:53], v[52:53], v[56:57] op_sel_hi:[0,1]
	v_ashrrev_i32_e32 v55, 31, v54
	v_add_u32_e32 v37, v36, v51
	v_cvt_pk_bf16_f32 v49, v52, v53
	v_lshl_add_u64 v[52:53], s[0:1], 0, v[54:55]
	v_lshl_add_u32 v37, v37, 1, 0
	global_store_dwordx4 v[52:53], v[46:49], off
	ds_read_b64 v[46:47], v37
	v_and_or_b32 v52, v58, 32, v51
	v_and_or_b32 v53, v115, -16, v114
	v_add_u32_e32 v36, v36, v59
	v_mad_u32_u24 v37, v52, s23, v53
	v_lshl_add_u32 v36, v36, 1, 0
	v_lshl_add_u32 v48, v37, 1, 0
	ds_read_b64 v[36:37], v36
	ds_read_u16 v56, v48 offset:17408
	s_waitcnt lgkmcnt(2)
	v_lshlrev_b32_e32 v48, 16, v46
	v_and_b32_e32 v49, 0xffff0000, v46
	v_pk_mul_f32 v[48:49], v[50:51], v[48:49] op_sel_hi:[0,1]
	v_cvt_pk_bf16_f32 v46, v48, v49
	v_lshlrev_b32_e32 v48, 16, v47
	v_and_b32_e32 v49, 0xffff0000, v47
	v_pk_mul_f32 v[48:49], v[50:51], v[48:49] op_sel_hi:[0,1]
	v_cvt_pk_bf16_f32 v47, v48, v49
	s_waitcnt lgkmcnt(1)
	v_lshlrev_b32_e32 v48, 16, v36
	v_and_b32_e32 v49, 0xffff0000, v36
	v_lshlrev_b32_e32 v36, 16, v37
	v_and_b32_e32 v37, 0xffff0000, v37
	v_pk_mul_f32 v[48:49], v[50:51], v[48:49] op_sel_hi:[0,1]
	v_pk_mul_f32 v[36:37], v[50:51], v[36:37] op_sel_hi:[0,1]
	v_cvt_pk_bf16_f32 v48, v48, v49
	v_cvt_pk_bf16_f32 v49, v36, v37
	v_lshlrev_b32_e32 v36, 4, v60
	v_ashrrev_i32_e32 v37, 31, v36
	v_lshl_add_u64 v[50:51], s[0:1], 0, v[36:37]
	global_store_dwordx4 v[50:51], v[46:49], off
	v_mad_u32_u24 v64, v52, s23, s23
	v_mad_u32_u24 v66, v52, s23, v108
	v_lshl_add_u32 v46, v52, 2, 0
	v_mad_u32_u24 v68, v52, s23, v110
	v_mad_u32_u24 v69, v52, s23, v111
	v_ashrrev_i32_e32 v60, 3, v60
	v_add_u32_e32 v50, 0x1d300, v46
	v_add_u32_e32 v46, v64, v53
	v_mad_u32_u24 v65, v52, s23, v107
	v_add_u32_e32 v58, v66, v53
	v_mad_u32_u24 v67, v52, s23, v109
	v_add_u32_e32 v61, v68, v53
	v_add_u32_e32 v62, v69, v53
	v_mad_u32_u24 v70, v52, s23, v112
	v_and_or_b32 v71, v60, -16, v114
	v_lshl_add_u32 v51, v46, 1, 0
	v_add_u32_e32 v57, v65, v53
	v_lshl_add_u32 v58, v58, 1, 0
	v_add_u32_e32 v59, v67, v53
	v_lshl_add_u32 v61, v61, 1, 0
	v_lshl_add_u32 v62, v62, 1, 0
	v_add_u32_e32 v53, v70, v53
	v_mad_u32_u24 v52, v52, s23, v71
	ds_read_b128 v[46:49], v50
	v_lshl_add_u32 v57, v57, 1, 0
	v_lshl_add_u32 v59, v59, 1, 0
	v_lshl_add_u32 v53, v53, 1, 0
	v_lshl_add_u32 v52, v52, 1, 0
	ds_read_u16 v51, v51 offset:17408
	ds_read_u16 v60, v57 offset:17408
	ds_read_u16 v58, v58 offset:17408
	ds_read_u16 v63, v59 offset:17408
	ds_read_u16 v61, v61 offset:17408
	ds_read_u16 v62, v62 offset:17408
	ds_read_u16 v72, v53 offset:17408
	ds_read_u16 v73, v52 offset:17408
	s_waitcnt lgkmcnt(7)
	v_lshlrev_b32_e32 v57, 16, v51
	ds_read_b128 v[50:53], v50 offset:64
	s_add_u32 s0, s4, 0x8000
	v_lshlrev_b32_e32 v56, 16, v56
	s_waitcnt lgkmcnt(6)
	v_lshlrev_b32_e32 v59, 16, v58
	v_lshlrev_b32_e32 v58, 16, v60
	s_waitcnt lgkmcnt(4)
	v_lshlrev_b32_e32 v61, 16, v61
	v_lshlrev_b32_e32 v60, 16, v63
	s_waitcnt lgkmcnt(2)
	v_lshlrev_b32_e32 v63, 16, v72
	v_lshlrev_b32_e32 v62, 16, v62
	s_addc_u32 s1, s5, 0
	v_pk_mul_f32 v[56:57], v[46:47], v[56:57]
	v_pk_mul_f32 v[58:59], v[48:49], v[58:59]
	s_waitcnt lgkmcnt(0)
	v_pk_mul_f32 v[60:61], v[50:51], v[60:61]
	v_pk_mul_f32 v[62:63], v[52:53], v[62:63]
	v_cvt_pk_bf16_f32 v56, v56, v57
	v_cvt_pk_bf16_f32 v57, v58, v59
	v_cvt_pk_bf16_f32 v58, v60, v61
	v_cvt_pk_bf16_f32 v59, v62, v63
	v_lshl_add_u64 v[54:55], s[0:1], 0, v[54:55]
	global_store_dwordx4 v[54:55], v[56:59], off
	v_add_u32_e32 v54, v64, v71
	v_add_u32_e32 v60, v70, v71
	v_add_u32_e32 v56, v66, v71
	v_add_u32_e32 v57, v67, v71
	v_add_u32_e32 v58, v68, v71
	v_add_u32_e32 v59, v69, v71
	v_lshl_add_u32 v54, v54, 1, 0
	v_add_u32_e32 v55, v65, v71
	v_lshl_add_u32 v56, v56, 1, 0
	v_lshl_add_u32 v57, v57, 1, 0
	v_lshl_add_u32 v58, v58, 1, 0
	v_lshl_add_u32 v59, v59, 1, 0
	v_lshl_add_u32 v60, v60, 1, 0
	v_lshl_add_u32 v55, v55, 1, 0
	ds_read_u16 v54, v54 offset:17408
	ds_read_u16 v61, v55 offset:17408
	ds_read_u16 v56, v56 offset:17408
	ds_read_u16 v57, v57 offset:17408
	ds_read_u16 v58, v58 offset:17408
	ds_read_u16 v59, v59 offset:17408
	ds_read_u16 v60, v60 offset:17408
	s_waitcnt lgkmcnt(6)
	v_lshlrev_b32_e32 v55, 16, v54
	v_lshlrev_b32_e32 v54, 16, v73
	v_pk_mul_f32 v[46:47], v[46:47], v[54:55]
	s_waitcnt lgkmcnt(4)
	v_lshlrev_b32_e32 v55, 16, v56
	v_lshlrev_b32_e32 v54, 16, v61
	v_pk_mul_f32 v[48:49], v[48:49], v[54:55]
	s_waitcnt lgkmcnt(2)
	v_lshlrev_b32_e32 v55, 16, v58
	v_lshlrev_b32_e32 v54, 16, v57
	v_pk_mul_f32 v[50:51], v[50:51], v[54:55]
	s_waitcnt lgkmcnt(0)
	v_lshlrev_b32_e32 v55, 16, v60
	v_lshlrev_b32_e32 v54, 16, v59
	v_pk_mul_f32 v[52:53], v[52:53], v[54:55]
	v_cvt_pk_bf16_f32 v46, v46, v47
	v_cvt_pk_bf16_f32 v47, v48, v49
	v_cvt_pk_bf16_f32 v48, v50, v51
	v_cvt_pk_bf16_f32 v49, v52, v53
	v_lshl_add_u64 v[36:37], s[0:1], 0, v[36:37]
	s_cmp_eq_u32 s29, s3
	global_store_dwordx4 v[36:37], v[46:49], off
	s_barrier
	s_cbranch_scc1 .LBB0_553

; __device__ __forceinline__ float silu_f(float x) { return x * __builtin_amdgcn_rcpf(1.0f + __expf(-x)); }
; __device__ __forceinline__ void gdn_prep_item(LAS unsigned char* lds, int item, int b0, PrepRaw& R, int next_item, const bf16_t* qkv, const float* bg, const float* gconv_w, unsigned char* rec, float* gtarr) {
;     ...
;         const int cc = tid & 15, i0 = (tid >> 4) * 2;
;         const float be0 = Bs[i0], be1 = Bs[i0 + 1], eg0 = EG[i0], eg1 = EG[i0 + 1];
; #pragma unroll
;         for (int part = 0; part < 3; ++part) {
;             const int col = part * 1024 + h * 128 + 8 * cc;
;             float y0[8], y1[8];
; #pragma unroll
;             for (int e = 0; e < 8; ++e) { y0[e] = 0.f; y1[e] = 0.f; }
; #pragma unroll
;             for (int j = 0; j < 5; ++j) { const u32x4 v = part < 2 ? R.x[part < 2 ? part : 0][j] : xv[j]; const unsigned vv[4] = {v.x, v.y, v.z, v.w}; float x[8];
; #pragma unroll
;                 for (int e = 0; e < 4; ++e) { x[2 * e] = __uint_as_float(vv[e] << 16); x[2 * e + 1] = __uint_as_float(vv[e] & 0xffff0000u); }
;                 if (j < 4) { const f32x4 wa = *(const f32x4*)(gconv_w + j * CONVCH + col), wb = *(const f32x4*)(gconv_w + j * CONVCH + col + 4);
; #pragma unroll
;                     for (int e = 0; e < 8; ++e) y0[e] += (e < 4 ? wa[e] : wb[e - 4]) * x[e]; }
;                 if (j > 0) { const f32x4 wa = *(const f32x4*)(gconv_w + (j - 1) * CONVCH + col), wb = *(const f32x4*)(gconv_w + (j - 1) * CONVCH + col + 4);
; #pragma unroll
;                     for (int e = 0; e < 8; ++e) y1[e] += (e < 4 ? wa[e] : wb[e - 4]) * x[e]; } }
;             float s0 = 0.f, s1 = 0.f;
; #pragma unroll
;             for (int e = 0; e < 8; ++e) { y0[e] = silu_f(y0[e]); y1[e] = silu_f(y1[e]); s0 += y0[e] * y0[e]; s1 += y1[e] * y1[e]; }
.LBB0_482:
	s_or_b64 exec, exec, s[0:1]
	v_or_b32_e32 v36, s6, v94
	v_lshlrev_b32_e32 v36, 2, v36
	v_mov_b32_e32 v37, v34
	v_lshl_add_u64 v[98:99], s[72:73], 0, v[36:37]
	s_mov_b64 s[0:1], 0x3000
	s_waitcnt lgkmcnt(0)
	s_barrier
	v_lshl_add_u64 v[36:37], v[98:99], 0, s[0:1]
	s_mov_b64 s[0:1], 0x6000
	s_mov_b64 s[0:1], 0x9000
	v_lshl_add_u64 v[36:37], v[98:99], 0, s[0:1]
	s_movk_i32 s0, 0x4000
	v_add_co_u32_e32 v100, vcc, s0, v98
	s_movk_i32 s0, 0x7000
	s_nop 0
	v_addc_co_u32_e32 v101, vcc, 0, v99, vcc
	v_add_co_u32_e32 v102, vcc, s0, v98
	s_mov_b32 s0, 0xa000
	s_nop 0
	v_addc_co_u32_e32 v103, vcc, 0, v99, vcc
	v_add_co_u32_e32 v104, vcc, s0, v98
	v_addc_co_u32_e32 v105, vcc, 0, v99, vcc
	s_waitcnt vmcnt(16)
	v_lshlrev_b32_e32 v132, 16, v4
	v_and_b32_e32 v133, 0xffff0000, v4
	v_lshlrev_b32_e32 v134, 16, v12
	v_and_b32_e32 v135, 0xffff0000, v12
	v_lshlrev_b32_e32 v136, 16, v16
	v_and_b32_e32 v137, 0xffff0000, v16
	v_lshlrev_b32_e32 v138, 16, v20
	v_and_b32_e32 v139, 0xffff0000, v20
	v_lshlrev_b32_e32 v140, 16, v3
	v_and_b32_e32 v141, 0xffff0000, v3
	v_lshlrev_b32_e32 v142, 16, v11
	v_and_b32_e32 v143, 0xffff0000, v11
	v_lshlrev_b32_e32 v144, 16, v15
	v_and_b32_e32 v145, 0xffff0000, v15
	v_lshlrev_b32_e32 v154, 16, v2
	v_and_b32_e32 v155, 0xffff0000, v2
	v_lshlrev_b32_e32 v158, 16, v10
	v_and_b32_e32 v159, 0xffff0000, v10
	v_lshlrev_b32_e32 v160, 16, v14
	v_and_b32_e32 v161, 0xffff0000, v14
	v_lshlrev_b32_e32 v162, 16, v18
	v_and_b32_e32 v163, 0xffff0000, v18
	s_add_i32 s29, s29, 1
	s_add_i32 s0, s99, s96
	s_and_b32 s100, s0, 7
	s_lshr_b32 s101, s0, 3
	s_and_b32 s98, s101, 7
	s_lshr_b32 s101, s101, 3
	s_mul_i32 s98, s98, 33
	s_add_i32 s98, s98, s101
	s_lshl_b32 s98, s98, 3
	s_or_b32 s0, s98, s100
	v_or_b32_e32 v164, 1, v115
	s_cmp_lt_i32 s29, s3
	v_lshlrev_b32_e32 v36, 2, v95
	v_lshlrev_b32_e32 v37, 2, v164
	s_cselect_b32 s14, s0, -1
	s_add_i32 s0, 0, 0x1d100
	s_add_i32 s31, 0, 0x1d200
	v_lshlrev_b32_e32 v124, 16, v5
	v_and_b32_e32 v125, 0xffff0000, v5
	v_add_u32_e32 v96, s0, v36
	v_add_u32_e32 v97, s0, v37
	v_add_u32_e32 v146, s31, v36
	v_add_u32_e32 v147, s31, v37
	ds_read_b32 v36, v96
	ds_read_b32 v37, v97
	ds_read_b32 v96, v146
	ds_read_b32 v97, v147
	v_lshlrev_b32_e32 v126, 16, v13
	v_and_b32_e32 v127, 0xffff0000, v13
	v_lshlrev_b32_e32 v128, 16, v17
	v_and_b32_e32 v129, 0xffff0000, v17
	v_lshlrev_b32_e32 v130, 16, v21
	v_and_b32_e32 v131, 0xffff0000, v21
	v_pk_fma_f32 v[148:149], v[82:83], v[132:133], 0 op_sel_hi:[1,1,0]
	v_pk_fma_f32 v[150:151], v[168:169], v[140:141], 0 op_sel_hi:[1,1,0]
	v_pk_fma_f32 v[156:157], v[166:167], v[154:155], 0 op_sel_hi:[1,1,0]
	v_pk_fma_f32 v[146:147], v[84:85], v[124:125], 0 op_sel_hi:[1,1,0]
	v_pk_fma_f32 v[148:149], v[86:87], v[134:135], v[148:149]
	v_pk_fma_f32 v[148:149], v[90:91], v[136:137], v[148:149]
	v_pk_fma_f32 v[146:147], v[88:89], v[126:127], v[146:147]
	v_pk_fma_f32 v[138:139], v[120:121], v[138:139], v[148:149]
	v_pk_fma_f32 v[146:147], v[92:93], v[128:129], v[146:147]
	v_mul_f32_e32 v148, 0xbfb8aa3b, v138
	v_mul_f32_e32 v149, 0xbfb8aa3b, v139
	v_exp_f32_e32 v148, v148
	v_exp_f32_e32 v149, v149
	v_pk_fma_f32 v[130:131], v[122:123], v[130:131], v[146:147]
	v_add_f32_e32 v148, 1.0, v148
	v_add_f32_e32 v149, 1.0, v149
	v_rcp_f32_e32 v148, v148
	v_rcp_f32_e32 v149, v149
	v_mul_f32_e32 v146, 0xbfb8aa3b, v130
	v_pk_fma_f32 v[150:151], v[72:73], v[142:143], v[150:151]
	v_pk_fma_f32 v[156:157], v[70:71], v[158:159], v[156:157]
	v_pk_fma_f32 v[150:151], v[76:77], v[144:145], v[150:151]
	v_pk_mul_f32 v[138:139], v[138:139], v[148:149]
	v_lshlrev_b32_e32 v148, 16, v19
	v_and_b32_e32 v149, 0xffff0000, v19
	v_pk_fma_f32 v[148:149], v[80:81], v[148:149], v[150:151]
	v_pk_fma_f32 v[156:157], v[74:75], v[160:161], v[156:157]
	v_mul_f32_e32 v150, 0xbfb8aa3b, v148
	v_exp_f32_e32 v152, v150
	v_mul_f32_e32 v150, 0xbfb8aa3b, v149
	v_exp_f32_e32 v153, v150
	v_pk_fma_f32 v[156:157], v[78:79], v[162:163], v[156:157]
	v_add_f32_e32 v152, 1.0, v152
	v_mul_f32_e32 v162, 0xbfb8aa3b, v156
	v_add_f32_e32 v153, 1.0, v153
	v_mul_f32_e32 v163, 0xbfb8aa3b, v157
	v_rcp_f32_e32 v152, v152
	v_rcp_f32_e32 v153, v153
	v_exp_f32_e32 v162, v162
	v_exp_f32_e32 v163, v163
	v_mul_f32_e32 v147, 0xbfb8aa3b, v131
	v_pk_mul_f32 v[148:149], v[148:149], v[152:153]
	v_add_f32_e32 v152, 1.0, v162
	v_add_f32_e32 v153, 1.0, v163
	v_lshlrev_b32_e32 v162, 16, v9
	v_and_b32_e32 v163, 0xffff0000, v9
	v_pk_fma_f32 v[84:85], v[84:85], v[162:163], 0 op_sel_hi:[1,1,0]
	v_exp_f32_e32 v146, v146
	v_pk_fma_f32 v[84:85], v[88:89], v[124:125], v[84:85]
	v_exp_f32_e32 v147, v147
	v_pk_fma_f32 v[84:85], v[92:93], v[126:127], v[84:85]
	v_rcp_f32_e32 v152, v152
	v_pk_fma_f32 v[84:85], v[122:123], v[128:129], v[84:85]
	v_rcp_f32_e32 v153, v153
	v_mul_f32_e32 v88, 0xbfb8aa3b, v84
	v_mul_f32_e32 v89, 0xbfb8aa3b, v85
	v_exp_f32_e32 v88, v88
	v_exp_f32_e32 v89, v89
	v_add_f32_e32 v146, 1.0, v146
	v_add_f32_e32 v147, 1.0, v147
	v_add_f32_e32 v88, 1.0, v88
	v_add_f32_e32 v89, 1.0, v89
	v_rcp_f32_e32 v88, v88
	v_rcp_f32_e32 v89, v89
	v_pk_mul_f32 v[122:123], v[156:157], v[152:153]
	v_rcp_f32_e32 v146, v146
	v_rcp_f32_e32 v147, v147
	v_pk_mul_f32 v[84:85], v[84:85], v[88:89]
	v_lshlrev_b32_e32 v88, 16, v8
	v_and_b32_e32 v89, 0xffff0000, v8
	v_pk_fma_f32 v[82:83], v[82:83], v[88:89], 0 op_sel_hi:[1,1,0]
	v_pk_mul_f32 v[124:125], v[122:123], v[122:123]
	v_pk_fma_f32 v[82:83], v[86:87], v[132:133], v[82:83]
	v_pk_mul_f32 v[92:93], v[148:149], v[148:149]
	v_pk_fma_f32 v[82:83], v[90:91], v[134:135], v[82:83]
	v_lshlrev_b32_e32 v90, 16, v7
	v_and_b32_e32 v91, 0xffff0000, v7
	v_pk_fma_f32 v[68:69], v[168:169], v[90:91], 0 op_sel_hi:[1,1,0]
	v_pk_fma_f32 v[82:83], v[120:121], v[136:137], v[82:83]
; #define LAS __attribute__((address_space(3)))
; __device__ __forceinline__ unsigned cvt_pk_bf16(float lo, float hi) { const bf16x2_t r = __builtin_convertvector((f32x2){lo, hi}, bf16x2_t); return __builtin_bit_cast(unsigned, r); }
; __device__ __forceinline__ float silu_f(float x) { return x * __builtin_amdgcn_rcpf(1.0f + __expf(-x)); }
; __device__ __forceinline__ void gdn_prep_item(LAS unsigned char* lds, int item, int b0, PrepRaw& R, int next_item, const bf16_t* qkv, const float* bg, const float* gconv_w, unsigned char* rec, float* gtarr) {
;     ...
;             float s0 = 0.f, s1 = 0.f;
; #pragma unroll
;             for (int e = 0; e < 8; ++e) { y0[e] = silu_f(y0[e]); y1[e] = silu_f(y1[e]); s0 += y0[e] * y0[e]; s1 += y1[e] * y1[e]; }
;             if (part < 2) {
;                 s0 = row16_sum(s0); s1 = row16_sum(s1);
;                 float sc0 = rsqrtf(s0 + EPS), sc1 = rsqrtf(s1 + EPS); if (part == 0) { sc0 *= 0.08838834764831845f; sc1 *= 0.08838834764831845f; }
; #pragma unroll
;                 for (int e = 0; e < 8; ++e) { y0[e] *= sc0; y1[e] *= sc1; }
;                 LAS unsigned char* img = lds + (part == 0 ? P2_QN : P2_KN);
;                 u32x4 w0, w1; w0.x = cvt_pk_bf16(y0[0], y0[1]); w0.y = cvt_pk_bf16(y0[2], y0[3]); w0.z = cvt_pk_bf16(y0[4], y0[5]); w0.w = cvt_pk_bf16(y0[6], y0[7]);
;                 w1.x = cvt_pk_bf16(y1[0], y1[1]); w1.y = cvt_pk_bf16(y1[2], y1[3]); w1.z = cvt_pk_bf16(y1[4], y1[5]); w1.w = cvt_pk_bf16(y1[6], y1[7]);
;                 *(LAS u32x4*)(img + (i0 * 136 + 8 * cc) * 2) = w0; *(LAS u32x4*)(img + ((i0 + 1) * 136 + 8 * cc) * 2) = w1;
	v_pk_fma_f32 v[68:69], v[72:73], v[140:141], v[68:69]
	v_mul_f32_e32 v86, 0xbfb8aa3b, v82
	v_pk_fma_f32 v[68:69], v[76:77], v[142:143], v[68:69]
	v_exp_f32_e32 v88, v86
	v_pk_fma_f32 v[68:69], v[80:81], v[144:145], v[68:69]
	v_lshlrev_b32_e32 v80, 16, v6
	v_and_b32_e32 v81, 0xffff0000, v6
	v_pk_fma_f32 v[66:67], v[166:167], v[80:81], 0 op_sel_hi:[1,1,0]
	v_mul_f32_e32 v72, 0xbfb8aa3b, v68
	v_pk_fma_f32 v[66:67], v[70:71], v[154:155], v[66:67]
	v_exp_f32_e32 v76, v72
	v_pk_fma_f32 v[66:67], v[74:75], v[158:159], v[66:67]
	v_mul_f32_e32 v72, 0xbfb8aa3b, v69
	v_pk_fma_f32 v[66:67], v[78:79], v[160:161], v[66:67]
	v_exp_f32_e32 v77, v72
	v_mul_f32_e32 v70, 0xbfb8aa3b, v66
	v_mul_f32_e32 v71, 0xbfb8aa3b, v67
	v_exp_f32_e32 v70, v70
	v_exp_f32_e32 v71, v71
	v_mul_f32_e32 v86, 0xbfb8aa3b, v83
	v_exp_f32_e32 v89, v86
	v_add_f32_e32 v70, 1.0, v70
	v_add_f32_e32 v71, 1.0, v71
	v_add_f32_e32 v76, 1.0, v76
	v_add_f32_e32 v77, 1.0, v77
	v_rcp_f32_e32 v70, v70
	v_rcp_f32_e32 v71, v71
	v_rcp_f32_e32 v76, v76
	v_rcp_f32_e32 v77, v77
	v_add_f32_e32 v88, 1.0, v88
	v_add_f32_e32 v89, 1.0, v89
	v_rcp_f32_e32 v88, v88
	v_rcp_f32_e32 v89, v89
	v_pk_mul_f32 v[66:67], v[66:67], v[70:71]
	v_pk_mul_f32 v[68:69], v[68:69], v[76:77]
	v_pk_mul_f32 v[70:71], v[66:67], v[66:67]
	v_pk_mul_f32 v[76:77], v[68:69], v[68:69]
	v_mov_b32_e32 v78, v124
	v_mov_b32_e32 v79, v70
	v_mov_b32_e32 v70, v125
	v_pk_mul_f32 v[72:73], v[82:83], v[88:89]
	v_pk_add_f32 v[70:71], v[78:79], v[70:71]
	v_mov_b32_e32 v78, v92
	v_mov_b32_e32 v79, v76
	v_pk_mul_f32 v[150:151], v[138:139], v[138:139]
	v_pk_mul_f32 v[74:75], v[72:73], v[72:73]
	v_pk_add_f32 v[70:71], v[78:79], v[70:71]
	v_mov_b32_e32 v76, v93
	v_pk_mul_f32 v[130:131], v[130:131], v[146:147]
	v_pk_add_f32 v[70:71], v[76:77], v[70:71]
	v_mov_b32_e32 v76, v150
	v_mov_b32_e32 v77, v74
	v_pk_mul_f32 v[146:147], v[130:131], v[130:131]
	v_pk_mul_f32 v[86:87], v[84:85], v[84:85]
	v_pk_add_f32 v[70:71], v[76:77], v[70:71]
	v_mov_b32_e32 v74, v151
	v_pk_add_f32 v[70:71], v[74:75], v[70:71]
	v_mov_b32_e32 v74, v146
	v_mov_b32_e32 v75, v86
	v_pk_add_f32 v[70:71], v[74:75], v[70:71]
	v_mov_b32_e32 v86, v147
	v_pk_add_f32 v[70:71], v[86:87], v[70:71]
	v_mov_b32_e32 v74, v34
	v_mov_b32_e32 v75, v34
	v_mad_u64_u32 v[76:77], s[0:1], v164, s23, v[94:95]
	v_mov_b32_dpp v74, v70 quad_perm:[1,0,3,2] row_mask:0xf bank_mask:0xf
	v_mov_b32_dpp v75, v71 quad_perm:[1,0,3,2] row_mask:0xf bank_mask:0xf
	v_pk_add_f32 v[70:71], v[70:71], v[74:75]
	v_mov_b32_e32 v74, v34
	v_mov_b32_e32 v75, v34
	v_lshl_add_u32 v160, v76, 1, 0
	v_mov_b32_dpp v74, v70 quad_perm:[2,3,0,1] row_mask:0xf bank_mask:0xf
	v_mov_b32_dpp v75, v71 quad_perm:[2,3,0,1] row_mask:0xf bank_mask:0xf
	v_pk_add_f32 v[70:71], v[70:71], v[74:75]
	v_mov_b32_e32 v74, v34
	v_mov_b32_e32 v75, v34
	s_nop 0
	v_mov_b32_dpp v74, v70 row_ror:4 row_mask:0xf bank_mask:0xf
	v_mov_b32_dpp v75, v71 row_ror:4 row_mask:0xf bank_mask:0xf
	v_pk_add_f32 v[70:71], v[70:71], v[74:75]
	v_mov_b32_e32 v74, v34
	v_mov_b32_e32 v75, v34
	s_nop 0
	v_mov_b32_dpp v74, v70 row_ror:8 row_mask:0xf bank_mask:0xf
	v_mov_b32_dpp v75, v71 row_ror:8 row_mask:0xf bank_mask:0xf
	v_pk_add_f32 v[70:71], v[70:71], v[74:75]
	s_nop 0
	v_pk_add_f32 v[70:71], v[70:71], s[16:17] op_sel_hi:[1,0]
	s_nop 0
	v_mul_f32_e32 v74, 0x4b800000, v70
	v_cmp_gt_f32_e32 vcc, s24, v70
	s_nop 1
	v_cndmask_b32_e32 v70, v70, v74, vcc
	v_rsq_f32_e32 v70, v70
	v_mad_u64_u32 v[74:75], s[0:1], v95, s23, v[94:95]
	v_lshl_add_u32 v94, v74, 1, 0
	v_mul_f32_e32 v75, 0x45800000, v70
	v_cndmask_b32_e32 v70, v70, v75, vcc
	v_mul_f32_e32 v70, 0x3db504f3, v70
	v_mul_f32_e32 v75, 0x4b800000, v71
	v_cmp_gt_f32_e32 vcc, s24, v71
	v_pk_mul_f32 v[78:79], v[122:123], v[70:71] op_sel_hi:[1,0]
	s_nop 0
	v_cndmask_b32_e32 v71, v71, v75, vcc
	v_rsq_f32_e32 v71, v71
	s_nop 0
	v_pk_mul_f32 v[80:81], v[148:149], v[70:71] op_sel_hi:[1,0]
	v_pk_mul_f32 v[82:83], v[138:139], v[70:71] op_sel_hi:[1,0]
	v_pk_mul_f32 v[86:87], v[130:131], v[70:71] op_sel_hi:[1,0]
	v_mul_f32_e32 v70, 0x45800000, v71
	v_cndmask_b32_e32 v70, v71, v70, vcc
	v_mul_f32_e32 v70, 0x3db504f3, v70
	v_pk_mul_f32 v[66:67], v[66:67], v[70:71] op_sel_hi:[1,0]
	v_pk_mul_f32 v[68:69], v[68:69], v[70:71] op_sel_hi:[1,0]
	v_pk_mul_f32 v[72:73], v[72:73], v[70:71] op_sel_hi:[1,0]
	v_pk_mul_f32 v[70:71], v[84:85], v[70:71] op_sel_hi:[1,0]
	v_cvt_pk_bf16_f32 v66, v66, v67
	v_cvt_pk_bf16_f32 v67, v68, v69
	v_cvt_pk_bf16_f32 v68, v72, v73
	v_cvt_pk_bf16_f32 v69, v70, v71
	v_cvt_pk_bf16_f32 v70, v78, v79
	v_cvt_pk_bf16_f32 v71, v80, v81
	v_cvt_pk_bf16_f32 v72, v82, v83
	v_cvt_pk_bf16_f32 v73, v86, v87
	ds_write_b128 v94, v[66:69]
	ds_write_b128 v160, v[70:73]
	s_mov_b64 s[0:1], 0x1000
	v_lshl_add_u64 v[66:67], v[98:99], 0, s[0:1]
	s_movk_i32 s0, 0x2000
	v_add_co_u32_e32 v82, vcc, s0, v98
	s_mov_b64 s[0:1], 0x4000
	s_nop 0
	v_addc_co_u32_e32 v83, vcc, 0, v99, vcc
	v_lshl_add_u64 v[70:71], v[98:99], 0, s[0:1]
	s_mov_b64 s[0:1], 0x7000
	s_nop 0
	v_lshl_add_u64 v[74:75], v[98:99], 0, s[0:1]
	s_mov_b64 s[0:1], 0xa000
	s_nop 0
	v_lshl_add_u64 v[78:79], v[98:99], 0, s[0:1]
	s_nop 0
	v_lshlrev_b32_e32 v136, 16, v27
	v_and_b32_e32 v137, 0xffff0000, v27
	v_lshlrev_b32_e32 v138, 16, v31
	v_and_b32_e32 v139, 0xffff0000, v31
	v_lshlrev_b32_e32 v140, 16, v39
	v_and_b32_e32 v141, 0xffff0000, v39
	v_lshlrev_b32_e32 v142, 16, v43
	v_and_b32_e32 v143, 0xffff0000, v43
	v_lshlrev_b32_e32 v144, 16, v26
	v_and_b32_e32 v145, 0xffff0000, v26
	v_lshlrev_b32_e32 v146, 16, v30
	v_and_b32_e32 v147, 0xffff0000, v30
	v_lshlrev_b32_e32 v148, 16, v38
	v_and_b32_e32 v149, 0xffff0000, v38
	v_lshlrev_b32_e32 v150, 16, v42
	v_and_b32_e32 v151, 0xffff0000, v42
	v_lshlrev_b32_e32 v92, 16, v29
	v_and_b32_e32 v93, 0xffff0000, v29
	v_lshlrev_b32_e32 v104, 16, v33
	v_and_b32_e32 v105, 0xffff0000, v33
	v_lshlrev_b32_e32 v124, 16, v41
	v_and_b32_e32 v125, 0xffff0000, v41
	v_lshlrev_b32_e32 v128, 16, v28
	v_and_b32_e32 v129, 0xffff0000, v28
	v_lshlrev_b32_e32 v130, 16, v32
	v_and_b32_e32 v131, 0xffff0000, v32
	v_lshlrev_b32_e32 v132, 16, v40
	v_and_b32_e32 v133, 0xffff0000, v40
	v_lshlrev_b32_e32 v134, 16, v44
	v_and_b32_e32 v135, 0xffff0000, v44
	v_lshlrev_b32_e32 v126, 16, v45
	v_and_b32_e32 v127, 0xffff0000, v45
	s_movk_i32 s0, 0x240
	s_waitcnt vmcnt(8)
; __device__ __forceinline__ float silu_f(float x) { return x * __builtin_amdgcn_rcpf(1.0f + __expf(-x)); }
; __device__ __forceinline__ void gdn_prep_item(LAS unsigned char* lds, int item, int b0, PrepRaw& R, int next_item, const bf16_t* qkv, const float* bg, const float* gconv_w, unsigned char* rec, float* gtarr) {
;     ...
;             for (int j = 0; j < 5; ++j) { const u32x4 v = part < 2 ? R.x[part < 2 ? part : 0][j] : xv[j]; const unsigned vv[4] = {v.x, v.y, v.z, v.w}; float x[8];
; #pragma unroll
;                 for (int e = 0; e < 4; ++e) { x[2 * e] = __uint_as_float(vv[e] << 16); x[2 * e + 1] = __uint_as_float(vv[e] & 0xffff0000u); }
;                 if (j < 4) { const f32x4 wa = *(const f32x4*)(gconv_w + j * CONVCH + col), wb = *(const f32x4*)(gconv_w + j * CONVCH + col + 4);
; #pragma unroll
;                     for (int e = 0; e < 8; ++e) y0[e] += (e < 4 ? wa[e] : wb[e - 4]) * x[e]; }
;                 if (j > 0) { const f32x4 wa = *(const f32x4*)(gconv_w + (j - 1) * CONVCH + col), wb = *(const f32x4*)(gconv_w + (j - 1) * CONVCH + col + 4);
; #pragma unroll
;                     for (int e = 0; e < 8; ++e) y1[e] += (e < 4 ? wa[e] : wb[e - 4]) * x[e]; } }
;             float s0 = 0.f, s1 = 0.f;
; #pragma unroll
;             for (int e = 0; e < 8; ++e) { y0[e] = silu_f(y0[e]); y1[e] = silu_f(y1[e]); s0 += y0[e] * y0[e]; s1 += y1[e] * y1[e]; }
;             if (part < 2) {
;                 s0 = row16_sum(s0); s1 = row16_sum(s1);
	v_pk_fma_f32 v[152:153], v[172:173], v[92:93], 0 op_sel_hi:[1,1,0]
	v_pk_fma_f32 v[154:155], v[170:171], v[128:129], 0 op_sel_hi:[1,1,0]
	v_pk_fma_f32 v[156:157], v[176:177], v[136:137], 0 op_sel_hi:[1,1,0]
	v_pk_fma_f32 v[158:159], v[174:175], v[144:145], 0 op_sel_hi:[1,1,0]
	v_pk_fma_f32 v[156:157], v[184:185], v[138:139], v[156:157]
	v_pk_fma_f32 v[158:159], v[182:183], v[146:147], v[158:159]
	v_pk_fma_f32 v[152:153], v[180:181], v[104:105], v[152:153]
	v_pk_fma_f32 v[156:157], v[192:193], v[140:141], v[156:157]
	v_pk_fma_f32 v[158:159], v[190:191], v[148:149], v[158:159]
	v_pk_fma_f32 v[142:143], v[200:201], v[142:143], v[156:157]
	v_pk_fma_f32 v[150:151], v[198:199], v[150:151], v[158:159]
	v_mul_f32_e32 v156, 0xbfb8aa3b, v142
	v_mul_f32_e32 v157, 0xbfb8aa3b, v143
	v_exp_f32_e32 v156, v156
	v_exp_f32_e32 v157, v157
	v_mul_f32_e32 v158, 0xbfb8aa3b, v150
	v_mul_f32_e32 v159, 0xbfb8aa3b, v151
	v_add_f32_e32 v156, 1.0, v156
	v_add_f32_e32 v157, 1.0, v157
	v_exp_f32_e32 v158, v158
	v_rcp_f32_e32 v156, v156
	v_rcp_f32_e32 v157, v157
	v_exp_f32_e32 v159, v159
	v_pk_fma_f32 v[154:155], v[178:179], v[130:131], v[154:155]
	v_pk_fma_f32 v[152:153], v[188:189], v[124:125], v[152:153]
	v_pk_mul_f32 v[142:143], v[142:143], v[156:157]
	v_add_f32_e32 v156, 1.0, v158
	v_add_f32_e32 v157, 1.0, v159
	v_lshlrev_b32_e32 v158, 16, v25
	v_and_b32_e32 v159, 0xffff0000, v25
	v_pk_fma_f32 v[86:87], v[172:173], v[158:159], 0 op_sel_hi:[1,1,0]
	v_pk_fma_f32 v[154:155], v[186:187], v[132:133], v[154:155]
	v_pk_fma_f32 v[86:87], v[180:181], v[92:93], v[86:87]
	v_pk_fma_f32 v[134:135], v[194:195], v[134:135], v[154:155]
	v_pk_fma_f32 v[86:87], v[188:189], v[104:105], v[86:87]
	v_mul_f32_e32 v154, 0xbfb8aa3b, v134
	v_pk_fma_f32 v[86:87], v[196:197], v[124:125], v[86:87]
	v_mul_f32_e32 v155, 0xbfb8aa3b, v135
	v_mul_f32_e32 v90, 0xbfb8aa3b, v86
	v_mul_f32_e32 v91, 0xbfb8aa3b, v87
	v_exp_f32_e32 v90, v90
	v_exp_f32_e32 v91, v91
	v_pk_fma_f32 v[126:127], v[196:197], v[126:127], v[152:153]
	v_exp_f32_e32 v154, v154
	v_add_f32_e32 v90, 1.0, v90
	v_add_f32_e32 v91, 1.0, v91
	v_rcp_f32_e32 v90, v90
	v_rcp_f32_e32 v91, v91
	v_exp_f32_e32 v155, v155
	v_mul_f32_e32 v152, 0xbfb8aa3b, v126
	v_mul_f32_e32 v153, 0xbfb8aa3b, v127
	v_pk_mul_f32 v[86:87], v[86:87], v[90:91]
	v_lshlrev_b32_e32 v90, 16, v24
	v_and_b32_e32 v91, 0xffff0000, v24
	v_pk_fma_f32 v[84:85], v[170:171], v[90:91], 0 op_sel_hi:[1,1,0]
	v_exp_f32_e32 v152, v152
	v_pk_fma_f32 v[84:85], v[178:179], v[128:129], v[84:85]
	v_exp_f32_e32 v153, v153
	v_pk_fma_f32 v[84:85], v[186:187], v[130:131], v[84:85]
	v_rcp_f32_e32 v156, v156
	v_pk_fma_f32 v[84:85], v[194:195], v[132:133], v[84:85]
	v_lshlrev_b32_e32 v100, 16, v23
	v_and_b32_e32 v101, 0xffff0000, v23
	v_pk_fma_f32 v[68:69], v[176:177], v[100:101], 0 op_sel_hi:[1,1,0]
	v_mul_f32_e32 v88, 0xbfb8aa3b, v84
	v_pk_fma_f32 v[68:69], v[184:185], v[136:137], v[68:69]
	v_exp_f32_e32 v90, v88
	v_pk_fma_f32 v[68:69], v[192:193], v[138:139], v[68:69]
	v_mul_f32_e32 v88, 0xbfb8aa3b, v85
	v_pk_fma_f32 v[68:69], v[200:201], v[140:141], v[68:69]
	v_lshlrev_b32_e32 v80, 16, v22
	v_and_b32_e32 v81, 0xffff0000, v22
	v_pk_fma_f32 v[66:67], v[174:175], v[80:81], 0 op_sel_hi:[1,1,0]
	v_mul_f32_e32 v72, 0xbfb8aa3b, v68
	v_pk_fma_f32 v[66:67], v[182:183], v[144:145], v[66:67]
	v_exp_f32_e32 v76, v72
	v_pk_fma_f32 v[66:67], v[190:191], v[146:147], v[66:67]
	v_mul_f32_e32 v72, 0xbfb8aa3b, v69
	v_pk_fma_f32 v[66:67], v[198:199], v[148:149], v[66:67]
	v_exp_f32_e32 v77, v72
	v_mul_f32_e32 v70, 0xbfb8aa3b, v66
	v_mul_f32_e32 v71, 0xbfb8aa3b, v67
	v_exp_f32_e32 v70, v70
	v_exp_f32_e32 v71, v71
	v_exp_f32_e32 v91, v88
	v_rcp_f32_e32 v157, v157
	v_add_f32_e32 v70, 1.0, v70
	v_add_f32_e32 v71, 1.0, v71
	v_add_f32_e32 v76, 1.0, v76
	v_add_f32_e32 v77, 1.0, v77
	v_rcp_f32_e32 v70, v70
	v_rcp_f32_e32 v71, v71
	v_rcp_f32_e32 v76, v76
	v_rcp_f32_e32 v77, v77
	v_add_f32_e32 v154, 1.0, v154
	v_add_f32_e32 v155, 1.0, v155
	v_add_f32_e32 v90, 1.0, v90
	v_add_f32_e32 v91, 1.0, v91
	v_rcp_f32_e32 v154, v154
	v_rcp_f32_e32 v155, v155
	v_rcp_f32_e32 v90, v90
	v_rcp_f32_e32 v91, v91
	v_add_f32_e32 v152, 1.0, v152
	v_add_f32_e32 v153, 1.0, v153
	v_pk_mul_f32 v[102:103], v[150:151], v[156:157]
	v_pk_mul_f32 v[66:67], v[66:67], v[70:71]
	v_rcp_f32_e32 v152, v152
	v_rcp_f32_e32 v153, v153
	v_pk_mul_f32 v[104:105], v[102:103], v[102:103]
	v_pk_mul_f32 v[68:69], v[68:69], v[76:77]
	v_pk_mul_f32 v[70:71], v[66:67], v[66:67]
	v_pk_mul_f32 v[92:93], v[142:143], v[142:143]
	v_pk_mul_f32 v[76:77], v[68:69], v[68:69]
	v_mov_b32_e32 v78, v104
	v_mov_b32_e32 v79, v70
	v_mov_b32_e32 v70, v105
	v_pk_mul_f32 v[134:135], v[134:135], v[154:155]
	v_pk_mul_f32 v[72:73], v[84:85], v[90:91]
	v_pk_add_f32 v[70:71], v[78:79], v[70:71]
	v_mov_b32_e32 v78, v92
	v_mov_b32_e32 v79, v76
	v_pk_mul_f32 v[154:155], v[134:135], v[134:135]
	v_pk_mul_f32 v[74:75], v[72:73], v[72:73]
	v_pk_add_f32 v[70:71], v[78:79], v[70:71]
	v_mov_b32_e32 v76, v93
	v_pk_mul_f32 v[126:127], v[126:127], v[152:153]
	v_pk_add_f32 v[70:71], v[76:77], v[70:71]
	v_mov_b32_e32 v76, v154
	v_mov_b32_e32 v77, v74
	v_pk_mul_f32 v[152:153], v[126:127], v[126:127]
	v_pk_mul_f32 v[88:89], v[86:87], v[86:87]
	v_pk_add_f32 v[70:71], v[76:77], v[70:71]
	v_mov_b32_e32 v74, v155
	v_pk_add_f32 v[70:71], v[74:75], v[70:71]
	v_mov_b32_e32 v74, v152
	v_mov_b32_e32 v75, v88
	v_pk_add_f32 v[70:71], v[74:75], v[70:71]
	v_mov_b32_e32 v88, v153
	v_pk_add_f32 v[70:71], v[88:89], v[70:71]
	v_mov_b32_e32 v74, v34
	v_mov_b32_e32 v75, v34
	s_nop 0
	v_mov_b32_dpp v74, v70 quad_perm:[1,0,3,2] row_mask:0xf bank_mask:0xf
	v_mov_b32_dpp v75, v71 quad_perm:[1,0,3,2] row_mask:0xf bank_mask:0xf
; #define LAS __attribute__((address_space(3)))
; __device__ __forceinline__ unsigned cvt_pk_bf16(float lo, float hi) { const bf16x2_t r = __builtin_convertvector((f32x2){lo, hi}, bf16x2_t); return __builtin_bit_cast(unsigned, r); }
; __device__ __forceinline__ void gdn_prep_item(LAS unsigned char* lds, int item, int b0, PrepRaw& R, int next_item, const bf16_t* qkv, const float* bg, const float* gconv_w, unsigned char* rec, float* gtarr) {
;     ...
;             if (part < 2) {
;                 s0 = row16_sum(s0); s1 = row16_sum(s1);
;                 float sc0 = rsqrtf(s0 + EPS), sc1 = rsqrtf(s1 + EPS); if (part == 0) { sc0 *= 0.08838834764831845f; sc1 *= 0.08838834764831845f; }
; #pragma unroll
;                 for (int e = 0; e < 8; ++e) { y0[e] *= sc0; y1[e] *= sc1; }
;                 LAS unsigned char* img = lds + (part == 0 ? P2_QN : P2_KN);
;                 u32x4 w0, w1; w0.x = cvt_pk_bf16(y0[0], y0[1]); w0.y = cvt_pk_bf16(y0[2], y0[3]); w0.z = cvt_pk_bf16(y0[4], y0[5]); w0.w = cvt_pk_bf16(y0[6], y0[7]);
;                 w1.x = cvt_pk_bf16(y1[0], y1[1]); w1.y = cvt_pk_bf16(y1[2], y1[3]); w1.z = cvt_pk_bf16(y1[4], y1[5]); w1.w = cvt_pk_bf16(y1[6], y1[7]);
;                 *(LAS u32x4*)(img + (i0 * 136 + 8 * cc) * 2) = w0; *(LAS u32x4*)(img + ((i0 + 1) * 136 + 8 * cc) * 2) = w1;
;                 if (part == 1) {
;                     const float f0 = be0 * eg0, f1 = be1 * eg1;
; #pragma unroll
;                     for (int e = 0; e < 8; ++e) *(LAS unsigned*)(lds + P2_KBT + ((8 * cc + e) * 72 + i0) * 2) = cvt_pk_bf16(y0[e] * f0, y1[e] * f1);
;                 }
;             } else {
; #pragma unroll
;                 for (int e = 0; e < 8; ++e) *(LAS unsigned*)(lds + P2_VBT + ((8 * cc + e) * 72 + i0) * 2) = cvt_pk_bf16(y0[e] * be0, y1[e] * be1);
	v_pk_add_f32 v[70:71], v[70:71], v[74:75]
	v_mov_b32_e32 v74, v34
	v_mov_b32_e32 v75, v34
	s_nop 0
	v_mov_b32_dpp v74, v70 quad_perm:[2,3,0,1] row_mask:0xf bank_mask:0xf
	v_mov_b32_dpp v75, v71 quad_perm:[2,3,0,1] row_mask:0xf bank_mask:0xf
	v_pk_add_f32 v[70:71], v[70:71], v[74:75]
	v_mov_b32_e32 v74, v34
	v_mov_b32_e32 v75, v34
	s_nop 0
	v_mov_b32_dpp v74, v70 row_ror:4 row_mask:0xf bank_mask:0xf
	v_mov_b32_dpp v75, v71 row_ror:4 row_mask:0xf bank_mask:0xf
	v_pk_add_f32 v[70:71], v[70:71], v[74:75]
	v_mov_b32_e32 v74, v34
	v_mov_b32_e32 v75, v34
	s_nop 0
	v_mov_b32_dpp v74, v70 row_ror:8 row_mask:0xf bank_mask:0xf
	v_mov_b32_dpp v75, v71 row_ror:8 row_mask:0xf bank_mask:0xf
	v_pk_add_f32 v[70:71], v[70:71], v[74:75]
	s_nop 0
	v_pk_add_f32 v[70:71], v[70:71], s[16:17] op_sel_hi:[1,0]
	s_nop 0
	v_mul_f32_e32 v74, 0x4b800000, v70
	v_cmp_gt_f32_e32 vcc, s24, v70
	v_mul_f32_e32 v76, 0x4b800000, v71
	s_nop 0
	v_cndmask_b32_e32 v70, v70, v74, vcc
	v_rsq_f32_e32 v70, v70
	s_nop 0
	v_mul_f32_e32 v74, 0x45800000, v70
	v_cndmask_b32_e32 v70, v70, v74, vcc
	v_cmp_gt_f32_e32 vcc, s24, v71
	v_pk_mul_f32 v[74:75], v[102:103], v[70:71] op_sel_hi:[1,0]
	s_nop 0
	v_cndmask_b32_e32 v71, v71, v76, vcc
	v_rsq_f32_e32 v71, v71
	s_nop 0
	v_pk_mul_f32 v[76:77], v[142:143], v[70:71] op_sel_hi:[1,0]
	v_pk_mul_f32 v[78:79], v[134:135], v[70:71] op_sel_hi:[1,0]
	v_pk_mul_f32 v[80:81], v[126:127], v[70:71] op_sel_hi:[1,0]
	v_mul_f32_e32 v70, 0x45800000, v71
	v_cndmask_b32_e32 v70, v71, v70, vcc
	v_pk_mul_f32 v[84:85], v[66:67], v[70:71] op_sel_hi:[1,0]
	v_pk_mul_f32 v[88:89], v[68:69], v[70:71] op_sel_hi:[1,0]
	v_pk_mul_f32 v[90:91], v[72:73], v[70:71] op_sel_hi:[1,0]
	v_pk_mul_f32 v[86:87], v[86:87], v[70:71] op_sel_hi:[1,0]
	v_cvt_pk_bf16_f32 v66, v84, v85
	v_cvt_pk_bf16_f32 v67, v88, v89
	v_cvt_pk_bf16_f32 v68, v90, v91
	v_cvt_pk_bf16_f32 v69, v86, v87
	v_cvt_pk_bf16_f32 v70, v74, v75
	v_cvt_pk_bf16_f32 v71, v76, v77
	v_cvt_pk_bf16_f32 v72, v78, v79
	v_cvt_pk_bf16_f32 v73, v80, v81
	ds_write_b128 v94, v[66:69] offset:17408
	ds_write_b128 v160, v[70:73] offset:17408
	s_waitcnt lgkmcnt(4)
	v_pk_mul_f32 v[66:67], v[36:37], v[96:97]
	v_mov_b32_e32 v68, v84
	v_mov_b32_e32 v69, v74
	v_pk_mul_f32 v[68:69], v[66:67], v[68:69]
	v_mov_b32_e32 v74, v85
	v_cvt_pk_bf16_f32 v70, v68, v69
	v_and_b32_e32 v248, 3, v114
	v_lshlrev_b32_e32 v248, 3, v248
	v_xor_b32_e32 v248, v248, v95
	v_mad_u32_u24 v68, v114, s0, v248
	v_lshl_add_u32 v84, v68, 1, 0
	v_pk_mul_f32 v[68:69], v[66:67], v[74:75]
	v_add_u32_e32 v71, 0xd000, v84
	v_cvt_pk_bf16_f32 v68, v68, v69
	ds_write2_b32 v71, v70, v68 offset1:36
	v_mov_b32_e32 v68, v88
	v_mov_b32_e32 v69, v76
	v_pk_mul_f32 v[68:69], v[66:67], v[68:69]
	v_mov_b32_e32 v76, v89
	v_cvt_pk_bf16_f32 v70, v68, v69
	v_pk_mul_f32 v[68:69], v[66:67], v[76:77]
	s_nop 0
	v_cvt_pk_bf16_f32 v68, v68, v69
	ds_write2_b32 v71, v70, v68 offset0:72 offset1:108
	v_mov_b32_e32 v68, v90
	v_mov_b32_e32 v69, v78
	v_pk_mul_f32 v[68:69], v[66:67], v[68:69]
	v_mov_b32_e32 v78, v91
	v_cvt_pk_bf16_f32 v70, v68, v69
	v_pk_mul_f32 v[68:69], v[66:67], v[78:79]
	s_nop 0
	v_cvt_pk_bf16_f32 v68, v68, v69
	ds_write2_b32 v71, v70, v68 offset0:144 offset1:180
	v_mov_b32_e32 v68, v86
	v_mov_b32_e32 v69, v80
	v_mov_b32_e32 v80, v87
	v_pk_mul_f32 v[68:69], v[66:67], v[68:69]
	v_pk_mul_f32 v[66:67], v[66:67], v[80:81]
	v_cvt_pk_bf16_f32 v68, v68, v69
	v_cvt_pk_bf16_f32 v66, v66, v67
	ds_write2_b32 v71, v68, v66 offset0:216 offset1:252
	s_waitcnt vmcnt(0)
	s_movk_i32 s0, 0x5000
	v_add_co_u32_e32 v66, vcc, s0, v98
	s_mov_b32 s0, 0x8000
	s_nop 0
	v_addc_co_u32_e32 v67, vcc, 0, v99, vcc
	v_add_co_u32_e32 v70, vcc, s0, v98
	s_nop 0
	v_addc_co_u32_e32 v71, vcc, 0, v99, vcc
	s_mov_b32 s0, 0xb000
	v_add_co_u32_e32 v74, vcc, s0, v98
	s_nop 0
	v_addc_co_u32_e32 v75, vcc, 0, v99, vcc
	s_mov_b64 s[0:1], 0x2000
	s_mov_b64 s[4:5], 0x5000
	v_lshlrev_b32_e32 v101, 16, v54
	v_lshlrev_b32_e32 v105, 16, v62
	v_and_b32_e32 v123, 0xffff0000, v54
	v_and_b32_e32 v127, 0xffff0000, v62
	v_lshlrev_b32_e32 v130, 16, v47
	v_lshlrev_b32_e32 v133, 16, v51
	v_lshlrev_b32_e32 v135, 16, v63
	v_and_b32_e32 v54, 0xffff0000, v47
	v_and_b32_e32 v47, 0xffff0000, v51
	v_and_b32_e32 v51, 0xffff0000, v63
	v_lshl_add_u64 v[62:63], v[98:99], 0, s[0:1]
	v_lshl_add_u64 v[78:79], v[98:99], 0, s[4:5]
	s_mov_b64 s[6:7], 0x8000
	v_add_u32_e32 v138, 0x8800, v84
	s_mov_b64 s[8:9], 0xb000
	v_lshl_add_u64 v[80:81], v[98:99], 0, s[6:7]
	v_lshl_add_u64 v[98:99], v[98:99], 0, s[8:9]
	s_nop 0
	v_lshlrev_b32_e32 v100, 16, v46
	v_and_b32_e32 v122, 0xffff0000, v46
	v_lshlrev_b32_e32 v103, 16, v50
	v_and_b32_e32 v125, 0xffff0000, v50
	v_lshlrev_b32_e32 v131, 16, v55
	v_mov_b32_e32 v102, v101
	v_mov_b32_e32 v124, v123
	v_mov_b32_e32 v104, v103
	v_mov_b32_e32 v126, v125
	v_mov_b32_e32 v132, v131
	v_lshlrev_b32_e32 v121, 16, v58
	v_and_b32_e32 v129, 0xffff0000, v58
	v_mov_b32_e32 v120, v105
	v_mov_b32_e32 v128, v127
	v_mov_b32_e32 v134, v133
	v_lshlrev_b32_e32 v137, 16, v59
	v_and_b32_e32 v55, 0xffff0000, v55
	v_mov_b32_e32 v136, v135
	v_mov_b32_e32 v46, v55
	v_mov_b32_e32 v50, v47
	v_pk_fma_f32 v[62:63], v[202:203], v[100:101], 0 op_sel_hi:[0,1,0]
	v_pk_fma_f32 v[94:95], v[202:203], v[122:123], 0 op_sel:[1,0,0] op_sel_hi:[1,1,0]
	v_pk_fma_f32 v[98:99], v[204:205], v[130:131], 0 op_sel_hi:[0,1,0]
	v_mov_b32_e32 v58, v205
	v_pk_fma_f32 v[62:63], v[206:207], v[102:103], v[62:63] op_sel_hi:[0,1,1]
	v_pk_fma_f32 v[66:67], v[206:207], v[124:125], v[94:95] op_sel:[1,0,0]
	v_pk_fma_f32 v[94:95], v[208:209], v[132:133], v[98:99] op_sel_hi:[0,1,1]
	v_pk_fma_f32 v[62:63], v[210:211], v[104:105], v[62:63] op_sel_hi:[0,1,1]
; #define LAS __attribute__((address_space(3)))
; __device__ __forceinline__ unsigned cvt_pk_bf16(float lo, float hi) { const bf16x2_t r = __builtin_convertvector((f32x2){lo, hi}, bf16x2_t); return __builtin_bit_cast(unsigned, r); }
; __device__ __forceinline__ void gdn_prep_load(PrepRaw& R, int item, int b0, const bf16_t* qkv, const float* bg, int tid) {
;     const int h = item & 7, c = (item >> 3) % NCHUNK, b = b0 + (item >> 3) / NCHUNK;
;     const int tbase = 64 * c - 48, cc = tid & 15, i0 = (tid >> 4) * 2;
; #pragma unroll
;     for (int part = 0; part < 2; ++part)
; #pragma unroll
;         for (int j = 0; j < 5; ++j) { const int t = tbase + i0 - 3 + j;
;             R.x[part][j] = (t >= 0) ? *(const u32x4*)(qkv + (size_t)(b * LP + t) * CONVCH + part * 1024 + h * 128 + 8 * cc) : (u32x4){0u, 0u, 0u, 0u}; }
; __device__ __forceinline__ void gdn_prep_item(LAS unsigned char* lds, int item, int b0, PrepRaw& R, int next_item, const bf16_t* qkv, const float* bg, const float* gconv_w, unsigned char* rec, float* gtarr) {
;     ...
;             } else {
; #pragma unroll
;                 for (int e = 0; e < 8; ++e) *(LAS unsigned*)(lds + P2_VBT + ((8 * cc + e) * 72 + i0) * 2) = cvt_pk_bf16(y0[e] * be0, y1[e] * be1);
;             }
;             __builtin_amdgcn_sched_barrier(0);
;         }
;     }
;     if (next_item >= 0) gdn_prep_load(R, next_item, b0, qkv, bg, tid);
	v_pk_fma_f32 v[66:67], v[210:211], v[126:127], v[66:67] op_sel:[1,0,0]
	v_pk_fma_f32 v[70:71], v[212:213], v[134:135], v[94:95] op_sel_hi:[0,1,1]
	v_pk_fma_f32 v[62:63], v[214:215], v[120:121], v[62:63] op_sel_hi:[0,1,1]
	v_pk_fma_f32 v[66:67], v[214:215], v[128:129], v[66:67] op_sel:[1,0,0]
	v_pk_fma_f32 v[54:55], v[58:59], v[54:55], 0 op_sel_hi:[0,1,0]
	v_pk_fma_f32 v[70:71], v[216:217], v[136:137], v[70:71] op_sel_hi:[0,1,1]
	v_mul_f32_e32 v58, 0xbfb8aa3b, v63
	v_mul_f32_e32 v68, 0xbfb8aa3b, v62
	v_mul_f32_e32 v72, 0xbfb8aa3b, v67
	v_mul_f32_e32 v74, 0xbfb8aa3b, v66
	v_mul_f32_e32 v75, 0xbfb8aa3b, v71
	v_exp_f32_e32 v58, v58
	v_exp_f32_e32 v68, v68
	v_exp_f32_e32 v72, v72
	v_exp_f32_e32 v74, v74
	v_exp_f32_e32 v75, v75
	v_add_f32_e32 v58, 1.0, v58
	v_add_f32_e32 v68, 1.0, v68
	v_add_f32_e32 v72, 1.0, v72
	v_add_f32_e32 v94, 1.0, v74
	v_add_f32_e32 v96, 1.0, v75
	v_rcp_f32_e32 v75, v58
	v_rcp_f32_e32 v74, v68
	v_rcp_f32_e32 v95, v72
	v_rcp_f32_e32 v94, v94
	v_and_b32_e32 v59, 0xffff0000, v59
	v_pk_mul_f32 v[62:63], v[62:63], v[74:75]
	v_mul_f32_e32 v76, 0xbfb8aa3b, v70
	v_pk_mul_f32 v[66:67], v[66:67], v[94:95]
	v_pk_mul_f32 v[62:63], v[36:37], v[62:63]
	v_pk_mul_f32 v[66:67], v[36:37], v[66:67]
	v_cvt_pk_bf16_f32 v58, v62, v63
	v_cvt_pk_bf16_f32 v62, v66, v67
	ds_write2_b32 v138, v58, v62 offset1:36
	v_mov_b32_e32 v62, v209
	v_pk_fma_f32 v[46:47], v[62:63], v[46:47], v[54:55] op_sel_hi:[0,1,1]
	v_mov_b32_e32 v54, v213
	v_mov_b32_e32 v58, v51
	v_pk_fma_f32 v[46:47], v[54:55], v[50:51], v[46:47] op_sel_hi:[0,1,1]
	v_mov_b32_e32 v50, v217
	v_pk_fma_f32 v[46:47], v[50:51], v[58:59], v[46:47] op_sel_hi:[0,1,1]
	v_mul_f32_e32 v50, 0xbfb8aa3b, v47
	v_exp_f32_e32 v50, v50
	v_mul_f32_e32 v51, 0xbfb8aa3b, v46
	v_exp_f32_e32 v54, v51
	v_exp_f32_e32 v76, v76
	v_add_f32_e32 v50, 1.0, v50
	v_rcp_f32_e32 v51, v50
	v_add_f32_e32 v50, 1.0, v54
	v_rcp_f32_e32 v50, v50
	v_add_f32_e32 v68, 1.0, v76
	v_rcp_f32_e32 v97, v96
	v_rcp_f32_e32 v96, v68
	v_pk_mul_f32 v[46:47], v[46:47], v[50:51]
	v_lshlrev_b32_e32 v51, 16, v52
	v_pk_mul_f32 v[46:47], v[36:37], v[46:47]
	v_pk_mul_f32 v[54:55], v[70:71], v[96:97]
	v_cvt_pk_bf16_f32 v63, v46, v47
	v_lshlrev_b32_e32 v47, 16, v56
	v_lshlrev_b32_e32 v46, 16, v48
	v_pk_mul_f32 v[54:55], v[36:37], v[54:55]
	v_mov_b32_e32 v50, v47
	v_pk_fma_f32 v[46:47], v[222:223], v[46:47], 0 op_sel_hi:[0,1,0]
	v_cvt_pk_bf16_f32 v62, v54, v55
	v_lshlrev_b32_e32 v55, 16, v64
	v_mov_b32_e32 v54, v51
	v_pk_fma_f32 v[46:47], v[226:227], v[50:51], v[46:47] op_sel_hi:[0,1,1]
	v_lshlrev_b32_e32 v59, 16, v60
	v_mov_b32_e32 v58, v55
	v_pk_fma_f32 v[46:47], v[230:231], v[54:55], v[46:47] op_sel_hi:[0,1,1]
	v_pk_fma_f32 v[46:47], v[234:235], v[58:59], v[46:47] op_sel_hi:[0,1,1]
	v_mul_f32_e32 v50, 0xbfb8aa3b, v47
	v_exp_f32_e32 v50, v50
	v_mul_f32_e32 v51, 0xbfb8aa3b, v46
	v_exp_f32_e32 v54, v51
	v_and_b32_e32 v55, 0xffff0000, v56
	v_add_f32_e32 v50, 1.0, v50
	v_rcp_f32_e32 v51, v50
	v_add_f32_e32 v50, 1.0, v54
	v_and_b32_e32 v54, 0xffff0000, v48
	v_and_b32_e32 v59, 0xffff0000, v52
	v_mov_b32_e32 v58, v55
	v_pk_fma_f32 v[54:55], v[222:223], v[54:55], 0 op_sel:[1,0,0] op_sel_hi:[1,1,0]
	ds_write2_b32 v138, v62, v63 offset0:72 offset1:108
	v_and_b32_e32 v63, 0xffff0000, v64
	v_mov_b32_e32 v62, v59
	v_pk_fma_f32 v[54:55], v[226:227], v[58:59], v[54:55] op_sel:[1,0,0]
	v_and_b32_e32 v67, 0xffff0000, v60
	v_mov_b32_e32 v66, v63
	v_pk_fma_f32 v[54:55], v[230:231], v[62:63], v[54:55] op_sel:[1,0,0]
	v_rcp_f32_e32 v50, v50
	v_pk_fma_f32 v[54:55], v[234:235], v[66:67], v[54:55] op_sel:[1,0,0]
	v_pk_mul_f32 v[46:47], v[46:47], v[50:51]
	v_mul_f32_e32 v48, 0xbfb8aa3b, v55
	v_exp_f32_e32 v48, v48
	v_mul_f32_e32 v52, 0xbfb8aa3b, v54
	v_exp_f32_e32 v52, v52
	v_pk_mul_f32 v[46:47], v[36:37], v[46:47]
	v_add_f32_e32 v48, 1.0, v48
	v_rcp_f32_e32 v59, v48
	v_add_f32_e32 v48, 1.0, v52
	v_rcp_f32_e32 v58, v48
	v_cvt_pk_bf16_f32 v48, v46, v47
	v_lshlrev_b32_e32 v51, 16, v53
	v_pk_mul_f32 v[46:47], v[54:55], v[58:59]
	s_nop 0
	v_pk_mul_f32 v[46:47], v[36:37], v[46:47]
	v_lshlrev_b32_e32 v55, 16, v65
	v_cvt_pk_bf16_f32 v52, v46, v47
	v_lshlrev_b32_e32 v46, 16, v49
	v_lshlrev_b32_e32 v47, 16, v57
	v_mov_b32_e32 v50, v47
	v_pk_fma_f32 v[46:47], v[224:225], v[46:47], 0 op_sel_hi:[0,1,0]
	v_mov_b32_e32 v54, v51
	v_pk_fma_f32 v[46:47], v[228:229], v[50:51], v[46:47] op_sel_hi:[0,1,1]
	v_lshlrev_b32_e32 v59, 16, v61
	v_mov_b32_e32 v58, v55
	v_pk_fma_f32 v[46:47], v[232:233], v[54:55], v[46:47] op_sel_hi:[0,1,1]
	v_pk_fma_f32 v[46:47], v[236:237], v[58:59], v[46:47] op_sel_hi:[0,1,1]
	v_mul_f32_e32 v50, 0xbfb8aa3b, v47
	v_exp_f32_e32 v50, v50
	v_mul_f32_e32 v51, 0xbfb8aa3b, v46
	v_exp_f32_e32 v54, v51
	ds_write2_b32 v138, v48, v52 offset0:144 offset1:180
	v_add_f32_e32 v48, 1.0, v50
	v_rcp_f32_e32 v51, v48
	v_add_f32_e32 v58, 1.0, v54
	v_and_b32_e32 v55, 0xffff0000, v57
	v_and_b32_e32 v54, 0xffff0000, v49
	v_mov_b32_e32 v50, v225
	v_and_b32_e32 v49, 0xffff0000, v53
	v_mov_b32_e32 v48, v55
	v_pk_fma_f32 v[54:55], v[50:51], v[54:55], 0 op_sel_hi:[0,1,0]
	v_mov_b32_e32 v50, v229
	v_and_b32_e32 v53, 0xffff0000, v65
	v_mov_b32_e32 v52, v49
	v_pk_fma_f32 v[48:49], v[50:51], v[48:49], v[54:55] op_sel_hi:[0,1,1]
	v_mov_b32_e32 v50, v233
	v_and_b32_e32 v57, 0xffff0000, v61
	v_mov_b32_e32 v56, v53
	v_pk_fma_f32 v[48:49], v[50:51], v[52:53], v[48:49] op_sel_hi:[0,1,1]
	v_mov_b32_e32 v50, v237
	v_pk_fma_f32 v[48:49], v[50:51], v[56:57], v[48:49] op_sel_hi:[0,1,1]
	v_mul_f32_e32 v50, 0xbfb8aa3b, v49
	v_exp_f32_e32 v52, v50
	v_mul_f32_e32 v50, 0xbfb8aa3b, v48
	v_exp_f32_e32 v54, v50
	v_rcp_f32_e32 v50, v58
	v_add_f32_e32 v52, 1.0, v52
	v_rcp_f32_e32 v53, v52
	v_add_f32_e32 v52, 1.0, v54
	v_rcp_f32_e32 v52, v52
	v_pk_mul_f32 v[46:47], v[46:47], v[50:51]
	s_nop 0
	v_pk_mul_f32 v[46:47], v[36:37], v[46:47]
	s_nop 0
	v_cvt_pk_bf16_f32 v50, v46, v47
	v_pk_mul_f32 v[46:47], v[48:49], v[52:53]
	s_nop 0
	v_pk_mul_f32 v[36:37], v[36:37], v[46:47]
	s_nop 0
	v_cvt_pk_bf16_f32 v36, v36, v37
	ds_write2_b32 v138, v50, v36 offset0:216 offset1:252
	s_cmp_gt_i32 s14, -1
	v_lshlrev_b32_e32 v54, 4, v116
	s_cbranch_scc0 .LBB0_508
	s_lshr_b32 s0, s14, 3
	s_mul_hi_u32 s1, s0, 0x1f07c1f1
	s_lshr_b32 s1, s1, 2
	s_mul_i32 s1, s1, 33
	s_and_b32 s34, s14, 7
	s_sub_i32 s0, s0, s1
	s_mul_hi_u32 s1, s14, 0x3e0f83e1
	s_lshr_b32 s14, s1, 6
	s_lshl_b32 s35, s0, 6
	s_lshl_b32 s0, s34, 8
	s_add_u32 s0, s88, s0
	s_addc_u32 s1, s89, 0
	v_and_b32_e32 v2, 0xf0, v54
	v_mov_b32_e32 v3, v34
	v_mov_b32_e32 v4, v34
	v_mov_b32_e32 v5, v34
	v_add_u32_e32 v18, s35, v119
	s_mulk_i32 s14, 0x810
	v_lshl_add_u64 v[46:47], s[0:1], 0, v[2:3]
	v_mov_b32_e32 v2, v34
	v_mov_b64_e32 v[8:9], v[4:5]
	v_cmp_lt_i32_e32 vcc, -1, v18
	v_add_u32_e32 v26, s14, v18
	v_mov_b64_e32 v[6:7], v[2:3]
	s_and_saveexec_b64 s[0:1], vcc
	s_cbranch_execz .LBB0_485
	v_mad_u64_u32 v[6:7], s[4:5], v26, s2, v[46:47]
	global_load_dwordx4 v[6:9], v[6:7], off

; __device__ __forceinline__ float silu_f(float x) { return x * __builtin_amdgcn_rcpf(1.0f + __expf(-x)); }
; __device__ __forceinline__ void gdn_prep_item(LAS unsigned char* lds, int item, int b0, PrepRaw& R, int next_item, const bf16_t* qkv, const float* bg, const float* gconv_w, unsigned char* rec, float* gtarr) {
;     ...
;     {
;         const int cc = tid & 15, i0 = (tid >> 4) * 2;
;         const float be0 = Bs[i0], be1 = Bs[i0 + 1], eg0 = EG[i0], eg1 = EG[i0 + 1];
; #pragma unroll
;         for (int part = 0; part < 3; ++part) {
;             const int col = part * 1024 + h * 128 + 8 * cc;
;             float y0[8], y1[8];
; #pragma unroll
;             for (int e = 0; e < 8; ++e) { y0[e] = 0.f; y1[e] = 0.f; }
; #pragma unroll
;             for (int j = 0; j < 5; ++j) { const u32x4 v = part < 2 ? R.x[part < 2 ? part : 0][j] : xv[j]; const unsigned vv[4] = {v.x, v.y, v.z, v.w}; float x[8];
; #pragma unroll
;                 for (int e = 0; e < 4; ++e) { x[2 * e] = __uint_as_float(vv[e] << 16); x[2 * e + 1] = __uint_as_float(vv[e] & 0xffff0000u); }
;                 if (j < 4) { const f32x4 wa = *(const f32x4*)(gconv_w + j * CONVCH + col), wb = *(const f32x4*)(gconv_w + j * CONVCH + col + 4);
; #pragma unroll
;                     for (int e = 0; e < 8; ++e) y0[e] += (e < 4 ? wa[e] : wb[e - 4]) * x[e]; }
;                 if (j > 0) { const f32x4 wa = *(const f32x4*)(gconv_w + (j - 1) * CONVCH + col), wb = *(const f32x4*)(gconv_w + (j - 1) * CONVCH + col + 4);
; #pragma unroll
;                     for (int e = 0; e < 8; ++e) y1[e] += (e < 4 ? wa[e] : wb[e - 4]) * x[e]; } }
;             float s0 = 0.f, s1 = 0.f;
; #pragma unroll
;             for (int e = 0; e < 8; ++e) { y0[e] = silu_f(y0[e]); y1[e] = silu_f(y1[e]); s0 += y0[e] * y0[e]; s1 += y1[e] * y1[e]; }
.LBB0_655:
	s_or_b64 exec, exec, s[0:1]
	s_waitcnt vmcnt(0)
	v_or_b32_e32 v58, s6, v90
	v_lshlrev_b32_e32 v86, 2, v58
	v_mov_b32_e32 v87, 0
	s_waitcnt lgkmcnt(0)
	s_barrier
	v_lshl_add_u64 v[88:89], s[72:73], 0, v[86:87]
	global_load_dwordx4 v[78:81], v86, s[72:73] offset:16
	s_mov_b64 s[0:1], 0x3000
	v_lshl_add_u64 v[62:63], v[88:89], 0, s[0:1]
	s_mov_b64 s[0:1], 0x6000
	v_lshl_add_u64 v[64:65], v[88:89], 0, s[0:1]
	global_load_dwordx4 v[82:85], v[62:63], off offset:16
	global_load_dwordx4 v[104:107], v[64:65], off offset:16
	s_mov_b64 s[0:1], 0x9000
	v_lshl_add_u64 v[62:63], v[88:89], 0, s[0:1]
	global_load_dwordx4 v[108:111], v[62:63], off offset:16
	s_nop 0
	global_load_dwordx4 v[62:65], v86, s[72:73]
	s_movk_i32 s0, 0x4000
	v_add_co_u32_e32 v94, vcc, s0, v88
	s_movk_i32 s1, 0x7000
	s_nop 0
	v_addc_co_u32_e32 v95, vcc, 0, v89, vcc
	v_add_co_u32_e32 v96, vcc, s1, v88
	s_mov_b32 s4, 0xa000
	s_nop 0
	v_addc_co_u32_e32 v97, vcc, 0, v89, vcc
	v_add_co_u32_e32 v92, vcc, s4, v88
	global_load_dwordx4 v[66:69], v[94:95], off offset:-4096
	global_load_dwordx4 v[70:73], v[96:97], off offset:-4096
	v_addc_co_u32_e32 v93, vcc, 0, v89, vcc
	global_load_dwordx4 v[74:77], v[92:93], off offset:-4096
	v_or_b32_e32 v103, 1, v98
	v_lshlrev_b32_e32 v58, 2, v102
	s_add_i32 s0, 0, 0x1d100
	s_add_i32 s21, 0, 0x1d200
	v_lshlrev_b32_e32 v112, 16, v61
	v_and_b32_e32 v113, 0xffff0000, v61
	v_lshlrev_b32_e32 v120, 16, v60
	v_and_b32_e32 v121, 0xffff0000, v60
	v_lshlrev_b32_e32 v122, 16, v52
	v_and_b32_e32 v123, 0xffff0000, v52
	v_lshlrev_b32_e32 v52, 2, v103
	v_lshlrev_b32_e32 v114, 16, v53
	v_and_b32_e32 v115, 0xffff0000, v53
	v_lshlrev_b32_e32 v116, 16, v49
	v_and_b32_e32 v117, 0xffff0000, v49
	v_lshlrev_b32_e32 v118, 16, v57
	v_and_b32_e32 v119, 0xffff0000, v57
	v_lshlrev_b32_e32 v124, 16, v48
	v_and_b32_e32 v125, 0xffff0000, v48
	v_lshlrev_b32_e32 v48, 16, v56
	v_and_b32_e32 v49, 0xffff0000, v56
	v_lshlrev_b32_e32 v56, 16, v59
	v_and_b32_e32 v57, 0xffff0000, v59
	v_add_u32_e32 v60, s0, v58
	v_add_u32_e32 v61, s21, v58
	v_add_u32_e32 v128, s0, v52
	v_add_u32_e32 v129, s21, v52
	v_lshlrev_b32_e32 v130, 16, v47
	v_and_b32_e32 v131, 0xffff0000, v47
	v_lshlrev_b32_e32 v132, 16, v55
	v_and_b32_e32 v133, 0xffff0000, v55
	v_lshlrev_b32_e32 v136, 16, v91
	v_and_b32_e32 v137, 0xffff0000, v91
	v_lshlrev_b32_e32 v140, 16, v50
	v_and_b32_e32 v141, 0xffff0000, v50
	s_movk_i32 s1, 0x88
	s_mov_b32 s0, 0x358637bd
	s_mov_b32 s4, 0x800000
	v_lshrrev_b32_e32 v86, 4, v101
	s_waitcnt vmcnt(7)
	v_pk_fma_f32 v[52:53], v[80:81], v[112:113], 0 op_sel_hi:[1,1,0]
	v_pk_fma_f32 v[58:59], v[78:79], v[120:121], 0 op_sel_hi:[1,1,0]
	s_waitcnt vmcnt(6)
	v_pk_fma_f32 v[52:53], v[84:85], v[114:115], v[52:53]
	v_pk_fma_f32 v[58:59], v[82:83], v[122:123], v[58:59]
	s_waitcnt vmcnt(5)
	v_pk_fma_f32 v[52:53], v[106:107], v[116:117], v[52:53]
	v_pk_fma_f32 v[58:59], v[104:105], v[124:125], v[58:59]
	s_waitcnt vmcnt(4)
	v_pk_fma_f32 v[52:53], v[110:111], v[118:119], v[52:53]
	v_pk_fma_f32 v[118:119], v[108:109], v[48:49], v[58:59]
	v_mul_f32_e32 v48, 0xbfb8aa3b, v52
	v_mul_f32_e32 v49, 0xbfb8aa3b, v53
	v_mul_f32_e32 v58, 0xbfb8aa3b, v118
	v_mul_f32_e32 v59, 0xbfb8aa3b, v119
	v_exp_f32_e32 v48, v48
	v_exp_f32_e32 v49, v49
	v_exp_f32_e32 v58, v58
	v_exp_f32_e32 v59, v59
	v_add_f32_e32 v48, 1.0, v48
	v_add_f32_e32 v49, 1.0, v49
	v_add_f32_e32 v58, 1.0, v58
	v_add_f32_e32 v59, 1.0, v59
	v_rcp_f32_e32 v48, v48
	v_rcp_f32_e32 v49, v49
	v_rcp_f32_e32 v126, v58
	v_rcp_f32_e32 v127, v59
	ds_read_b32 v58, v60
	ds_read_b32 v59, v128
	ds_read_b32 v60, v61
	ds_read_b32 v61, v129
	v_pk_mul_f32 v[48:49], v[52:53], v[48:49]
	v_lshlrev_b32_e32 v128, 16, v51
	v_pk_mul_f32 v[52:53], v[118:119], v[126:127]
	s_waitcnt vmcnt(3)
	v_pk_fma_f32 v[126:127], v[64:65], v[56:57], 0 op_sel_hi:[1,1,0]
	v_and_b32_e32 v129, 0xffff0000, v51
	s_waitcnt vmcnt(2)
	v_pk_fma_f32 v[126:127], v[68:69], v[128:129], v[126:127]
	v_pk_fma_f32 v[138:139], v[62:63], v[136:137], 0 op_sel_hi:[1,1,0]
	s_waitcnt vmcnt(1)
	v_pk_fma_f32 v[126:127], v[72:73], v[130:131], v[126:127]
	v_pk_mul_f32 v[118:119], v[48:49], v[48:49]
	s_waitcnt vmcnt(0)
	v_pk_fma_f32 v[126:127], v[76:77], v[132:133], v[126:127]
	v_pk_mul_f32 v[132:133], v[52:53], v[52:53]
	v_mul_f32_e32 v47, 0xbfb8aa3b, v126
	v_exp_f32_e32 v47, v47
	v_mul_f32_e32 v51, 0xbfb8aa3b, v127
	v_exp_f32_e32 v51, v51
	v_add_f32_e32 v47, 1.0, v47
	v_rcp_f32_e32 v134, v47
	v_add_f32_e32 v47, 1.0, v51
	v_pk_fma_f32 v[50:51], v[66:67], v[140:141], v[138:139]
	v_lshlrev_b32_e32 v138, 16, v46
	v_and_b32_e32 v139, 0xffff0000, v46
	v_rcp_f32_e32 v135, v47
	v_pk_fma_f32 v[46:47], v[70:71], v[138:139], v[50:51]
	v_lshlrev_b32_e32 v50, 16, v54
	v_and_b32_e32 v51, 0xffff0000, v54
	v_pk_fma_f32 v[46:47], v[74:75], v[50:51], v[46:47]
	s_nop 0
	v_mul_f32_e32 v50, 0xbfb8aa3b, v46
	v_exp_f32_e32 v54, v50
	v_mul_f32_e32 v50, 0xbfb8aa3b, v47
	v_exp_f32_e32 v55, v50
	v_pk_mul_f32 v[50:51], v[126:127], v[134:135]
	v_lshlrev_b32_e32 v126, 16, v45
	v_and_b32_e32 v127, 0xffff0000, v45
	v_pk_fma_f32 v[80:81], v[80:81], v[126:127], 0 op_sel_hi:[1,1,0]
	v_add_f32_e32 v54, 1.0, v54
	v_pk_fma_f32 v[80:81], v[84:85], v[112:113], v[80:81]
	v_add_f32_e32 v55, 1.0, v55
	v_pk_fma_f32 v[80:81], v[106:107], v[114:115], v[80:81]
	v_rcp_f32_e32 v54, v54
	v_pk_fma_f32 v[80:81], v[110:111], v[116:117], v[80:81]
	v_rcp_f32_e32 v55, v55
	v_mul_f32_e32 v45, 0xbfb8aa3b, v80
	v_exp_f32_e32 v45, v45
	v_mul_f32_e32 v84, 0xbfb8aa3b, v81
	v_exp_f32_e32 v85, v84
	v_pk_mul_f32 v[46:47], v[46:47], v[54:55]
	v_add_f32_e32 v45, 1.0, v45
	v_rcp_f32_e32 v84, v45
	v_add_f32_e32 v45, 1.0, v85
	v_rcp_f32_e32 v85, v45
	v_pk_mul_f32 v[54:55], v[46:47], v[46:47]
; #define LAS __attribute__((address_space(3)))
; __device__ __forceinline__ unsigned cvt_pk_bf16(float lo, float hi) { const bf16x2_t r = __builtin_convertvector((f32x2){lo, hi}, bf16x2_t); return __builtin_bit_cast(unsigned, r); }
; __device__ __forceinline__ float silu_f(float x) { return x * __builtin_amdgcn_rcpf(1.0f + __expf(-x)); }
; __device__ __forceinline__ void gdn_prep_item(LAS unsigned char* lds, int item, int b0, PrepRaw& R, int next_item, const bf16_t* qkv, const float* bg, const float* gconv_w, unsigned char* rec, float* gtarr) {
;     ...
;             float s0 = 0.f, s1 = 0.f;
; #pragma unroll
;             for (int e = 0; e < 8; ++e) { y0[e] = silu_f(y0[e]); y1[e] = silu_f(y1[e]); s0 += y0[e] * y0[e]; s1 += y1[e] * y1[e]; }
;             if (part < 2) {
;                 s0 = row16_sum(s0); s1 = row16_sum(s1);
;                 float sc0 = rsqrtf(s0 + EPS), sc1 = rsqrtf(s1 + EPS); if (part == 0) { sc0 *= 0.08838834764831845f; sc1 *= 0.08838834764831845f; }
; #pragma unroll
;                 for (int e = 0; e < 8; ++e) { y0[e] *= sc0; y1[e] *= sc1; }
;                 LAS unsigned char* img = lds + (part == 0 ? P2_QN : P2_KN);
;                 u32x4 w0, w1; w0.x = cvt_pk_bf16(y0[0], y0[1]); w0.y = cvt_pk_bf16(y0[2], y0[3]); w0.z = cvt_pk_bf16(y0[4], y0[5]); w0.w = cvt_pk_bf16(y0[6], y0[7]);
;                 w1.x = cvt_pk_bf16(y1[0], y1[1]); w1.y = cvt_pk_bf16(y1[2], y1[3]); w1.z = cvt_pk_bf16(y1[4], y1[5]); w1.w = cvt_pk_bf16(y1[6], y1[7]);
;                 *(LAS u32x4*)(img + (i0 * 136 + 8 * cc) * 2) = w0; *(LAS u32x4*)(img + ((i0 + 1) * 136 + 8 * cc) * 2) = w1;
	v_pk_mul_f32 v[106:107], v[50:51], v[50:51]
	v_pk_mul_f32 v[80:81], v[80:81], v[84:85]
	v_lshlrev_b32_e32 v84, 16, v44
	v_and_b32_e32 v85, 0xffff0000, v44
	v_pk_fma_f32 v[44:45], v[78:79], v[84:85], 0 op_sel_hi:[1,1,0]
	v_lshlrev_b32_e32 v84, 16, v43
	v_and_b32_e32 v85, 0xffff0000, v43
	v_pk_fma_f32 v[64:65], v[64:65], v[84:85], 0 op_sel_hi:[1,1,0]
	v_pk_fma_f32 v[44:45], v[82:83], v[120:121], v[44:45]
	v_pk_fma_f32 v[56:57], v[68:69], v[56:57], v[64:65]
	v_lshlrev_b32_e32 v68, 16, v42
	v_pk_fma_f32 v[56:57], v[72:73], v[128:129], v[56:57]
	v_and_b32_e32 v69, 0xffff0000, v42
	v_pk_fma_f32 v[56:57], v[76:77], v[130:131], v[56:57]
	v_pk_fma_f32 v[44:45], v[104:105], v[122:123], v[44:45]
	v_mul_f32_e32 v43, 0xbfb8aa3b, v56
	v_exp_f32_e32 v43, v43
	v_mul_f32_e32 v64, 0xbfb8aa3b, v57
	v_exp_f32_e32 v65, v64
	v_pk_fma_f32 v[44:45], v[108:109], v[124:125], v[44:45]
	v_add_f32_e32 v43, 1.0, v43
	v_rcp_f32_e32 v64, v43
	v_pk_fma_f32 v[42:43], v[62:63], v[68:69], 0 op_sel_hi:[1,1,0]
	v_mul_f32_e32 v78, 0xbfb8aa3b, v44
	v_pk_fma_f32 v[42:43], v[66:67], v[136:137], v[42:43]
	v_exp_f32_e32 v82, v78
	v_pk_fma_f32 v[42:43], v[70:71], v[140:141], v[42:43]
	v_mul_f32_e32 v78, 0xbfb8aa3b, v45
	v_pk_fma_f32 v[42:43], v[74:75], v[138:139], v[42:43]
	v_exp_f32_e32 v83, v78
	v_mul_f32_e32 v62, 0xbfb8aa3b, v42
	v_mul_f32_e32 v63, 0xbfb8aa3b, v43
	v_exp_f32_e32 v62, v62
	v_exp_f32_e32 v63, v63
	v_add_f32_e32 v65, 1.0, v65
	v_rcp_f32_e32 v65, v65
	v_add_f32_e32 v62, 1.0, v62
	v_add_f32_e32 v63, 1.0, v63
	v_rcp_f32_e32 v62, v62
	v_rcp_f32_e32 v63, v63
	v_add_f32_e32 v82, 1.0, v82
	v_add_f32_e32 v83, 1.0, v83
	v_rcp_f32_e32 v82, v82
	v_rcp_f32_e32 v83, v83
	v_pk_mul_f32 v[42:43], v[42:43], v[62:63]
	v_pk_mul_f32 v[56:57], v[56:57], v[64:65]
	v_pk_mul_f32 v[62:63], v[42:43], v[42:43]
	v_pk_mul_f32 v[64:65], v[56:57], v[56:57]
	v_mov_b32_e32 v68, v54
	v_mov_b32_e32 v69, v62
	v_mov_b32_e32 v62, v55
	v_pk_mul_f32 v[44:45], v[44:45], v[82:83]
	v_pk_add_f32 v[54:55], v[68:69], v[62:63]
	v_mov_b32_e32 v62, v106
	v_mov_b32_e32 v63, v64
	v_pk_mul_f32 v[66:67], v[44:45], v[44:45]
	v_pk_add_f32 v[54:55], v[62:63], v[54:55]
	v_mov_b32_e32 v64, v107
	v_pk_add_f32 v[54:55], v[64:65], v[54:55]
	v_mov_b32_e32 v62, v132
	v_mov_b32_e32 v63, v66
	v_pk_mul_f32 v[78:79], v[80:81], v[80:81]
	v_pk_add_f32 v[54:55], v[62:63], v[54:55]
	v_mov_b32_e32 v66, v133
	v_pk_add_f32 v[54:55], v[66:67], v[54:55]
	v_mov_b32_e32 v62, v118
	v_mov_b32_e32 v63, v78
	v_pk_add_f32 v[54:55], v[62:63], v[54:55]
	v_mov_b32_e32 v78, v119
	v_pk_add_f32 v[54:55], v[78:79], v[54:55]
	v_mov_b32_e32 v62, v87
	v_mov_b32_e32 v63, v87
	v_mad_u64_u32 v[64:65], s[6:7], v103, s1, v[90:91]
	v_mov_b32_dpp v62, v54 quad_perm:[1,0,3,2] row_mask:0xf bank_mask:0xf
	v_mov_b32_dpp v63, v55 quad_perm:[1,0,3,2] row_mask:0xf bank_mask:0xf
	v_pk_add_f32 v[54:55], v[54:55], v[62:63]
	v_mov_b32_e32 v62, v87
	v_mov_b32_e32 v63, v87
	v_lshl_add_u32 v116, v64, 1, 0
	v_mov_b32_dpp v62, v54 quad_perm:[2,3,0,1] row_mask:0xf bank_mask:0xf
	v_mov_b32_dpp v63, v55 quad_perm:[2,3,0,1] row_mask:0xf bank_mask:0xf
	v_pk_add_f32 v[54:55], v[54:55], v[62:63]
	v_mov_b32_e32 v62, v87
	v_mov_b32_e32 v63, v87
	s_nop 0
	v_mov_b32_dpp v62, v54 row_ror:4 row_mask:0xf bank_mask:0xf
	v_mov_b32_dpp v63, v55 row_ror:4 row_mask:0xf bank_mask:0xf
	v_pk_add_f32 v[54:55], v[54:55], v[62:63]
	v_mov_b32_e32 v62, v87
	v_mov_b32_e32 v63, v87
	s_nop 0
	v_mov_b32_dpp v62, v54 row_ror:8 row_mask:0xf bank_mask:0xf
	v_mov_b32_dpp v63, v55 row_ror:8 row_mask:0xf bank_mask:0xf
	v_pk_add_f32 v[54:55], v[54:55], v[62:63]
	s_nop 0
	v_pk_add_f32 v[54:55], v[54:55], s[0:1] op_sel_hi:[1,0]
	s_nop 0
	v_mul_f32_e32 v62, 0x4b800000, v54
	v_cmp_gt_f32_e32 vcc, s4, v54
	s_nop 1
	v_cndmask_b32_e32 v54, v54, v62, vcc
	v_rsq_f32_e32 v54, v54
	v_mad_u64_u32 v[62:63], s[6:7], v102, s1, v[90:91]
	v_lshl_add_u32 v103, v62, 1, 0
	v_mul_f32_e32 v63, 0x45800000, v54
	v_cndmask_b32_e32 v54, v54, v63, vcc
	v_mul_f32_e32 v54, 0x3db504f3, v54
	v_mul_f32_e32 v63, 0x4b800000, v55
	v_cmp_gt_f32_e32 vcc, s4, v55
	v_pk_mul_f32 v[46:47], v[46:47], v[54:55] op_sel_hi:[1,0]
	s_nop 0
	v_cndmask_b32_e32 v55, v55, v63, vcc
	v_rsq_f32_e32 v63, v55
	v_pk_mul_f32 v[50:51], v[50:51], v[54:55] op_sel_hi:[1,0]
	v_pk_mul_f32 v[52:53], v[52:53], v[54:55] op_sel_hi:[1,0]
	v_pk_mul_f32 v[54:55], v[48:49], v[54:55] op_sel_hi:[1,0]
	v_mul_f32_e32 v48, 0x45800000, v63
	v_cndmask_b32_e32 v48, v63, v48, vcc
	v_mul_f32_e32 v48, 0x3db504f3, v48
	v_pk_mul_f32 v[42:43], v[42:43], v[48:49] op_sel_hi:[1,0]
	v_pk_mul_f32 v[56:57], v[56:57], v[48:49] op_sel_hi:[1,0]
	v_pk_mul_f32 v[44:45], v[44:45], v[48:49] op_sel_hi:[1,0]
	v_pk_mul_f32 v[48:49], v[80:81], v[48:49] op_sel_hi:[1,0]
	v_cvt_pk_bf16_f32 v42, v42, v43
	v_cvt_pk_bf16_f32 v43, v56, v57
	v_cvt_pk_bf16_f32 v44, v44, v45
	v_cvt_pk_bf16_f32 v45, v48, v49
	v_cvt_pk_bf16_f32 v46, v46, v47
	v_cvt_pk_bf16_f32 v47, v50, v51
	v_cvt_pk_bf16_f32 v48, v52, v53
	v_cvt_pk_bf16_f32 v49, v54, v55
	ds_write_b128 v103, v[42:45]
	ds_write_b128 v116, v[46:49]
	s_movk_i32 s5, 0x2000
	s_mov_b64 s[6:7], 0x1000
	v_add_co_u32_e32 v62, vcc, s5, v88
	v_lshl_add_u64 v[46:47], v[88:89], 0, s[6:7]
	s_nop 0
	v_addc_co_u32_e32 v63, vcc, 0, v89, vcc
	s_mov_b64 s[6:7], 0x4000
	global_load_dwordx4 v[42:45], v[62:63], off offset:-4096
	global_load_dwordx4 v[64:67], v[46:47], off offset:16
	v_lshl_add_u64 v[46:47], v[88:89], 0, s[6:7]
	global_load_dwordx4 v[68:71], v[46:47], off offset:16
	s_mov_b64 s[6:7], 0x7000
	v_lshl_add_u64 v[54:55], v[88:89], 0, s[6:7]
	global_load_dwordx4 v[46:49], v[94:95], off
	global_load_dwordx4 v[50:53], v[96:97], off
	global_load_dwordx4 v[72:75], v[54:55], off offset:16
	s_mov_b64 s[6:7], 0xa000
	v_lshl_add_u64 v[54:55], v[88:89], 0, s[6:7]
	global_load_dwordx4 v[76:79], v[54:55], off offset:16
	s_nop 0
	global_load_dwordx4 v[54:57], v[92:93], off
	v_lshlrev_b32_e32 v92, 16, v36
	v_and_b32_e32 v93, 0xffff0000, v36
	v_lshlrev_b32_e32 v80, 16, v37
	v_and_b32_e32 v81, 0xffff0000, v37
	v_lshlrev_b32_e32 v82, 16, v29
	v_and_b32_e32 v83, 0xffff0000, v29
	v_lshlrev_b32_e32 v84, 16, v41
	v_and_b32_e32 v85, 0xffff0000, v41
	v_lshlrev_b32_e32 v90, 16, v33
	v_and_b32_e32 v91, 0xffff0000, v33
	v_lshlrev_b32_e32 v36, 16, v28
	v_and_b32_e32 v37, 0xffff0000, v28
	v_lshlrev_b32_e32 v28, 16, v40
	v_and_b32_e32 v29, 0xffff0000, v40
	v_lshlrev_b32_e32 v40, 16, v32
	v_and_b32_e32 v41, 0xffff0000, v32
	v_lshlrev_b32_e32 v32, 16, v35
	v_and_b32_e32 v33, 0xffff0000, v35
	v_lshlrev_b32_e32 v94, 16, v27
	v_and_b32_e32 v95, 0xffff0000, v27
	v_lshlrev_b32_e32 v96, 16, v39
	v_and_b32_e32 v97, 0xffff0000, v39
	v_lshlrev_b32_e32 v106, 16, v34
	v_and_b32_e32 v107, 0xffff0000, v34
	v_lshlrev_b32_e32 v34, 16, v26
	v_and_b32_e32 v35, 0xffff0000, v26
	v_lshlrev_b32_e32 v26, 16, v38
	v_and_b32_e32 v27, 0xffff0000, v38
	v_lshlrev_b32_e32 v104, 16, v31
	v_and_b32_e32 v105, 0xffff0000, v31
	s_waitcnt vmcnt(7)
; __device__ __forceinline__ float silu_f(float x) { return x * __builtin_amdgcn_rcpf(1.0f + __expf(-x)); }
; __device__ __forceinline__ void gdn_prep_item(LAS unsigned char* lds, int item, int b0, PrepRaw& R, int next_item, const bf16_t* qkv, const float* bg, const float* gconv_w, unsigned char* rec, float* gtarr) {
;     ...
;             for (int j = 0; j < 5; ++j) { const u32x4 v = part < 2 ? R.x[part < 2 ? part : 0][j] : xv[j]; const unsigned vv[4] = {v.x, v.y, v.z, v.w}; float x[8];
; #pragma unroll
;                 for (int e = 0; e < 4; ++e) { x[2 * e] = __uint_as_float(vv[e] << 16); x[2 * e + 1] = __uint_as_float(vv[e] & 0xffff0000u); }
;                 if (j < 4) { const f32x4 wa = *(const f32x4*)(gconv_w + j * CONVCH + col), wb = *(const f32x4*)(gconv_w + j * CONVCH + col + 4);
; #pragma unroll
;                     for (int e = 0; e < 8; ++e) y0[e] += (e < 4 ? wa[e] : wb[e - 4]) * x[e]; }
;                 if (j > 0) { const f32x4 wa = *(const f32x4*)(gconv_w + (j - 1) * CONVCH + col), wb = *(const f32x4*)(gconv_w + (j - 1) * CONVCH + col + 4);
; #pragma unroll
;                     for (int e = 0; e < 8; ++e) y1[e] += (e < 4 ? wa[e] : wb[e - 4]) * x[e]; } }
;             float s0 = 0.f, s1 = 0.f;
; #pragma unroll
;             for (int e = 0; e < 8; ++e) { y0[e] = silu_f(y0[e]); y1[e] = silu_f(y1[e]); s0 += y0[e] * y0[e]; s1 += y1[e] * y1[e]; }
;             if (part < 2) {
;                 s0 = row16_sum(s0); s1 = row16_sum(s1);
	v_pk_fma_f32 v[110:111], v[44:45], v[32:33], 0 op_sel_hi:[1,1,0]
	s_waitcnt vmcnt(6)
	v_pk_fma_f32 v[108:109], v[64:65], v[92:93], 0 op_sel_hi:[1,1,0]
	v_pk_fma_f32 v[38:39], v[66:67], v[80:81], 0 op_sel_hi:[1,1,0]
	s_waitcnt vmcnt(5)
	v_pk_fma_f32 v[108:109], v[68:69], v[36:37], v[108:109]
	v_pk_fma_f32 v[38:39], v[70:71], v[82:83], v[38:39]
	s_waitcnt vmcnt(4)
	v_pk_fma_f32 v[110:111], v[48:49], v[94:95], v[110:111]
	s_waitcnt vmcnt(2)
	v_pk_fma_f32 v[108:109], v[72:73], v[28:29], v[108:109]
	v_pk_fma_f32 v[38:39], v[74:75], v[84:85], v[38:39]
	v_pk_fma_f32 v[110:111], v[52:53], v[96:97], v[110:111]
	s_waitcnt vmcnt(1)
	v_pk_fma_f32 v[40:41], v[76:77], v[40:41], v[108:109]
	v_pk_fma_f32 v[38:39], v[78:79], v[90:91], v[38:39]
	s_waitcnt vmcnt(0)
	v_pk_fma_f32 v[90:91], v[56:57], v[104:105], v[110:111]
	v_mul_f32_e32 v105, 0xbfb8aa3b, v40
	v_mul_f32_e32 v108, 0xbfb8aa3b, v41
	v_mul_f32_e32 v31, 0xbfb8aa3b, v38
	v_mul_f32_e32 v109, 0xbfb8aa3b, v90
	v_exp_f32_e32 v105, v105
	v_exp_f32_e32 v108, v108
	v_mul_f32_e32 v104, 0xbfb8aa3b, v39
	v_exp_f32_e32 v31, v31
	v_exp_f32_e32 v109, v109
	v_mul_f32_e32 v110, 0xbfb8aa3b, v91
	v_exp_f32_e32 v104, v104
	v_pk_fma_f32 v[112:113], v[42:43], v[106:107], 0 op_sel_hi:[1,1,0]
	v_exp_f32_e32 v110, v110
	v_pk_fma_f32 v[112:113], v[46:47], v[34:35], v[112:113]
	v_add_f32_e32 v114, 1.0, v105
	v_add_f32_e32 v115, 1.0, v108
	v_pk_fma_f32 v[112:113], v[50:51], v[26:27], v[112:113]
	v_add_f32_e32 v31, 1.0, v31
	v_add_f32_e32 v117, 1.0, v109
	v_rcp_f32_e32 v108, v114
	v_rcp_f32_e32 v109, v115
	v_lshlrev_b32_e32 v114, 16, v30
	v_and_b32_e32 v115, 0xffff0000, v30
	v_add_f32_e32 v111, 1.0, v104
	v_rcp_f32_e32 v104, v31
	v_pk_fma_f32 v[30:31], v[54:55], v[114:115], v[112:113]
	v_add_f32_e32 v118, 1.0, v110
	v_mul_f32_e32 v112, 0xbfb8aa3b, v30
	v_mul_f32_e32 v113, 0xbfb8aa3b, v31
	v_rcp_f32_e32 v105, v111
	v_rcp_f32_e32 v110, v117
	v_rcp_f32_e32 v111, v118
	v_exp_f32_e32 v112, v112
	v_exp_f32_e32 v113, v113
	v_pk_mul_f32 v[40:41], v[40:41], v[108:109]
	v_pk_mul_f32 v[90:91], v[90:91], v[110:111]
	v_add_f32_e32 v110, 1.0, v112
	v_add_f32_e32 v111, 1.0, v113
	v_lshlrev_b32_e32 v112, 16, v25
	v_and_b32_e32 v113, 0xffff0000, v25
	v_pk_fma_f32 v[66:67], v[66:67], v[112:113], 0 op_sel_hi:[1,1,0]
	v_rcp_f32_e32 v110, v110
	v_pk_fma_f32 v[66:67], v[70:71], v[80:81], v[66:67]
	v_rcp_f32_e32 v111, v111
	v_pk_fma_f32 v[66:67], v[74:75], v[82:83], v[66:67]
	v_pk_mul_f32 v[74:75], v[90:91], v[90:91]
	v_pk_fma_f32 v[66:67], v[78:79], v[84:85], v[66:67]
	v_pk_mul_f32 v[30:31], v[30:31], v[110:111]
	v_mul_f32_e32 v25, 0xbfb8aa3b, v66
	v_exp_f32_e32 v25, v25
	v_mul_f32_e32 v70, 0xbfb8aa3b, v67
	v_exp_f32_e32 v71, v70
	v_pk_mul_f32 v[78:79], v[30:31], v[30:31]
	v_add_f32_e32 v25, 1.0, v25
	v_rcp_f32_e32 v70, v25
	v_add_f32_e32 v25, 1.0, v71
	v_rcp_f32_e32 v71, v25
	v_pk_mul_f32 v[108:109], v[40:41], v[40:41]
	v_pk_mul_f32 v[38:39], v[38:39], v[104:105]
	v_pk_mul_f32 v[66:67], v[66:67], v[70:71]
	v_lshlrev_b32_e32 v70, 16, v24
	v_and_b32_e32 v71, 0xffff0000, v24
	v_pk_fma_f32 v[24:25], v[64:65], v[70:71], 0 op_sel_hi:[1,1,0]
	v_lshlrev_b32_e32 v64, 16, v23
	v_pk_fma_f32 v[24:25], v[68:69], v[92:93], v[24:25]
	v_and_b32_e32 v65, 0xffff0000, v23
	v_pk_fma_f32 v[24:25], v[72:73], v[36:37], v[24:25]
	v_pk_fma_f32 v[44:45], v[44:45], v[64:65], 0 op_sel_hi:[1,1,0]
	v_pk_fma_f32 v[24:25], v[76:77], v[28:29], v[24:25]
	v_pk_fma_f32 v[32:33], v[48:49], v[32:33], v[44:45]
	v_mul_f32_e32 v28, 0xbfb8aa3b, v24
	v_exp_f32_e32 v36, v28
	v_mul_f32_e32 v28, 0xbfb8aa3b, v25
	v_exp_f32_e32 v37, v28
	v_pk_fma_f32 v[32:33], v[52:53], v[94:95], v[32:33]
	v_add_f32_e32 v36, 1.0, v36
	v_pk_fma_f32 v[32:33], v[56:57], v[96:97], v[32:33]
	v_add_f32_e32 v37, 1.0, v37
	v_mul_f32_e32 v23, 0xbfb8aa3b, v32
	v_mul_f32_e32 v44, 0xbfb8aa3b, v33
	v_rcp_f32_e32 v36, v36
	v_rcp_f32_e32 v37, v37
	v_exp_f32_e32 v23, v23
	v_exp_f32_e32 v44, v44
	v_and_b32_e32 v45, 0xffff0000, v22
	v_pk_mul_f32 v[24:25], v[24:25], v[36:37]
	v_add_f32_e32 v23, 1.0, v23
	v_add_f32_e32 v37, 1.0, v44
	v_lshlrev_b32_e32 v44, 16, v22
	v_rcp_f32_e32 v36, v23
	v_pk_fma_f32 v[22:23], v[42:43], v[44:45], 0 op_sel_hi:[1,1,0]
	v_rcp_f32_e32 v37, v37
	v_pk_fma_f32 v[22:23], v[46:47], v[106:107], v[22:23]
	v_mov_b32_e32 v42, v78
	v_pk_fma_f32 v[22:23], v[50:51], v[34:35], v[22:23]
	v_pk_mul_f32 v[32:33], v[32:33], v[36:37]
	v_pk_fma_f32 v[22:23], v[54:55], v[26:27], v[22:23]
	v_pk_mul_f32 v[36:37], v[32:33], v[32:33]
	v_mul_f32_e32 v26, 0xbfb8aa3b, v22
	v_mul_f32_e32 v27, 0xbfb8aa3b, v23
	v_exp_f32_e32 v26, v26
	v_exp_f32_e32 v27, v27
	v_pk_mul_f32 v[34:35], v[24:25], v[24:25]
	v_pk_mul_f32 v[104:105], v[38:39], v[38:39]
	v_add_f32_e32 v26, 1.0, v26
	v_add_f32_e32 v27, 1.0, v27
	v_rcp_f32_e32 v26, v26
	v_rcp_f32_e32 v27, v27
	v_pk_mul_f32 v[28:29], v[66:67], v[66:67]
	v_pk_mul_f32 v[22:23], v[22:23], v[26:27]
	s_nop 0
	v_pk_mul_f32 v[26:27], v[22:23], v[22:23]
	s_nop 0
	v_mov_b32_e32 v43, v26
	v_mov_b32_e32 v26, v79
	v_pk_add_f32 v[26:27], v[42:43], v[26:27]
	v_mov_b32_e32 v42, v74
	v_mov_b32_e32 v43, v36
	v_pk_add_f32 v[26:27], v[42:43], v[26:27]
	v_mov_b32_e32 v36, v75
	v_pk_add_f32 v[26:27], v[36:37], v[26:27]
	v_mov_b32_e32 v36, v108
	v_mov_b32_e32 v37, v34
	v_pk_add_f32 v[26:27], v[36:37], v[26:27]
	v_mov_b32_e32 v34, v109
	v_pk_add_f32 v[26:27], v[34:35], v[26:27]
	v_mov_b32_e32 v34, v104
	v_mov_b32_e32 v35, v28
	v_pk_add_f32 v[26:27], v[34:35], v[26:27]
	v_mov_b32_e32 v28, v105
	v_pk_add_f32 v[26:27], v[28:29], v[26:27]
	v_mov_b32_e32 v28, v87
	v_mov_b32_e32 v29, v87
	s_nop 0
	v_mov_b32_dpp v28, v26 quad_perm:[1,0,3,2] row_mask:0xf bank_mask:0xf
	v_mov_b32_dpp v29, v27 quad_perm:[1,0,3,2] row_mask:0xf bank_mask:0xf
; #define LAS __attribute__((address_space(3)))
; __device__ __forceinline__ unsigned cvt_pk_bf16(float lo, float hi) { const bf16x2_t r = __builtin_convertvector((f32x2){lo, hi}, bf16x2_t); return __builtin_bit_cast(unsigned, r); }
; __device__ __forceinline__ void gdn_prep_item(LAS unsigned char* lds, int item, int b0, PrepRaw& R, int next_item, const bf16_t* qkv, const float* bg, const float* gconv_w, unsigned char* rec, float* gtarr) {
;     ...
;             if (part < 2) {
;                 s0 = row16_sum(s0); s1 = row16_sum(s1);
;                 float sc0 = rsqrtf(s0 + EPS), sc1 = rsqrtf(s1 + EPS); if (part == 0) { sc0 *= 0.08838834764831845f; sc1 *= 0.08838834764831845f; }
; #pragma unroll
;                 for (int e = 0; e < 8; ++e) { y0[e] *= sc0; y1[e] *= sc1; }
;                 LAS unsigned char* img = lds + (part == 0 ? P2_QN : P2_KN);
;                 u32x4 w0, w1; w0.x = cvt_pk_bf16(y0[0], y0[1]); w0.y = cvt_pk_bf16(y0[2], y0[3]); w0.z = cvt_pk_bf16(y0[4], y0[5]); w0.w = cvt_pk_bf16(y0[6], y0[7]);
;                 w1.x = cvt_pk_bf16(y1[0], y1[1]); w1.y = cvt_pk_bf16(y1[2], y1[3]); w1.z = cvt_pk_bf16(y1[4], y1[5]); w1.w = cvt_pk_bf16(y1[6], y1[7]);
;                 *(LAS u32x4*)(img + (i0 * 136 + 8 * cc) * 2) = w0; *(LAS u32x4*)(img + ((i0 + 1) * 136 + 8 * cc) * 2) = w1;
;                 if (part == 1) {
;                     const float f0 = be0 * eg0, f1 = be1 * eg1;
; #pragma unroll
;                     for (int e = 0; e < 8; ++e) *(LAS unsigned*)(lds + P2_KBT + ((8 * cc + e) * 72 + i0) * 2) = cvt_pk_bf16(y0[e] * f0, y1[e] * f1);
;                 }
;             } else {
; #pragma unroll
;                 for (int e = 0; e < 8; ++e) *(LAS unsigned*)(lds + P2_VBT + ((8 * cc + e) * 72 + i0) * 2) = cvt_pk_bf16(y0[e] * be0, y1[e] * be1);
	v_pk_add_f32 v[26:27], v[26:27], v[28:29]
	v_mov_b32_e32 v28, v87
	v_mov_b32_e32 v29, v87
	s_nop 0
	v_mov_b32_dpp v28, v26 quad_perm:[2,3,0,1] row_mask:0xf bank_mask:0xf
	v_mov_b32_dpp v29, v27 quad_perm:[2,3,0,1] row_mask:0xf bank_mask:0xf
	v_pk_add_f32 v[26:27], v[26:27], v[28:29]
	v_mov_b32_e32 v28, v87
	v_mov_b32_e32 v29, v87
	s_nop 0
	v_mov_b32_dpp v28, v26 row_ror:4 row_mask:0xf bank_mask:0xf
	v_mov_b32_dpp v29, v27 row_ror:4 row_mask:0xf bank_mask:0xf
	v_pk_add_f32 v[26:27], v[26:27], v[28:29]
	v_mov_b32_e32 v28, v87
	v_mov_b32_e32 v29, v87
	s_nop 0
	v_mov_b32_dpp v28, v26 row_ror:8 row_mask:0xf bank_mask:0xf
	v_mov_b32_dpp v29, v27 row_ror:8 row_mask:0xf bank_mask:0xf
	v_pk_add_f32 v[26:27], v[26:27], v[28:29]
	s_nop 0
	v_pk_add_f32 v[26:27], v[26:27], s[0:1] op_sel_hi:[1,0]
	s_movk_i32 s0, 0x240
	v_mul_f32_e32 v28, 0x4b800000, v26
	v_cmp_gt_f32_e32 vcc, s4, v26
	s_nop 1
	v_cndmask_b32_e32 v26, v26, v28, vcc
	v_rsq_f32_e32 v26, v26
	s_nop 0
	v_mul_f32_e32 v28, 0x45800000, v26
	v_cndmask_b32_e32 v26, v26, v28, vcc
	v_mul_f32_e32 v28, 0x4b800000, v27
	v_cmp_gt_f32_e32 vcc, s4, v27
	v_pk_mul_f32 v[30:31], v[30:31], v[26:27] op_sel_hi:[1,0]
	s_nop 0
	v_cndmask_b32_e32 v27, v27, v28, vcc
	v_rsq_f32_e32 v27, v27
	s_nop 0
	v_pk_mul_f32 v[34:35], v[90:91], v[26:27] op_sel_hi:[1,0]
	v_pk_mul_f32 v[36:37], v[40:41], v[26:27] op_sel_hi:[1,0]
	v_pk_mul_f32 v[38:39], v[38:39], v[26:27] op_sel_hi:[1,0]
	v_mul_f32_e32 v26, 0x45800000, v27
	v_cndmask_b32_e32 v26, v27, v26, vcc
	v_pk_mul_f32 v[40:41], v[22:23], v[26:27] op_sel_hi:[1,0]
	v_pk_mul_f32 v[32:33], v[32:33], v[26:27] op_sel_hi:[1,0]
	v_pk_mul_f32 v[42:43], v[24:25], v[26:27] op_sel_hi:[1,0]
	v_pk_mul_f32 v[44:45], v[66:67], v[26:27] op_sel_hi:[1,0]
	v_cvt_pk_bf16_f32 v22, v40, v41
	v_cvt_pk_bf16_f32 v23, v32, v33
	v_cvt_pk_bf16_f32 v24, v42, v43
	v_cvt_pk_bf16_f32 v25, v44, v45
	v_cvt_pk_bf16_f32 v26, v30, v31
	v_cvt_pk_bf16_f32 v27, v34, v35
	v_cvt_pk_bf16_f32 v28, v36, v37
	v_cvt_pk_bf16_f32 v29, v38, v39
	ds_write_b128 v103, v[22:25] offset:17408
	ds_write_b128 v116, v[26:29] offset:17408
	s_waitcnt lgkmcnt(4)
	v_pk_mul_f32 v[22:23], v[58:59], v[60:61]
	v_mov_b32_e32 v24, v40
	v_mov_b32_e32 v25, v30
	v_pk_mul_f32 v[24:25], v[22:23], v[24:25]
	v_mov_b32_e32 v30, v41
	v_cvt_pk_bf16_f32 v26, v24, v25
	v_and_b32_e32 v248, 3, v1
	v_lshlrev_b32_e32 v248, 3, v248
	v_xor_b32_e32 v248, v248, v102
	v_mad_u32_u24 v24, v1, s0, v248
	v_lshl_add_u32 v40, v24, 1, 0
	v_pk_mul_f32 v[24:25], v[22:23], v[30:31]
	v_add_u32_e32 v27, 0xd000, v40
	v_cvt_pk_bf16_f32 v24, v24, v25
	ds_write2_b32 v27, v26, v24 offset1:36
	v_mov_b32_e32 v24, v32
	v_mov_b32_e32 v25, v34
	v_pk_mul_f32 v[24:25], v[22:23], v[24:25]
	v_mov_b32_e32 v34, v33
	v_cvt_pk_bf16_f32 v26, v24, v25
	v_pk_mul_f32 v[24:25], v[22:23], v[34:35]
	s_nop 0
	v_cvt_pk_bf16_f32 v24, v24, v25
	ds_write2_b32 v27, v26, v24 offset0:72 offset1:108
	v_mov_b32_e32 v24, v42
	v_mov_b32_e32 v25, v36
	v_pk_mul_f32 v[24:25], v[22:23], v[24:25]
	v_mov_b32_e32 v36, v43
	v_cvt_pk_bf16_f32 v26, v24, v25
	v_pk_mul_f32 v[24:25], v[22:23], v[36:37]
	s_nop 0
	v_cvt_pk_bf16_f32 v24, v24, v25
	ds_write2_b32 v27, v26, v24 offset0:144 offset1:180
	v_mov_b32_e32 v24, v44
	v_mov_b32_e32 v25, v38
	v_mov_b32_e32 v38, v45
	v_pk_mul_f32 v[24:25], v[22:23], v[24:25]
	v_pk_mul_f32 v[22:23], v[22:23], v[38:39]
	v_cvt_pk_bf16_f32 v24, v24, v25
	v_cvt_pk_bf16_f32 v22, v22, v23
	ds_write2_b32 v27, v24, v22 offset0:216 offset1:252
	s_movk_i32 s0, 0x5000
	v_add_co_u32_e32 v26, vcc, s0, v88
	s_mov_b32 s0, 0x8000
	s_nop 0
	v_addc_co_u32_e32 v27, vcc, 0, v89, vcc
	v_add_co_u32_e32 v30, vcc, s0, v88
	global_load_dwordx4 v[22:25], v[62:63], off
	s_nop 0
	v_addc_co_u32_e32 v31, vcc, 0, v89, vcc
	s_mov_b32 s0, 0xb000
	global_load_dwordx4 v[26:29], v[26:27], off
	v_add_co_u32_e32 v34, vcc, s0, v88
	global_load_dwordx4 v[30:33], v[30:31], off
	s_nop 0
	v_addc_co_u32_e32 v35, vcc, 0, v89, vcc
	global_load_dwordx4 v[34:37], v[34:35], off
	s_mov_b64 s[4:5], 0x2000
	s_mov_b64 s[6:7], 0x5000
	s_mov_b64 s[8:9], 0x8000
	s_mov_b64 s[22:23], 0xb000
	v_lshl_add_u64 v[38:39], v[88:89], 0, s[4:5]
	v_lshl_add_u64 v[42:43], v[88:89], 0, s[6:7]
	v_lshl_add_u64 v[46:47], v[88:89], 0, s[8:9]
	v_lshl_add_u64 v[50:51], v[88:89], 0, s[22:23]
	v_add_u32_e32 v80, 0x8800, v40
	global_load_dwordx4 v[38:41], v[38:39], off offset:16
	s_nop 0
	global_load_dwordx4 v[42:45], v[42:43], off offset:16
	s_nop 0
	global_load_dwordx4 v[46:49], v[46:47], off offset:16
	s_nop 0
	global_load_dwordx4 v[50:53], v[50:51], off offset:16
	v_lshlrev_b32_e32 v55, 16, v10
	v_lshlrev_b32_e32 v54, 16, v2
	v_and_b32_e32 v65, 0xffff0000, v10
	v_and_b32_e32 v64, 0xffff0000, v2
	v_lshlrev_b32_e32 v57, 16, v6
	v_and_b32_e32 v67, 0xffff0000, v6
	v_mov_b32_e32 v56, v55
	v_mov_b32_e32 v66, v65
	v_lshlrev_b32_e32 v61, 16, v18
	v_and_b32_e32 v69, 0xffff0000, v18
	v_mov_b32_e32 v60, v57
	v_mov_b32_e32 v68, v67
	v_lshlrev_b32_e32 v63, 16, v14
	v_and_b32_e32 v71, 0xffff0000, v14
	v_mov_b32_e32 v62, v61
	v_mov_b32_e32 v70, v69
	v_lshlrev_b32_e32 v72, 16, v3
	v_lshlrev_b32_e32 v73, 16, v11
	v_lshlrev_b32_e32 v75, 16, v7
	v_mov_b32_e32 v74, v73
	v_lshlrev_b32_e32 v77, 16, v19
	v_mov_b32_e32 v76, v75
	v_lshlrev_b32_e32 v79, 16, v15
	v_mov_b32_e32 v78, v77
	v_and_b32_e32 v11, 0xffff0000, v11
	s_waitcnt vmcnt(7)
	v_pk_fma_f32 v[54:55], v[22:23], v[54:55], 0 op_sel_hi:[0,1,0]
	v_pk_fma_f32 v[22:23], v[22:23], v[64:65], 0 op_sel:[1,0,0] op_sel_hi:[1,1,0]
	v_pk_fma_f32 v[64:65], v[24:25], v[72:73], 0 op_sel_hi:[0,1,0]
	s_waitcnt vmcnt(6)
	v_pk_fma_f32 v[54:55], v[26:27], v[56:57], v[54:55] op_sel_hi:[0,1,1]
	v_pk_fma_f32 v[22:23], v[26:27], v[66:67], v[22:23] op_sel:[1,0,0]
	v_pk_fma_f32 v[26:27], v[28:29], v[74:75], v[64:65] op_sel_hi:[0,1,1]
	s_waitcnt vmcnt(5)
; #define LAS __attribute__((address_space(3)))
; __device__ __forceinline__ unsigned cvt_pk_bf16(float lo, float hi) { const bf16x2_t r = __builtin_convertvector((f32x2){lo, hi}, bf16x2_t); return __builtin_bit_cast(unsigned, r); }
; __device__ __forceinline__ void gdn_prep_item(LAS unsigned char* lds, int item, int b0, PrepRaw& R, int next_item, const bf16_t* qkv, const float* bg, const float* gconv_w, unsigned char* rec, float* gtarr) {
;     ...
;             } else {
; #pragma unroll
;                 for (int e = 0; e < 8; ++e) *(LAS unsigned*)(lds + P2_VBT + ((8 * cc + e) * 72 + i0) * 2) = cvt_pk_bf16(y0[e] * be0, y1[e] * be1);
;             }
;             __builtin_amdgcn_sched_barrier(0);
;         }
;     }
;     if (next_item >= 0) gdn_prep_load(R, next_item, b0, qkv, bg, tid);
;     __syncthreads();
	v_pk_fma_f32 v[54:55], v[30:31], v[60:61], v[54:55] op_sel_hi:[0,1,1]
	v_pk_fma_f32 v[22:23], v[30:31], v[68:69], v[22:23] op_sel:[1,0,0]
	v_pk_fma_f32 v[26:27], v[32:33], v[76:77], v[26:27] op_sel_hi:[0,1,1]
	s_waitcnt vmcnt(4)
	v_pk_fma_f32 v[30:31], v[34:35], v[62:63], v[54:55] op_sel_hi:[0,1,1]
	v_pk_fma_f32 v[22:23], v[34:35], v[70:71], v[22:23] op_sel:[1,0,0]
	v_mul_f32_e32 v2, 0xbfb8aa3b, v31
	v_mul_f32_e32 v6, 0xbfb8aa3b, v30
	v_mul_f32_e32 v10, 0xbfb8aa3b, v23
	v_mul_f32_e32 v14, 0xbfb8aa3b, v22
	v_exp_f32_e32 v2, v2
	v_exp_f32_e32 v6, v6
	v_exp_f32_e32 v10, v10
	v_exp_f32_e32 v14, v14
	v_add_f32_e32 v2, 1.0, v2
	v_add_f32_e32 v6, 1.0, v6
	v_add_f32_e32 v10, 1.0, v10
	v_add_f32_e32 v14, 1.0, v14
	v_rcp_f32_e32 v35, v2
	v_rcp_f32_e32 v34, v6
	v_rcp_f32_e32 v55, v10
	v_rcp_f32_e32 v54, v14
	v_pk_fma_f32 v[26:27], v[36:37], v[78:79], v[26:27] op_sel_hi:[0,1,1]
	v_mul_f32_e32 v18, 0xbfb8aa3b, v27
	v_exp_f32_e32 v2, v18
	v_mul_f32_e32 v24, 0xbfb8aa3b, v26
	v_pk_mul_f32 v[30:31], v[30:31], v[34:35]
	v_pk_mul_f32 v[22:23], v[22:23], v[54:55]
	v_exp_f32_e32 v6, v24
	v_pk_mul_f32 v[30:31], v[58:59], v[30:31]
	v_pk_mul_f32 v[22:23], v[58:59], v[22:23]
	v_cvt_pk_bf16_f32 v10, v30, v31
	v_cvt_pk_bf16_f32 v14, v22, v23
	ds_write2_b32 v80, v10, v14 offset1:36
	v_add_f32_e32 v2, 1.0, v2
	v_and_b32_e32 v10, 0xffff0000, v3
	v_mov_b32_e32 v14, v25
	v_rcp_f32_e32 v23, v2
	v_and_b32_e32 v3, 0xffff0000, v7
	v_mov_b32_e32 v2, v11
	v_pk_fma_f32 v[10:11], v[14:15], v[10:11], 0 op_sel_hi:[0,1,0]
	v_mov_b32_e32 v18, v29
	v_add_f32_e32 v22, 1.0, v6
	v_and_b32_e32 v7, 0xffff0000, v19
	v_mov_b32_e32 v6, v3
	v_pk_fma_f32 v[2:3], v[18:19], v[2:3], v[10:11] op_sel_hi:[0,1,1]
	v_mov_b32_e32 v10, v33
	v_and_b32_e32 v15, 0xffff0000, v15
	v_mov_b32_e32 v14, v7
	v_pk_fma_f32 v[2:3], v[10:11], v[6:7], v[2:3] op_sel_hi:[0,1,1]
	v_mov_b32_e32 v6, v37
	v_pk_fma_f32 v[2:3], v[6:7], v[14:15], v[2:3] op_sel_hi:[0,1,1]
	v_mul_f32_e32 v6, 0xbfb8aa3b, v3
	v_exp_f32_e32 v6, v6
	v_mul_f32_e32 v7, 0xbfb8aa3b, v2
	v_exp_f32_e32 v10, v7
	v_rcp_f32_e32 v22, v22
	v_add_f32_e32 v6, 1.0, v6
	v_rcp_f32_e32 v7, v6
	v_add_f32_e32 v6, 1.0, v10
	v_rcp_f32_e32 v6, v6
	v_pk_mul_f32 v[10:11], v[26:27], v[22:23]
	v_lshlrev_b32_e32 v15, 16, v16
	v_pk_mul_f32 v[10:11], v[58:59], v[10:11]
	v_pk_mul_f32 v[2:3], v[2:3], v[6:7]
	v_lshlrev_b32_e32 v7, 16, v8
	v_pk_mul_f32 v[2:3], v[58:59], v[2:3]
	v_cvt_pk_bf16_f32 v18, v10, v11
	v_cvt_pk_bf16_f32 v19, v2, v3
	v_lshlrev_b32_e32 v3, 16, v12
	v_lshlrev_b32_e32 v2, 16, v4
	v_mov_b32_e32 v6, v3
	s_waitcnt vmcnt(3)
	v_pk_fma_f32 v[2:3], v[38:39], v[2:3], 0 op_sel_hi:[0,1,0]
	v_lshlrev_b32_e32 v11, 16, v20
	v_mov_b32_e32 v10, v7
	s_waitcnt vmcnt(2)
	v_pk_fma_f32 v[2:3], v[42:43], v[6:7], v[2:3] op_sel_hi:[0,1,1]
	v_mov_b32_e32 v14, v11
	s_waitcnt vmcnt(1)
	v_pk_fma_f32 v[2:3], v[46:47], v[10:11], v[2:3] op_sel_hi:[0,1,1]
	s_waitcnt vmcnt(0)
	v_pk_fma_f32 v[2:3], v[50:51], v[14:15], v[2:3] op_sel_hi:[0,1,1]
	v_mul_f32_e32 v6, 0xbfb8aa3b, v3
	v_exp_f32_e32 v6, v6
	v_mul_f32_e32 v7, 0xbfb8aa3b, v2
	v_exp_f32_e32 v10, v7
	v_and_b32_e32 v11, 0xffff0000, v12
	v_add_f32_e32 v6, 1.0, v6
	v_rcp_f32_e32 v7, v6
	v_add_f32_e32 v6, 1.0, v10
	v_and_b32_e32 v10, 0xffff0000, v4
	v_and_b32_e32 v15, 0xffff0000, v8
	v_mov_b32_e32 v14, v11
	v_pk_fma_f32 v[10:11], v[38:39], v[10:11], 0 op_sel:[1,0,0] op_sel_hi:[1,1,0]
	ds_write2_b32 v80, v18, v19 offset0:72 offset1:108
	v_and_b32_e32 v19, 0xffff0000, v20
	v_mov_b32_e32 v18, v15
	v_pk_fma_f32 v[10:11], v[42:43], v[14:15], v[10:11] op_sel:[1,0,0]
	v_and_b32_e32 v23, 0xffff0000, v16
	v_mov_b32_e32 v22, v19
	v_pk_fma_f32 v[10:11], v[46:47], v[18:19], v[10:11] op_sel:[1,0,0]
	v_rcp_f32_e32 v6, v6
	v_pk_fma_f32 v[10:11], v[50:51], v[22:23], v[10:11] op_sel:[1,0,0]
	v_pk_mul_f32 v[2:3], v[2:3], v[6:7]
	v_mul_f32_e32 v4, 0xbfb8aa3b, v11
	v_exp_f32_e32 v4, v4
	v_mul_f32_e32 v8, 0xbfb8aa3b, v10
	v_exp_f32_e32 v8, v8
	v_pk_mul_f32 v[2:3], v[58:59], v[2:3]
	v_add_f32_e32 v4, 1.0, v4
	v_rcp_f32_e32 v15, v4
	v_add_f32_e32 v4, 1.0, v8
	v_rcp_f32_e32 v14, v4
	v_cvt_pk_bf16_f32 v4, v2, v3
	v_lshlrev_b32_e32 v7, 16, v9
	v_pk_mul_f32 v[2:3], v[10:11], v[14:15]
	s_nop 0
	v_pk_mul_f32 v[2:3], v[58:59], v[2:3]
	v_lshlrev_b32_e32 v11, 16, v21
	v_cvt_pk_bf16_f32 v8, v2, v3
	v_lshlrev_b32_e32 v2, 16, v5
	v_lshlrev_b32_e32 v3, 16, v13
	v_mov_b32_e32 v6, v3
	v_pk_fma_f32 v[2:3], v[40:41], v[2:3], 0 op_sel_hi:[0,1,0]
	v_mov_b32_e32 v10, v7
	v_pk_fma_f32 v[2:3], v[44:45], v[6:7], v[2:3] op_sel_hi:[0,1,1]
	v_lshlrev_b32_e32 v15, 16, v17
	v_mov_b32_e32 v14, v11
	v_pk_fma_f32 v[2:3], v[48:49], v[10:11], v[2:3] op_sel_hi:[0,1,1]
	v_pk_fma_f32 v[2:3], v[52:53], v[14:15], v[2:3] op_sel_hi:[0,1,1]
	v_mul_f32_e32 v6, 0xbfb8aa3b, v3
	v_exp_f32_e32 v6, v6
	v_mul_f32_e32 v7, 0xbfb8aa3b, v2
	v_exp_f32_e32 v10, v7
	ds_write2_b32 v80, v4, v8 offset0:144 offset1:180
	v_add_f32_e32 v4, 1.0, v6
	v_rcp_f32_e32 v7, v4
	v_add_f32_e32 v14, 1.0, v10
	v_and_b32_e32 v11, 0xffff0000, v13
	v_and_b32_e32 v10, 0xffff0000, v5
	v_mov_b32_e32 v6, v41
	v_and_b32_e32 v5, 0xffff0000, v9
	v_mov_b32_e32 v4, v11
	v_pk_fma_f32 v[10:11], v[6:7], v[10:11], 0 op_sel_hi:[0,1,0]
	v_mov_b32_e32 v6, v45
	v_and_b32_e32 v9, 0xffff0000, v21
	v_mov_b32_e32 v8, v5
	v_pk_fma_f32 v[4:5], v[6:7], v[4:5], v[10:11] op_sel_hi:[0,1,1]
	v_mov_b32_e32 v6, v49
	v_and_b32_e32 v13, 0xffff0000, v17
	v_mov_b32_e32 v12, v9
	v_pk_fma_f32 v[4:5], v[6:7], v[8:9], v[4:5] op_sel_hi:[0,1,1]
	v_mov_b32_e32 v6, v53
	v_pk_fma_f32 v[4:5], v[6:7], v[12:13], v[4:5] op_sel_hi:[0,1,1]
	v_mul_f32_e32 v6, 0xbfb8aa3b, v5
	v_exp_f32_e32 v8, v6
	v_mul_f32_e32 v6, 0xbfb8aa3b, v4
	v_exp_f32_e32 v10, v6
	v_rcp_f32_e32 v6, v14
	v_add_f32_e32 v8, 1.0, v8
	v_rcp_f32_e32 v9, v8
	v_add_f32_e32 v8, 1.0, v10
	v_rcp_f32_e32 v8, v8
	v_pk_mul_f32 v[2:3], v[2:3], v[6:7]
	s_nop 0
	v_pk_mul_f32 v[2:3], v[58:59], v[2:3]
	s_nop 0
	v_cvt_pk_bf16_f32 v6, v2, v3
	v_pk_mul_f32 v[2:3], v[4:5], v[8:9]
	s_nop 0
	v_pk_mul_f32 v[2:3], v[58:59], v[2:3]
	s_nop 0
	v_cvt_pk_bf16_f32 v2, v2, v3
	ds_write2_b32 v80, v6, v2 offset0:216 offset1:252
	s_ashr_i32 s22, s20, 1
	s_lshl_b32 s4, s22, 4
	v_or_b32_e32 v11, s4, v1
	v_mul_lo_u32 v2, v11, s1
	v_lshlrev_b32_e32 v10, 3, v86
	v_add_lshl_u32 v2, v2, v10, 1
	v_add_u32_e32 v6, 0, v2
	s_waitcnt lgkmcnt(0)
	s_barrier
; #define LAS __attribute__((address_space(3)))
; #define MFMA16(a, b, c) __builtin_amdgcn_mfma_f32_16x16x32_bf16(a, b, c, 0, 0, 0)
; __device__ __forceinline__ void gdn_prep_item(LAS unsigned char* lds, int item, int b0, PrepRaw& R, int next_item, const bf16_t* qkv, const float* bg, const float* gconv_w, unsigned char* rec, float* gtarr) {
;     ...
;     {
;         const f32x4 z4 = (f32x4){0.f, 0.f, 0.f, 0.f};
;         {
;             const int ta = wave >> 1;
; #pragma unroll
;             for (int q = 0; q < 2; ++q) { const int tb = 2 * (wave & 1) + q; f32x4 acc = z4;
; #pragma unroll
;                 for (int s = 0; s < 4; ++s) { const bf16x8 af = *(const LAS bf16x8*)(lds + P2_KN + ((16 * ta + l15) * 136 + 32 * s + 8 * g) * 2), bfr = *(const LAS bf16x8*)(lds + P2_KN + ((16 * tb + l15) * 136 + 32 * s + 8 * g) * 2);
;                     acc = MFMA16(af, bfr, acc); }
;                 const int j = 16 * tb + l15; const float Gj = Gs[j];
; #pragma unroll
;                 for (int r = 0; r < 4; ++r) { const int i = 16 * ta + 4 * g + r; Lf[i * LS + j] = (i > j) ? Bs[i] * acc[r] * __expf(Gs[i] - Gj) : 0.f; } }
;         }
;         {
;             const int rt = wave >> 1, s = wave & 1; f32x4 a0 = z4, a1 = z4;
; #pragma unroll
;             for (int ks = 0; ks < 4; ++ks) { const bf16x8 qf = *(const LAS bf16x8*)(lds + P2_QN + ((16 * rt + l15) * 136 + 32 * ks + 8 * g) * 2);
;                 const bf16x8 k0 = *(const LAS bf16x8*)(lds + P2_KN + ((32 * s + l15) * 136 + 32 * ks + 8 * g) * 2), k1 = *(const LAS bf16x8*)(lds + P2_KN + ((32 * s + 16 + l15) * 136 + 32 * ks + 8 * g) * 2);
;                 a0 = MFMA16(k0, qf, a0); a1 = MFMA16(k1, qf, a1); }
;             const int i = 16 * rt + l15; const float Gi = Gs[i];
; #pragma unroll
;             for (int r = 0; r < 4; ++r) { const int ia = 32 * s + 4 * g + r, ib = ia + 16;
;                 a0[r] = (i >= ia) ? a0[r] * __expf(Gi - Gs[ia]) : 0.f; a1[r] = (i >= ib) ? a1[r] * __expf(Gi - Gs[ib]) : 0.f; }
;             *(bf16x8*)(rec + REC_AM + ((rt * 2 + s) * 64 + lane) * 16) = pack8(a0, a1);
;         }
	s_and_b32 s23, s20, 1
	s_lshl_b32 s0, s23, 5
	v_or_b32_e32 v222, s0, v1
	v_lshl_or_b32 v223, v86, 2, s4
	v_lshl_or_b32 v230, v86, 2, s0
	v_lshlrev_b32_e32 v227, 2, v223
	v_add_u32_e32 v227, 0x1d000, v227
	v_lshlrev_b32_e32 v228, 2, v222
	v_add_u32_e32 v228, 0x1d000, v228
	v_lshlrev_b32_e32 v229, 2, v11
	v_add_u32_e32 v229, 0x1d000, v229
	v_sub_u32_e32 v225, v11, v230
	v_lshlrev_b32_e32 v230, 2, v230
	v_add_u32_e32 v230, 0x1d000, v230
	s_movk_i32 s0, 0x88
	v_mad_u32_u24 v231, v222, s0, v10
	v_lshlrev_b32_e32 v231, 1, v231
	ds_read_b128 v[200:203], v227
	ds_read_b128 v[204:207], v227 offset:256
	ds_read_b32 v216, v228
	ds_read_b32 v217, v228 offset:64
	ds_read_b32 v218, v229
	ds_read_b128 v[208:211], v230
	ds_read_b128 v[212:215], v230 offset:64
	ds_read_b128 v[136:139], v6 offset:17408
	ds_read_b128 v[152:155], v231 offset:17408
	ds_read_b128 v[168:171], v231 offset:21760
	ds_read_b128 v[184:187], v6
	ds_read_b128 v[140:143], v6 offset:17472
	ds_read_b128 v[156:159], v231 offset:17472
	ds_read_b128 v[172:175], v231 offset:21824
	ds_read_b128 v[188:191], v6 offset:64
	ds_read_b128 v[144:147], v6 offset:17536
	ds_read_b128 v[160:163], v231 offset:17536
	ds_read_b128 v[176:179], v231 offset:21888
	ds_read_b128 v[192:195], v6 offset:128
	ds_read_b128 v[148:151], v6 offset:17600
	ds_read_b128 v[164:167], v231 offset:17600
	ds_read_b128 v[180:183], v231 offset:21952
	ds_read_b128 v[196:199], v6 offset:192
	v_sub_u32_e32 v224, v223, v222
	s_movk_i32 s0, 0x110
	v_mad_u32_u24 v226, v223, s0, 0
	v_lshl_add_u32 v226, v222, 2, v226
	v_add_u32_e32 v226, 0x11800, v226
	s_waitcnt lgkmcnt(14)
	v_sub_f32_e32 v80, v200, v216
	v_sub_f32_e32 v81, v201, v216
	v_sub_f32_e32 v82, v202, v216
	v_sub_f32_e32 v83, v203, v216
	v_mul_f32_e32 v80, 0x3fb8aa3b, v80
	v_mul_f32_e32 v81, 0x3fb8aa3b, v81
	v_mul_f32_e32 v82, 0x3fb8aa3b, v82
	v_mul_f32_e32 v83, 0x3fb8aa3b, v83
	v_exp_f32_e32 v80, v80
	v_exp_f32_e32 v81, v81
	v_exp_f32_e32 v82, v82
	v_exp_f32_e32 v83, v83
	v_sub_f32_e32 v84, v200, v217
	v_sub_f32_e32 v85, v201, v217
	v_sub_f32_e32 v86, v202, v217
	v_sub_f32_e32 v87, v203, v217
	v_mul_f32_e32 v84, 0x3fb8aa3b, v84
	v_mul_f32_e32 v85, 0x3fb8aa3b, v85
	v_mul_f32_e32 v86, 0x3fb8aa3b, v86
	v_mul_f32_e32 v87, 0x3fb8aa3b, v87
	v_exp_f32_e32 v84, v84
	v_exp_f32_e32 v85, v85
	v_exp_f32_e32 v86, v86
	v_exp_f32_e32 v87, v87
	v_sub_f32_e32 v88, v218, v208
	v_sub_f32_e32 v89, v218, v209
	v_sub_f32_e32 v90, v218, v210
	v_sub_f32_e32 v91, v218, v211
	v_mul_f32_e32 v88, 0x3fb8aa3b, v88
	v_mul_f32_e32 v89, 0x3fb8aa3b, v89
	v_mul_f32_e32 v90, 0x3fb8aa3b, v90
	v_mul_f32_e32 v91, 0x3fb8aa3b, v91
	v_exp_f32_e32 v88, v88
	v_exp_f32_e32 v89, v89
	v_exp_f32_e32 v90, v90
	v_exp_f32_e32 v91, v91
	v_sub_f32_e32 v92, v218, v212
	v_sub_f32_e32 v93, v218, v213
	v_sub_f32_e32 v94, v218, v214
	v_sub_f32_e32 v95, v218, v215
	v_mul_f32_e32 v92, 0x3fb8aa3b, v92
	v_mul_f32_e32 v93, 0x3fb8aa3b, v93
	v_mul_f32_e32 v94, 0x3fb8aa3b, v94
	v_mul_f32_e32 v95, 0x3fb8aa3b, v95
	v_exp_f32_e32 v92, v92
	v_exp_f32_e32 v93, v93
	v_exp_f32_e32 v94, v94
	v_exp_f32_e32 v95, v95
	s_waitcnt lgkmcnt(12)
	v_mfma_f32_16x16x32_bf16 v[64:67], v[136:139], v[152:155], 0
	v_mfma_f32_16x16x32_bf16 v[68:71], v[136:139], v[168:171], 0
	v_mfma_f32_16x16x32_bf16 v[72:75], v[152:155], v[184:187], 0
	v_mfma_f32_16x16x32_bf16 v[76:79], v[168:171], v[184:187], 0
	s_waitcnt lgkmcnt(8)
	v_mfma_f32_16x16x32_bf16 v[64:67], v[140:143], v[156:159], v[64:67]
	v_mfma_f32_16x16x32_bf16 v[68:71], v[140:143], v[172:175], v[68:71]
	v_mfma_f32_16x16x32_bf16 v[72:75], v[156:159], v[188:191], v[72:75]
	v_mfma_f32_16x16x32_bf16 v[76:79], v[172:175], v[188:191], v[76:79]
	s_waitcnt lgkmcnt(4)
	v_mfma_f32_16x16x32_bf16 v[64:67], v[144:147], v[160:163], v[64:67]
	v_mfma_f32_16x16x32_bf16 v[68:71], v[144:147], v[176:179], v[68:71]
	v_mfma_f32_16x16x32_bf16 v[72:75], v[160:163], v[192:195], v[72:75]
	v_mfma_f32_16x16x32_bf16 v[76:79], v[176:179], v[192:195], v[76:79]
	s_waitcnt lgkmcnt(0)
	v_mfma_f32_16x16x32_bf16 v[64:67], v[148:151], v[164:167], v[64:67]
	v_mfma_f32_16x16x32_bf16 v[68:71], v[148:151], v[180:183], v[68:71]
	v_mfma_f32_16x16x32_bf16 v[72:75], v[164:167], v[196:199], v[72:75]
	v_mfma_f32_16x16x32_bf16 v[76:79], v[180:183], v[196:199], v[76:79]
	v_cmp_lt_i32_e64 s[36:37], 0, v224
	v_cmp_lt_i32_e64 s[38:39], -1, v224
	v_cmp_lt_i32_e64 s[40:41], -2, v224
	v_cmp_lt_i32_e64 s[42:43], -3, v224
	s_nop 3
	v_mul_f32_e32 v119, v64, v204
	v_mul_f32_e32 v120, v65, v205
	v_mul_f32_e32 v121, v66, v206
	v_mul_f32_e32 v122, v67, v207
	v_mul_f32_e32 v119, v119, v80
	v_mul_f32_e32 v120, v120, v81
	v_mul_f32_e32 v121, v121, v82
	v_mul_f32_e32 v122, v122, v83
	v_cndmask_b32_e64 v119, 0, v119, s[36:37]
	v_cndmask_b32_e64 v120, 0, v120, s[38:39]
	v_cndmask_b32_e64 v121, 0, v121, s[40:41]
	v_cndmask_b32_e64 v122, 0, v122, s[42:43]
	ds_write_b32 v226, v119
	ds_write_b32 v226, v120 offset:272
	ds_write_b32 v226, v121 offset:544
	ds_write_b32 v226, v122 offset:816
	v_cmp_lt_i32_e64 s[36:37], 16, v224
	v_cmp_lt_i32_e64 s[38:39], 15, v224
	v_cmp_lt_i32_e64 s[40:41], 14, v224
	v_cmp_lt_i32_e64 s[42:43], 13, v224
	v_mul_f32_e32 v119, v68, v204
	v_mul_f32_e32 v120, v69, v205
	v_mul_f32_e32 v121, v70, v206
	v_mul_f32_e32 v122, v71, v207
	v_mul_f32_e32 v119, v119, v84
	v_mul_f32_e32 v120, v120, v85
	v_mul_f32_e32 v121, v121, v86
	v_mul_f32_e32 v122, v122, v87
	v_cndmask_b32_e64 v119, 0, v119, s[36:37]
	v_cndmask_b32_e64 v120, 0, v120, s[38:39]
	v_cndmask_b32_e64 v121, 0, v121, s[40:41]
	v_cndmask_b32_e64 v122, 0, v122, s[42:43]
	ds_write_b32 v226, v119 offset:64
	ds_write_b32 v226, v120 offset:336
	ds_write_b32 v226, v121 offset:608
	ds_write_b32 v226, v122 offset:880
; #define LAS __attribute__((address_space(3)))
; __device__ __forceinline__ void gdn_prep_item(LAS unsigned char* lds, int item, int b0, PrepRaw& R, int next_item, const bf16_t* qkv, const float* bg, const float* gconv_w, unsigned char* rec, float* gtarr) {
;     ...
;             const int i = 16 * rt + l15; const float Gi = Gs[i];
; #pragma unroll
;             for (int r = 0; r < 4; ++r) { const int ia = 32 * s + 4 * g + r, ib = ia + 16;
;                 a0[r] = (i >= ia) ? a0[r] * __expf(Gi - Gs[ia]) : 0.f; a1[r] = (i >= ib) ? a1[r] * __expf(Gi - Gs[ib]) : 0.f; }
;             *(bf16x8*)(rec + REC_AM + ((rt * 2 + s) * 64 + lane) * 16) = pack8(a0, a1);
;         }
;     }
;     __syncthreads();
;     if (tid < 64) { const int blk = tid >> 4, cidx = tid & 15; float x[16];
; #pragma unroll
;         for (int i = 0; i < 16; ++i) x[i] = (i == cidx) ? 1.f : 0.f;
; #pragma unroll
;         for (int i = 1; i < 16; ++i) { float a = 0.f; const LAS float* row = Lf + (16 * blk + i) * LS + 16 * blk;
; #pragma unroll
;             for (int j4 = 0; j4 < (i + 3) / 4; ++j4) { const f32x4 l4 = *(const LAS f32x4*)(row + 4 * j4);
; #pragma unroll
;                 for (int e = 0; e < 4; ++e) if (4 * j4 + e < i) a += l4[e] * x[4 * j4 + e]; }
;             if (i > cidx) x[i] = -a; }
; #pragma unroll
;         for (int i = 0; i < 16; ++i) Tf[(16 * blk + i) * LS + 16 * blk + cidx] = x[i];
;     }
	v_cmp_le_i32_e64 s[36:37], 0, v225
	v_cmp_le_i32_e64 s[38:39], 1, v225
	v_cmp_le_i32_e64 s[40:41], 2, v225
	v_cmp_le_i32_e64 s[42:43], 3, v225
	v_mul_f32_e32 v72, v72, v88
	v_mul_f32_e32 v73, v73, v89
	v_mul_f32_e32 v74, v74, v90
	v_mul_f32_e32 v75, v75, v91
	v_cndmask_b32_e64 v72, 0, v72, s[36:37]
	v_cndmask_b32_e64 v73, 0, v73, s[38:39]
	v_cndmask_b32_e64 v74, 0, v74, s[40:41]
	v_cndmask_b32_e64 v75, 0, v75, s[42:43]
	v_cvt_pk_bf16_f32 v232, v72, v73
	v_cvt_pk_bf16_f32 v233, v74, v75
	v_cmp_le_i32_e64 s[36:37], 16, v225
	v_cmp_le_i32_e64 s[38:39], 17, v225
	v_cmp_le_i32_e64 s[40:41], 18, v225
	v_cmp_le_i32_e64 s[42:43], 19, v225
	v_mul_f32_e32 v76, v76, v92
	v_mul_f32_e32 v77, v77, v93
	v_mul_f32_e32 v78, v78, v94
	v_mul_f32_e32 v79, v79, v95
	v_cndmask_b32_e64 v76, 0, v76, s[36:37]
	v_cndmask_b32_e64 v77, 0, v77, s[38:39]
	v_cndmask_b32_e64 v78, 0, v78, s[40:41]
	v_cndmask_b32_e64 v79, 0, v79, s[42:43]
	v_cvt_pk_bf16_f32 v234, v76, v77
	v_cvt_pk_bf16_f32 v235, v78, v79
	s_add_i32 s0, s18, 0xfffff9c8
	s_cmpk_lt_i32 s18, 0x638
	s_cselect_b32 s0, s18, s0
	s_cselect_b32 s1, s19, 0
	v_readlane_b32 s36, v245, 19
	v_readlane_b32 s48, v245, 31
	v_readlane_b32 s49, v245, 32
	s_mul_i32 s1, s1, 0x12000
	s_mul_hi_u32 s6, s0, 0x12000
	s_cselect_b32 s5, s64, s49
	s_cselect_b32 s4, s33, s48
	s_add_i32 s6, s6, s1
	s_mul_i32 s0, s0, 0x12000
	v_lshlrev_b32_e32 v7, 4, v101
	s_add_u32 s4, s4, s0
	s_waitcnt lgkmcnt(0)
	v_lshl_or_b32 v2, s20, 10, v7
	s_addc_u32 s5, s5, s6
	v_ashrrev_i32_e32 v3, 31, v2
	v_lshl_add_u64 v[2:3], s[4:5], 0, v[2:3]
	v_add_co_u32_e32 v2, vcc, 0xc000, v2
	v_readlane_b32 s37, v245, 20
	s_nop 0
	v_addc_co_u32_e32 v3, vcc, 0, v3, vcc
	v_cmp_gt_i32_e32 vcc, 64, v99
	v_readlane_b32 s38, v245, 21
	v_readlane_b32 s39, v245, 22
	v_readlane_b32 s40, v245, 23
	v_readlane_b32 s41, v245, 24
	v_readlane_b32 s42, v245, 25
	v_readlane_b32 s43, v245, 26
	v_readlane_b32 s44, v245, 27
	v_readlane_b32 s45, v245, 28
	v_readlane_b32 s46, v245, 29
	v_readlane_b32 s47, v245, 30
	v_readlane_b32 s50, v245, 33
	v_readlane_b32 s51, v245, 34
	global_store_dwordx4 v[2:3], v[232:235], off sc0 sc1
	s_barrier
	s_and_saveexec_b64 s[6:7], vcc
	s_cbranch_execz .LBB0_689
	v_and_b32_e32 v61, -16, v99
	v_lshlrev_b32_e32 v96, 8, v61
	v_lshl_add_u32 v96, v61, 4, v96
	v_lshl_add_u32 v96, v61, 2, v96
	v_add_u32_e32 v97, 0x11800, v96
	v_lshl_add_u32 v119, v1, 2, v96
	v_add_u32_e32 v119, 0x15c00, v119
	v_cmp_eq_u32_e32 vcc, 0, v1
	s_nop 1
	v_cndmask_b32_e64 v248, 0, 1.0, vcc
	ds_read_b128 v[136:139], v97 offset:272
	ds_read_b128 v[140:143], v97 offset:544
	ds_read_b128 v[144:147], v97 offset:816
	ds_read_b128 v[148:151], v97 offset:1088
	ds_read_b128 v[152:155], v97 offset:1360
	ds_read_b128 v[156:159], v97 offset:1376
	ds_read_b128 v[160:163], v97 offset:1632
	ds_read_b128 v[164:167], v97 offset:1648
	ds_read_b128 v[168:171], v97 offset:1904
	ds_read_b128 v[172:175], v97 offset:1920
	ds_read_b128 v[176:179], v97 offset:2176
	ds_read_b128 v[180:183], v97 offset:2192
	ds_read_b128 v[184:187], v97 offset:2448
	ds_read_b128 v[188:191], v97 offset:2464
	s_waitcnt lgkmcnt(13)
	v_cmp_eq_u32_e64 s[0:1], 1, v1
	v_cmp_gt_u32_e32 vcc, 1, v1
	v_fma_f32 v132, v248, v136, 0
	s_nop 1
	v_cndmask_b32_e64 v249, 0, 1.0, s[0:1]
	v_cndmask_b32_e64 v249, v249, -v132, vcc
	ds_read_b128 v[192:195], v97 offset:2480
	s_waitcnt lgkmcnt(13)
	v_cmp_eq_u32_e64 s[0:1], 2, v1
	v_cmp_gt_u32_e32 vcc, 2, v1
	v_fma_f32 v133, v248, v140, 0
	v_fmac_f32_e32 v133, v141, v249
	s_nop 1
	v_cndmask_b32_e64 v250, 0, 1.0, s[0:1]
	v_cndmask_b32_e64 v250, v250, -v133, vcc
	ds_read_b128 v[196:199], v97 offset:2720
	s_waitcnt lgkmcnt(13)
	v_cmp_eq_u32_e64 s[0:1], 3, v1
	v_cmp_gt_u32_e32 vcc, 3, v1
	v_fma_f32 v132, v248, v144, 0
	v_fmac_f32_e32 v132, v145, v249
	v_fmac_f32_e32 v132, v146, v250
	v_cndmask_b32_e64 v251, 0, 1.0, s[0:1]
	v_cndmask_b32_e64 v251, v251, -v132, vcc
	ds_read_b128 v[200:203], v97 offset:2736
	s_waitcnt lgkmcnt(13)
	v_cmp_eq_u32_e64 s[0:1], 4, v1
	v_cmp_gt_u32_e32 vcc, 4, v1
	v_fma_f32 v133, v248, v148, 0
	v_fmac_f32_e32 v133, v149, v249
	v_fmac_f32_e32 v133, v150, v250
	v_fmac_f32_e32 v133, v151, v251
	v_cndmask_b32_e64 v252, 0, 1.0, s[0:1]
	v_cndmask_b32_e64 v252, v252, -v133, vcc
	ds_read_b128 v[204:207], v97 offset:2752
	s_waitcnt lgkmcnt(13)
	v_cmp_eq_u32_e64 s[0:1], 5, v1
	v_cmp_gt_u32_e32 vcc, 5, v1
	v_fma_f32 v132, v248, v152, 0
	v_fmac_f32_e32 v132, v153, v249
	v_fmac_f32_e32 v132, v154, v250
	v_fmac_f32_e32 v132, v155, v251
	ds_read_b128 v[208:211], v97 offset:2992
	s_waitcnt lgkmcnt(13)
	v_fmac_f32_e32 v132, v156, v252
	v_cndmask_b32_e64 v253, 0, 1.0, s[0:1]
	v_cndmask_b32_e64 v253, v253, -v132, vcc
	ds_read_b128 v[212:215], v97 offset:3008
	s_waitcnt lgkmcnt(13)
	v_cmp_eq_u32_e64 s[0:1], 6, v1
	v_cmp_gt_u32_e32 vcc, 6, v1
	v_fma_f32 v133, v248, v160, 0
	v_fmac_f32_e32 v133, v161, v249
	v_fmac_f32_e32 v133, v162, v250
	v_fmac_f32_e32 v133, v163, v251
	ds_read_b128 v[216:219], v97 offset:3024
	s_waitcnt lgkmcnt(13)
	v_fmac_f32_e32 v133, v164, v252
	v_fmac_f32_e32 v133, v165, v253
	v_cndmask_b32_e64 v254, 0, 1.0, s[0:1]
	v_cndmask_b32_e64 v254, v254, -v133, vcc
	ds_read_b128 v[64:67], v97 offset:3264
	s_waitcnt lgkmcnt(13)
	v_cmp_eq_u32_e64 s[0:1], 7, v1
	v_cmp_gt_u32_e32 vcc, 7, v1
	v_fma_f32 v132, v248, v168, 0
	v_fmac_f32_e32 v132, v169, v249
	v_fmac_f32_e32 v132, v170, v250
	v_fmac_f32_e32 v132, v171, v251
	ds_read_b128 v[68:71], v97 offset:3280
	s_waitcnt lgkmcnt(13)
	v_fmac_f32_e32 v132, v172, v252
	v_fmac_f32_e32 v132, v173, v253
	v_fmac_f32_e32 v132, v174, v254
	v_cndmask_b32_e64 v255, 0, 1.0, s[0:1]
	v_cndmask_b32_e64 v255, v255, -v132, vcc
	ds_read_b128 v[72:75], v97 offset:3296
	s_waitcnt lgkmcnt(13)
; #define LAS __attribute__((address_space(3)))
; __device__ __forceinline__ void gdn_prep_item(LAS unsigned char* lds, int item, int b0, PrepRaw& R, int next_item, const bf16_t* qkv, const float* bg, const float* gconv_w, unsigned char* rec, float* gtarr) {
;     ...
;     if (tid < 64) { const int blk = tid >> 4, cidx = tid & 15; float x[16];
; #pragma unroll
;         for (int i = 0; i < 16; ++i) x[i] = (i == cidx) ? 1.f : 0.f;
; #pragma unroll
;         for (int i = 1; i < 16; ++i) { float a = 0.f; const LAS float* row = Lf + (16 * blk + i) * LS + 16 * blk;
; #pragma unroll
;             for (int j4 = 0; j4 < (i + 3) / 4; ++j4) { const f32x4 l4 = *(const LAS f32x4*)(row + 4 * j4);
; #pragma unroll
;                 for (int e = 0; e < 4; ++e) if (4 * j4 + e < i) a += l4[e] * x[4 * j4 + e]; }
;             if (i > cidx) x[i] = -a; }
; #pragma unroll
;         for (int i = 0; i < 16; ++i) Tf[(16 * blk + i) * LS + 16 * blk + cidx] = x[i];
;     }
	v_cmp_eq_u32_e64 s[0:1], 8, v1
	v_cmp_gt_u32_e32 vcc, 8, v1
	v_fma_f32 v133, v248, v176, 0
	v_fmac_f32_e32 v133, v177, v249
	v_fmac_f32_e32 v133, v178, v250
	v_fmac_f32_e32 v133, v179, v251
	ds_read_b128 v[76:79], v97 offset:3536
	s_waitcnt lgkmcnt(13)
	v_fmac_f32_e32 v133, v180, v252
	v_fmac_f32_e32 v133, v181, v253
	v_fmac_f32_e32 v133, v182, v254
	v_fmac_f32_e32 v133, v183, v255
	v_cndmask_b32_e64 v240, 0, 1.0, s[0:1]
	v_cndmask_b32_e64 v240, v240, -v133, vcc
	ds_read_b128 v[80:83], v97 offset:3552
	s_waitcnt lgkmcnt(13)
	v_cmp_eq_u32_e64 s[0:1], 9, v1
	v_cmp_gt_u32_e32 vcc, 9, v1
	v_fma_f32 v132, v248, v184, 0
	v_fmac_f32_e32 v132, v185, v249
	v_fmac_f32_e32 v132, v186, v250
	v_fmac_f32_e32 v132, v187, v251
	ds_read_b128 v[84:87], v97 offset:3568
	s_waitcnt lgkmcnt(13)
	v_fmac_f32_e32 v132, v188, v252
	v_fmac_f32_e32 v132, v189, v253
	v_fmac_f32_e32 v132, v190, v254
	v_fmac_f32_e32 v132, v191, v255
	ds_read_b128 v[88:91], v97 offset:3584
	s_waitcnt lgkmcnt(13)
	v_fmac_f32_e32 v132, v192, v240
	v_cndmask_b32_e64 v241, 0, 1.0, s[0:1]
	v_cndmask_b32_e64 v241, v241, -v132, vcc
	ds_read_b128 v[92:95], v97 offset:3808
	s_waitcnt lgkmcnt(13)
	v_cmp_eq_u32_e64 s[0:1], 10, v1
	v_cmp_gt_u32_e32 vcc, 10, v1
	v_fma_f32 v133, v248, v196, 0
	v_fmac_f32_e32 v133, v197, v249
	v_fmac_f32_e32 v133, v198, v250
	v_fmac_f32_e32 v133, v199, v251
	ds_read_b128 v[120:123], v97 offset:3824
	s_waitcnt lgkmcnt(13)
	v_fmac_f32_e32 v133, v200, v252
	v_fmac_f32_e32 v133, v201, v253
	v_fmac_f32_e32 v133, v202, v254
	v_fmac_f32_e32 v133, v203, v255
	ds_read_b128 v[124:127], v97 offset:3840
	s_waitcnt lgkmcnt(13)
	v_fmac_f32_e32 v133, v204, v240
	v_fmac_f32_e32 v133, v205, v241
	v_cndmask_b32_e64 v242, 0, 1.0, s[0:1]
	v_cndmask_b32_e64 v242, v242, -v133, vcc
	ds_read_b128 v[128:131], v97 offset:3856
	s_waitcnt lgkmcnt(13)
	v_cmp_eq_u32_e64 s[0:1], 11, v1
	v_cmp_gt_u32_e32 vcc, 11, v1
	v_fma_f32 v132, v248, v208, 0
	v_fmac_f32_e32 v132, v209, v249
	v_fmac_f32_e32 v132, v210, v250
	v_fmac_f32_e32 v132, v211, v251
	ds_read_b128 v[222:225], v97 offset:4080
	s_waitcnt lgkmcnt(13)
	v_fmac_f32_e32 v132, v212, v252
	v_fmac_f32_e32 v132, v213, v253
	v_fmac_f32_e32 v132, v214, v254
	v_fmac_f32_e32 v132, v215, v255
	ds_read_b128 v[226:229], v97 offset:4096
	s_waitcnt lgkmcnt(13)
	v_fmac_f32_e32 v132, v216, v240
	v_fmac_f32_e32 v132, v217, v241
	v_fmac_f32_e32 v132, v218, v242
	v_cndmask_b32_e64 v243, 0, 1.0, s[0:1]
	v_cndmask_b32_e64 v243, v243, -v132, vcc
	ds_read_b128 v[230:233], v97 offset:4112
	s_waitcnt lgkmcnt(13)
	v_cmp_eq_u32_e64 s[0:1], 12, v1
	v_cmp_gt_u32_e32 vcc, 12, v1
	v_fma_f32 v133, v248, v64, 0
	v_fmac_f32_e32 v133, v65, v249
	v_fmac_f32_e32 v133, v66, v250
	v_fmac_f32_e32 v133, v67, v251
	ds_read_b128 v[234:237], v97 offset:4128
	s_waitcnt lgkmcnt(13)
	v_fmac_f32_e32 v133, v68, v252
	v_fmac_f32_e32 v133, v69, v253
	v_fmac_f32_e32 v133, v70, v254
	v_fmac_f32_e32 v133, v71, v255
	s_waitcnt lgkmcnt(12)
	v_fmac_f32_e32 v133, v72, v240
	v_fmac_f32_e32 v133, v73, v241
	v_fmac_f32_e32 v133, v74, v242
	v_fmac_f32_e32 v133, v75, v243
	v_cndmask_b32_e64 v102, 0, 1.0, s[0:1]
	v_cndmask_b32_e64 v102, v102, -v133, vcc
	s_waitcnt lgkmcnt(11)
	v_cmp_eq_u32_e64 s[0:1], 13, v1
	v_cmp_gt_u32_e32 vcc, 13, v1
	v_fma_f32 v132, v248, v76, 0
	v_fmac_f32_e32 v132, v77, v249
	v_fmac_f32_e32 v132, v78, v250
	v_fmac_f32_e32 v132, v79, v251
	s_waitcnt lgkmcnt(10)
	v_fmac_f32_e32 v132, v80, v252
	v_fmac_f32_e32 v132, v81, v253
	v_fmac_f32_e32 v132, v82, v254
	v_fmac_f32_e32 v132, v83, v255
	s_waitcnt lgkmcnt(9)
	v_fmac_f32_e32 v132, v84, v240
	v_fmac_f32_e32 v132, v85, v241
	v_fmac_f32_e32 v132, v86, v242
	v_fmac_f32_e32 v132, v87, v243
	s_waitcnt lgkmcnt(8)
	v_fmac_f32_e32 v132, v88, v102
	v_cndmask_b32_e64 v103, 0, 1.0, s[0:1]
	v_cndmask_b32_e64 v103, v103, -v132, vcc
	s_waitcnt lgkmcnt(7)
	v_cmp_eq_u32_e64 s[0:1], 14, v1
	v_cmp_gt_u32_e32 vcc, 14, v1
	v_fma_f32 v133, v248, v92, 0
	v_fmac_f32_e32 v133, v93, v249
	v_fmac_f32_e32 v133, v94, v250
	v_fmac_f32_e32 v133, v95, v251
	s_waitcnt lgkmcnt(6)
	v_fmac_f32_e32 v133, v120, v252
	v_fmac_f32_e32 v133, v121, v253
	v_fmac_f32_e32 v133, v122, v254
	v_fmac_f32_e32 v133, v123, v255
	s_waitcnt lgkmcnt(5)
	v_fmac_f32_e32 v133, v124, v240
	v_fmac_f32_e32 v133, v125, v241
	v_fmac_f32_e32 v133, v126, v242
	v_fmac_f32_e32 v133, v127, v243
	s_waitcnt lgkmcnt(4)
	v_fmac_f32_e32 v133, v128, v102
	v_fmac_f32_e32 v133, v129, v103
	v_cndmask_b32_e64 v104, 0, 1.0, s[0:1]
	v_cndmask_b32_e64 v104, v104, -v133, vcc
	s_waitcnt lgkmcnt(3)
	v_cmp_eq_u32_e64 s[0:1], 15, v1
	v_cmp_gt_u32_e32 vcc, 15, v1
	v_fma_f32 v132, v248, v222, 0
	v_fmac_f32_e32 v132, v223, v249
	v_fmac_f32_e32 v132, v224, v250
	v_fmac_f32_e32 v132, v225, v251
	s_waitcnt lgkmcnt(2)
	v_fmac_f32_e32 v132, v226, v252
	v_fmac_f32_e32 v132, v227, v253
	v_fmac_f32_e32 v132, v228, v254
	v_fmac_f32_e32 v132, v229, v255
	s_waitcnt lgkmcnt(1)
	v_fmac_f32_e32 v132, v230, v240
	v_fmac_f32_e32 v132, v231, v241
	v_fmac_f32_e32 v132, v232, v242
	v_fmac_f32_e32 v132, v233, v243
	s_waitcnt lgkmcnt(0)
	v_fmac_f32_e32 v132, v234, v102
	v_fmac_f32_e32 v132, v235, v103
	v_fmac_f32_e32 v132, v236, v104
	v_cndmask_b32_e64 v105, 0, 1.0, s[0:1]
	v_cndmask_b32_e64 v105, v105, -v132, vcc
	ds_write_b32 v119, v248
	ds_write_b32 v119, v249 offset:272
	ds_write_b32 v119, v250 offset:544
	ds_write_b32 v119, v251 offset:816
	ds_write_b32 v119, v252 offset:1088
	ds_write_b32 v119, v253 offset:1360
	ds_write_b32 v119, v254 offset:1632
	ds_write_b32 v119, v255 offset:1904
	ds_write_b32 v119, v240 offset:2176
	ds_write_b32 v119, v241 offset:2448
	ds_write_b32 v119, v242 offset:2720
	ds_write_b32 v119, v243 offset:2992
	ds_write_b32 v119, v102 offset:3264
	ds_write_b32 v119, v103 offset:3536
	ds_write_b32 v119, v104 offset:3808
	ds_write_b32 v119, v105 offset:4080

; #define LAS __attribute__((address_space(3)))
; __device__ __forceinline__ unsigned cvt_pk_bf16(float lo, float hi) { const bf16x2_t r = __builtin_convertvector((f32x2){lo, hi}, bf16x2_t); return __builtin_bit_cast(unsigned, r); }
; #define MFMA16(a, b, c) __builtin_amdgcn_mfma_f32_16x16x32_bf16(a, b, c, 0, 0, 0)
; __device__ __forceinline__ void gdn_prep_item(LAS unsigned char* lds, int item, int b0, PrepRaw& R, int next_item, const bf16_t* qkv, const float* bg, const float* gconv_w, unsigned char* rec, float* gtarr) {
;     ...
;     {
;         const f32x4 z4 = (f32x4){0.f, 0.f, 0.f, 0.f};
; #pragma unroll
;         for (int rt = 0; rt < 4; ++rt) { f32x4 acc = z4;
; #pragma unroll
;             for (int s = 0; s < 2; ++s) { const bf16x8 tf = *(const LAS bf16x8*)(lds + P2_TB + ((16 * rt + l15) * 72 + 32 * s + 8 * g) * 2), vf = *(const LAS bf16x8*)(lds + P2_VBT + ((16 * wave + l15) * 72 + 32 * s + 8 * g) * 2);
;                 acc = MFMA16(tf, vf, acc); }
;             u32x2 w; w.x = cvt_pk_bf16(acc[0], acc[1]); w.y = cvt_pk_bf16(acc[2], acc[3]);
;             *(u32x2*)(rec + REC_U + ((rt * 8 + wave) * 64 + lane) * 8) = w; }
;         const int rt = wave >> 1;
; #pragma unroll
;         for (int q = 0; q < 2; ++q) { const int s2 = 2 * (wave & 1) + q; f32x4 a0 = z4, a1 = z4;
; #pragma unroll
;             for (int s = 0; s < 2; ++s) { const bf16x8 tf = *(const LAS bf16x8*)(lds + P2_TB + ((16 * rt + l15) * 72 + 32 * s + 8 * g) * 2);
;                 const bf16x8 k0 = *(const LAS bf16x8*)(lds + P2_KBT + ((32 * s2 + l15) * 72 + 32 * s + 8 * g) * 2), k1 = *(const LAS bf16x8*)(lds + P2_KBT + ((32 * s2 + 16 + l15) * 72 + 32 * s + 8 * g) * 2);
;                 a0 = MFMA16(k0, tf, a0); a1 = MFMA16(k1, tf, a1); }
;             *(bf16x8*)(rec + REC_WN + ((rt * 4 + s2) * 64 + lane) * 16) = pack8(-a0, -a1); }
;     }
.LBB0_700:
	s_or_b64 exec, exec, s[0:1]
	s_movk_i32 s8, 0x48
	s_add_u32 s0, s4, 0xe000
	s_addc_u32 s1, s5, 0
	v_mad_u32_u24 v2, v1, s8, v10
	s_add_i32 s9, 0, 0x1a000
	v_lshl_add_u32 v38, v2, 1, s9
	s_waitcnt lgkmcnt(0)
	s_barrier
	ds_read_b128 v[2:5], v38
	v_lshl_or_b32 v9, s20, 4, v1
	s_and_b32 s98, s20, 1
	s_lshl_b32 s98, s98, 4
	v_and_or_b32 v248, v1, 8, s98
	v_xor_b32_e32 v248, v248, v10
	v_mad_u32_u24 v12, v9, s8, v248
	v_lshl_add_u32 v9, v12, 1, 0
	ds_read_b128 v[12:15], v38 offset:64
	ds_read_b128 v[16:19], v9 offset:34816
	ds_read_b128 v[20:23], v9 offset:34880
	s_waitcnt lgkmcnt(1)
	v_mfma_f32_16x16x32_bf16 v[2:5], v[2:5], v[16:19], 0
	ds_read_b128 v[24:27], v38 offset:2304
	v_or_b32_e32 v9, 0x480, v10
	v_and_b32_e32 v249, 8, v1
	v_xor_b32_e32 v249, v249, v10
	v_xor_b32_e32 v250, 16, v249
	v_or_b32_e32 v250, 0x480, v250
	v_lshl_or_b32 v7, s22, 12, v7
	s_waitcnt lgkmcnt(1)
	v_mfma_f32_16x16x32_bf16 v[2:5], v[12:15], v[20:23], v[2:5]
	ds_read_b128 v[12:15], v38 offset:2368
	s_nop 6
	v_cvt_pk_bf16_f32 v28, v2, v3
	v_lshlrev_b32_e32 v2, 3, v101
	v_lshl_or_b32 v36, s20, 9, v2
	v_ashrrev_i32_e32 v37, 31, v36
	v_cvt_pk_bf16_f32 v29, v4, v5
	s_waitcnt lgkmcnt(1)
	v_mfma_f32_16x16x32_bf16 v[2:5], v[24:27], v[16:19], 0
	v_lshl_add_u64 v[24:25], s[0:1], 0, v[36:37]
	global_store_dwordx2 v[24:25], v[28:29], off sc0 sc1
	ds_read_b128 v[24:27], v38 offset:4608
	s_waitcnt lgkmcnt(1)
	v_mfma_f32_16x16x32_bf16 v[2:5], v[12:15], v[20:23], v[2:5]
	ds_read_b128 v[12:15], v38 offset:4672
	v_add_u32_e32 v30, 0x1000, v36
	v_ashrrev_i32_e32 v31, 31, v30
	v_add_u32_e32 v34, 0x2000, v36
	v_ashrrev_i32_e32 v35, 31, v34
	s_nop 2
	v_cvt_pk_bf16_f32 v28, v2, v3
	v_cvt_pk_bf16_f32 v29, v4, v5
	s_waitcnt lgkmcnt(1)
	v_mfma_f32_16x16x32_bf16 v[2:5], v[24:27], v[16:19], 0
	v_lshl_add_u64 v[24:25], s[0:1], 0, v[30:31]
	global_store_dwordx2 v[24:25], v[28:29], off sc0 sc1
	ds_read_b128 v[24:27], v38 offset:6912
	s_waitcnt lgkmcnt(1)
	v_mfma_f32_16x16x32_bf16 v[2:5], v[12:15], v[20:23], v[2:5]
	v_lshl_add_u64 v[34:35], s[0:1], 0, v[34:35]
	v_add_u32_e32 v36, 0x3000, v36
	s_nop 5
	v_cvt_pk_bf16_f32 v32, v2, v3
	v_cvt_pk_bf16_f32 v33, v4, v5
	ds_read_b128 v[2:5], v38 offset:6976
	s_waitcnt lgkmcnt(1)
	v_mfma_f32_16x16x32_bf16 v[12:15], v[24:27], v[16:19], 0
	v_mad_u64_u32 v[16:17], s[6:7], v11, s8, v[10:11]
	v_lshl_or_b32 v24, s23, 6, v1
	v_lshl_add_u32 v11, v16, 1, s9
	v_mad_u32_u24 v16, v24, s8, v249
	v_lshl_add_u32 v37, v16, 1, 0
	v_mad_u32_u24 v28, v24, s8, v250
	ds_read_b128 v[16:19], v37 offset:53248
	ds_read_b128 v[24:27], v11
	v_lshl_add_u32 v39, v28, 1, 0
	ds_read_b128 v[28:31], v39 offset:53248
	s_waitcnt lgkmcnt(3)
	v_mfma_f32_16x16x32_bf16 v[2:5], v[2:5], v[20:23], v[12:15]
	s_nop 2
	ds_read_b128 v[12:15], v11 offset:64
	ds_read_b128 v[20:23], v37 offset:53312
	global_store_dwordx2 v[34:35], v[32:33], off sc0 sc1
	ds_read_b128 v[32:35], v39 offset:53312
	s_waitcnt lgkmcnt(4)
	v_mfma_f32_16x16x32_bf16 v[16:19], v[16:19], v[24:27], 0
	v_ashrrev_i32_e32 v37, 31, v36
	v_cvt_pk_bf16_f32 v38, v2, v3
	v_cvt_pk_bf16_f32 v39, v4, v5
	s_waitcnt lgkmcnt(3)
	v_mfma_f32_16x16x32_bf16 v[28:31], v[28:31], v[24:27], 0
	s_movk_i32 s6, 0x88
	s_waitcnt lgkmcnt(1)
	v_mfma_f32_16x16x32_bf16 v[2:5], v[20:23], v[12:15], v[16:19]
	s_nop 2
	v_lshl_add_u64 v[16:17], s[0:1], 0, v[36:37]
	global_store_dwordx2 v[16:17], v[38:39], off sc0 sc1
	s_waitcnt lgkmcnt(0)
	v_mfma_f32_16x16x32_bf16 v[16:19], v[32:35], v[12:15], v[28:31]
	s_lshl_b32 s0, s23, 1
	s_or_b32 s0, s0, 1
	v_xor_b32_e32 v11, 0x80000000, v5
	v_xor_b32_e32 v28, 0x80000000, v2
	v_xor_b32_e32 v22, 0x80000000, v4
	s_nop 2
	v_xor_b32_e32 v31, 0x80000000, v19
	v_lshl_or_b32 v19, s0, 5, v1
	v_mad_u32_u24 v2, v19, s8, v249
	v_mad_u32_u24 v9, v19, s8, v250
	v_lshl_add_u32 v10, v2, 1, 0
	v_lshl_add_u32 v9, v9, 1, 0
	v_xor_b32_e32 v23, 0x80000000, v3
	ds_read_b128 v[2:5], v10 offset:53248
	ds_read_b128 v[32:35], v10 offset:53312
	v_xor_b32_e32 v40, 0x80000000, v18
	ds_read_b128 v[18:21], v9 offset:53248
	ds_read_b128 v[36:39], v9 offset:53312
	v_xor_b32_e32 v17, 0x80000000, v17
	v_xor_b32_e32 v16, 0x80000000, v16
	s_waitcnt lgkmcnt(3)
	v_mfma_f32_16x16x32_bf16 v[2:5], v[2:5], v[24:27], 0
	v_cvt_pk_bf16_f32 v30, v16, v17
	v_lshl_or_b32 v10, s23, 11, v7
	v_cvt_pk_bf16_f32 v29, v22, v11
	s_waitcnt lgkmcnt(1)
	v_mfma_f32_16x16x32_bf16 v[16:19], v[18:21], v[24:27], 0
	v_ashrrev_i32_e32 v11, 31, v10
	v_cvt_pk_bf16_f32 v28, v28, v23
	v_cvt_pk_bf16_f32 v31, v40, v31
	v_lshl_add_u64 v[10:11], s[4:5], 0, v[10:11]
	v_mfma_f32_16x16x32_bf16 v[2:5], v[32:35], v[12:15], v[2:5]
	global_store_dwordx4 v[10:11], v[28:31], off sc0 sc1
	v_mov_b32_e32 v20, 0x990
	v_mov_b32_e32 v21, 0xa18
	s_waitcnt lgkmcnt(0)
	v_mfma_f32_16x16x32_bf16 v[10:13], v[36:39], v[12:15], v[16:19]
	v_and_b32_e32 v15, 12, v8
	s_nop 1
	v_xor_b32_e32 v5, 0x80000000, v5
	v_xor_b32_e32 v4, 0x80000000, v4
	v_xor_b32_e32 v3, 0x80000000, v3
	v_xor_b32_e32 v2, 0x80000000, v2
	s_nop 0
	v_xor_b32_e32 v11, 0x80000000, v11
	v_xor_b32_e32 v10, 0x80000000, v10
	v_cvt_pk_bf16_f32 v2, v2, v3
	v_cvt_pk_bf16_f32 v3, v4, v5
	v_cvt_pk_bf16_f32 v4, v10, v11
	v_lshl_or_b32 v10, s0, 10, v7
	v_xor_b32_e32 v9, 0x80000000, v13
	v_xor_b32_e32 v12, 0x80000000, v12
	v_ashrrev_i32_e32 v11, 31, v10
	v_cvt_pk_bf16_f32 v5, v12, v9
	v_lshl_add_u64 v[10:11], s[4:5], 0, v[10:11]
	global_store_dwordx4 v[10:11], v[2:5], off sc0 sc1
	v_lshrrev_b32_e32 v11, 1, v99
	v_and_b32_e32 v10, 0x60, v11
	v_ashrrev_i32_e32 v2, 4, v99
	v_and_or_b32 v2, v2, -16, v1
	v_lshl_add_u32 v7, v2, 2, s21
	v_mad_u64_u32 v[2:3], s[8:9], v2, s6, v[10:11]
	v_add_u32_e32 v3, v2, v15
	v_lshl_add_u32 v3, v3, 1, 0
	ds_read_b64 v[4:5], v3
	v_add_u32_e32 v18, 0x200, v99
	v_or_b32_e32 v16, 16, v15
	v_ashrrev_i32_e32 v3, 4, v18
	v_add_u32_e32 v2, v2, v16
	v_and_or_b32 v17, v3, -16, v1
	v_lshl_add_u32 v2, v2, 1, 0
	v_lshl_add_u32 v3, v17, 2, s21
	ds_read_b32 v8, v7
	ds_read_b64 v[12:13], v2
	ds_read_b32 v14, v3
	s_waitcnt lgkmcnt(3)
; #define LAS __attribute__((address_space(3)))
; __device__ __forceinline__ float bf2f(bf16_t b) { return __uint_as_float(((unsigned)b) << 16); }
; __device__ __forceinline__ void gdn_prep_item(LAS unsigned char* lds, int item, int b0, PrepRaw& R, int next_item, const bf16_t* qkv, const float* bg, const float* gconv_w, unsigned char* rec, float* gtarr) {
;     ...
;     for (int q = 0; q < 2; ++q) { const int task = tid + q * NTHREADS, fragi = task >> 6, ln = task & 63, lg = ln >> 4, l = ln & 15;
;         const int rt = fragi >> 2, s2 = fragi & 3, i = 16 * rt + l; const float e = EG[i];
;         const u32x2 lo = *(const LAS u32x2*)(lds + P2_QN + (i * 136 + 32 * s2 + 4 * lg) * 2), hi = *(const LAS u32x2*)(lds + P2_QN + (i * 136 + 32 * s2 + 16 + 4 * lg) * 2);
;         const unsigned vv[4] = {lo.x, lo.y, hi.x, hi.y}; u32x4 w; unsigned ww[4];
; #pragma unroll
;         for (int k2 = 0; k2 < 4; ++k2) ww[k2] = cvt_pk_bf16(__uint_as_float(vv[k2] << 16) * e, __uint_as_float(vv[k2] & 0xffff0000u) * e);
;         w.x = ww[0]; w.y = ww[1]; w.z = ww[2]; w.w = ww[3];
;         *(u32x4*)(rec + REC_QD + (fragi * 64 + ln) * 16) = w; }
; #pragma unroll
;     for (int q = 0; q < 2; ++q) { const int task = tid + q * NTHREADS, fragi = task >> 6, ln = task & 63, lg = ln >> 4, l = ln & 15;
;         const int dt = fragi >> 1, s = fragi & 1, dk = 16 * dt + l; float v[8];
; #pragma unroll
;         for (int j = 0; j < 8; ++j) { const int i = 32 * s + 4 * lg + (j & 3) + 16 * (j >> 2); v[j] = bf2f(*(const LAS bf16_t*)(lds + P2_KN + (i * 136 + dk) * 2)) * DKs[i]; }
;         u32x4 w; w.x = cvt_pk_bf16(v[0], v[1]); w.y = cvt_pk_bf16(v[2], v[3]); w.z = cvt_pk_bf16(v[4], v[5]); w.w = cvt_pk_bf16(v[6], v[7]);
;         *(u32x4*)(rec + REC_KDT + (fragi * 64 + ln) * 16) = w; }
;     __syncthreads();
; __device__ __forceinline__ void gdn_all(LAS unsigned char* lds, const XcdBarrier& xbar, const int G, const int bx, unsigned char* ws, float* out, const bf16_t* qkv, const float* bg, const float* gconv_w, ...
;     ...
;         asm volatile("s_waitcnt vmcnt(0)" ::: "memory"); __syncthreads();
;         if (threadIdx.x == 0) { __builtin_amdgcn_fence(__ATOMIC_RELEASE, "agent"); asm volatile("s_waitcnt vmcnt(0)" ::: "memory"); __hip_atomic_fetch_add(late_cnt, 1u, __ATOMIC_RELAXED, __HIP_MEMORY_SCOPE_AGENT); }
	v_lshlrev_b32_e32 v2, 16, v4
	v_and_b32_e32 v3, 0xffff0000, v4
	v_lshlrev_b32_e32 v4, 16, v5
	v_and_b32_e32 v5, 0xffff0000, v5
	s_waitcnt lgkmcnt(2)
	v_pk_mul_f32 v[2:3], v[8:9], v[2:3] op_sel_hi:[0,1]
	v_pk_mul_f32 v[4:5], v[8:9], v[4:5] op_sel_hi:[0,1]
	s_add_u32 s0, s4, 0x4000
	v_cvt_pk_bf16_f32 v2, v2, v3
	v_cvt_pk_bf16_f32 v3, v4, v5
	s_waitcnt lgkmcnt(1)
	v_lshlrev_b32_e32 v4, 16, v12
	v_and_b32_e32 v5, 0xffff0000, v12
	v_lshlrev_b32_e32 v12, 16, v13
	v_and_b32_e32 v13, 0xffff0000, v13
	s_addc_u32 s1, s5, 0
	v_pk_mul_f32 v[4:5], v[8:9], v[4:5] op_sel_hi:[0,1]
	v_pk_mul_f32 v[8:9], v[8:9], v[12:13] op_sel_hi:[0,1]
	v_ashrrev_i32_e32 v7, 31, v6
	v_cvt_pk_bf16_f32 v4, v4, v5
	v_cvt_pk_bf16_f32 v5, v8, v9
	v_lshl_add_u64 v[8:9], s[0:1], 0, v[6:7]
	global_store_dwordx4 v[8:9], v[2:5], off sc0 sc1
	v_mov_b32_e32 v19, 0x908
	v_mov_b32_e32 v13, 0x110
	v_mad_u64_u32 v[2:3], s[8:9], v17, s6, v[10:11]
	v_add_u32_e32 v3, v2, v15
	v_lshl_add_u32 v3, v3, 1, 0
	ds_read_b64 v[4:5], v3
	v_add_u32_e32 v2, v2, v16
	v_and_or_b32 v10, v11, 32, v15
	v_and_or_b32 v11, v98, -16, v1
	v_lshl_add_u32 v2, v2, 1, 0
	v_mad_u32_u24 v3, v10, s6, v11
	v_lshl_add_u32 v3, v3, 1, 0
	ds_read_b64 v[8:9], v2
	ds_read_u16 v12, v3 offset:17408
	s_waitcnt lgkmcnt(2)
	v_lshlrev_b32_e32 v2, 16, v4
	v_and_b32_e32 v3, 0xffff0000, v4
	v_lshlrev_b32_e32 v4, 16, v5
	v_and_b32_e32 v5, 0xffff0000, v5
	v_pk_mul_f32 v[2:3], v[14:15], v[2:3] op_sel_hi:[0,1]
	v_pk_mul_f32 v[4:5], v[14:15], v[4:5] op_sel_hi:[0,1]
	v_cvt_pk_bf16_f32 v2, v2, v3
	v_cvt_pk_bf16_f32 v3, v4, v5
	s_waitcnt lgkmcnt(1)
	v_lshlrev_b32_e32 v4, 16, v8
	v_and_b32_e32 v5, 0xffff0000, v8
	v_lshlrev_b32_e32 v8, 16, v9
	v_and_b32_e32 v9, 0xffff0000, v9
	v_lshlrev_b32_e32 v16, 4, v18
	v_pk_mul_f32 v[4:5], v[14:15], v[4:5] op_sel_hi:[0,1]
	v_pk_mul_f32 v[8:9], v[14:15], v[8:9] op_sel_hi:[0,1]
	v_ashrrev_i32_e32 v17, 31, v16
	v_cvt_pk_bf16_f32 v4, v4, v5
	v_cvt_pk_bf16_f32 v5, v8, v9
	v_lshl_add_u64 v[8:9], s[0:1], 0, v[16:17]
	v_mov_b32_e32 v14, 0x198
	global_store_dwordx4 v[8:9], v[2:5], off sc0 sc1
	v_mad_u32_u24 v22, v10, s6, s6
	v_mad_u32_u24 v24, v10, s6, v14
	v_lshl_add_u32 v2, v10, 2, 0
	v_mov_b32_e32 v15, 0x880
	v_mad_u32_u24 v26, v10, s6, v19
	v_mad_u32_u24 v27, v10, s6, v20
	v_ashrrev_i32_e32 v18, 3, v18
	v_add_u32_e32 v8, 0x1d300, v2
	v_add_u32_e32 v2, v22, v11
	v_mad_u32_u24 v23, v10, s6, v13
	v_add_u32_e32 v14, v24, v11
	v_mad_u32_u24 v25, v10, s6, v15
	v_add_u32_e32 v19, v26, v11
	v_add_u32_e32 v20, v27, v11
	v_mad_u32_u24 v28, v10, s6, v21
	v_and_or_b32 v1, v18, -16, v1
	v_lshl_add_u32 v9, v2, 1, 0
	v_add_u32_e32 v13, v23, v11
	v_lshl_add_u32 v14, v14, 1, 0
	v_add_u32_e32 v15, v25, v11
	v_lshl_add_u32 v19, v19, 1, 0
	v_lshl_add_u32 v20, v20, 1, 0
	v_add_u32_e32 v11, v28, v11
	v_mad_u32_u24 v10, v10, s6, v1
	ds_read_b128 v[2:5], v8
	v_lshl_add_u32 v13, v13, 1, 0
	v_lshl_add_u32 v15, v15, 1, 0
	v_lshl_add_u32 v11, v11, 1, 0
	v_lshl_add_u32 v10, v10, 1, 0
	ds_read_u16 v9, v9 offset:17408
	ds_read_u16 v18, v13 offset:17408
	ds_read_u16 v14, v14 offset:17408
	ds_read_u16 v21, v15 offset:17408
	ds_read_u16 v19, v19 offset:17408
	ds_read_u16 v20, v20 offset:17408
	ds_read_u16 v29, v11 offset:17408
	ds_read_u16 v30, v10 offset:17408
	s_waitcnt lgkmcnt(7)
	v_lshlrev_b32_e32 v13, 16, v9
	ds_read_b128 v[8:11], v8 offset:64
	s_add_u32 s0, s4, 0x8000
	v_lshlrev_b32_e32 v12, 16, v12
	s_waitcnt lgkmcnt(6)
	v_lshlrev_b32_e32 v15, 16, v14
	v_lshlrev_b32_e32 v14, 16, v18
	s_waitcnt lgkmcnt(4)
	v_lshlrev_b32_e32 v19, 16, v19
	v_lshlrev_b32_e32 v18, 16, v21
	s_waitcnt lgkmcnt(2)
	v_lshlrev_b32_e32 v21, 16, v29
	v_lshlrev_b32_e32 v20, 16, v20
	s_addc_u32 s1, s5, 0
	v_pk_mul_f32 v[12:13], v[2:3], v[12:13]
	v_pk_mul_f32 v[14:15], v[4:5], v[14:15]
	s_waitcnt lgkmcnt(0)
	v_pk_mul_f32 v[18:19], v[8:9], v[18:19]
	v_pk_mul_f32 v[20:21], v[10:11], v[20:21]
	v_cvt_pk_bf16_f32 v12, v12, v13
	v_cvt_pk_bf16_f32 v13, v14, v15
	v_cvt_pk_bf16_f32 v14, v18, v19
	v_cvt_pk_bf16_f32 v15, v20, v21
	v_lshl_add_u64 v[6:7], s[0:1], 0, v[6:7]
	global_store_dwordx4 v[6:7], v[12:15], off sc0 sc1
	v_add_u32_e32 v6, v22, v1
	v_add_u32_e32 v7, v23, v1
	v_add_u32_e32 v12, v24, v1
	v_add_u32_e32 v13, v25, v1
	v_add_u32_e32 v14, v26, v1
	v_add_u32_e32 v15, v27, v1
	v_add_u32_e32 v1, v28, v1
	v_lshl_add_u32 v6, v6, 1, 0
	v_lshl_add_u32 v12, v12, 1, 0
	v_lshl_add_u32 v13, v13, 1, 0
	v_lshl_add_u32 v14, v14, 1, 0
	v_lshl_add_u32 v15, v15, 1, 0
	v_lshl_add_u32 v1, v1, 1, 0
	v_lshl_add_u32 v7, v7, 1, 0
	ds_read_u16 v6, v6 offset:17408
	ds_read_u16 v18, v7 offset:17408
	ds_read_u16 v12, v12 offset:17408
	ds_read_u16 v13, v13 offset:17408
	ds_read_u16 v14, v14 offset:17408
	ds_read_u16 v15, v15 offset:17408
	ds_read_u16 v1, v1 offset:17408
	s_waitcnt lgkmcnt(6)
	v_lshlrev_b32_e32 v7, 16, v6
	v_lshlrev_b32_e32 v6, 16, v30
	v_pk_mul_f32 v[2:3], v[2:3], v[6:7]
	s_waitcnt lgkmcnt(4)
	v_lshlrev_b32_e32 v7, 16, v12
	v_lshlrev_b32_e32 v6, 16, v18
	v_pk_mul_f32 v[4:5], v[4:5], v[6:7]
	s_waitcnt lgkmcnt(2)
	v_lshlrev_b32_e32 v7, 16, v14
	v_lshlrev_b32_e32 v6, 16, v13
	v_pk_mul_f32 v[6:7], v[8:9], v[6:7]
	s_waitcnt lgkmcnt(0)
	v_lshlrev_b32_e32 v9, 16, v1
	v_lshlrev_b32_e32 v8, 16, v15
	v_pk_mul_f32 v[8:9], v[10:11], v[8:9]
	v_cvt_pk_bf16_f32 v2, v2, v3
	v_cvt_pk_bf16_f32 v3, v4, v5
	v_cvt_pk_bf16_f32 v4, v6, v7
	v_cvt_pk_bf16_f32 v5, v8, v9
	v_lshl_add_u64 v[6:7], s[0:1], 0, v[16:17]
	global_store_dwordx4 v[6:7], v[2:5], off sc0 sc1
	s_barrier
	s_waitcnt vmcnt(0)
	s_barrier
	s_and_saveexec_b64 s[0:1], s[66:67]
	s_cbranch_execz .LBB0_703
	s_mov_b64 s[4:5], exec
	v_mbcnt_lo_u32_b32 v1, s4, 0
	s_nop 0
	s_waitcnt vmcnt(0)
	s_waitcnt vmcnt(0)
	v_mbcnt_hi_u32_b32 v1, s5, v1
	v_cmp_eq_u32_e32 vcc, 0, v1
	s_and_b64 s[6:7], exec, vcc
	s_mov_b64 exec, s[6:7]
	s_cbranch_execz .LBB0_703
	s_bcnt1_i32_b64 s4, s[4:5]
	v_mov_b32_e32 v1, s99
	v_lshlrev_b32_e32 v1, 2, v1
	v_mov_b32_e32 v2, s4
	global_atomic_add v1, v2, s[14:15]
